# v28 with nt (streaming) hint on the hand-written epilogue stores
# baseline (speedup 1.0000x reference)
.LBB0_1051:
	ds_read_b128 v[152:155], v149
	ds_read_b128 v[156:159], v149 offset:1024
	ds_read_b128 v[160:163], v149 offset:2048
	ds_read_b128 v[164:167], v149 offset:3072
	s_add_u32 s4, s18, 0x100
	s_addc_u32 s5, s19, 0
	s_cmp_eq_u32 s45, 12
	s_cselect_b32 s23, s15, s5
	s_cselect_b32 s22, s14, s4
	s_cselect_b32 s21, s13, s44
	s_cselect_b32 s20, s42, s43
	v_lshl_add_u64 v[168:169], s[18:19], 0, v[140:141]
	s_add_i32 m0, s29, 0xc000
	ds_read_b128 v[172:175], v150
	ds_read_b128 v[176:179], v150 offset:1024
	ds_read_b128 v[180:183], v150 offset:2048
	ds_read_b128 v[184:187], v150 offset:3072
	ds_read_b128 v[188:191], v150 offset:4096
	ds_read_b128 v[192:195], v150 offset:5120
	ds_read_b128 v[196:199], v150 offset:6144
	ds_read_b128 v[200:203], v150 offset:7168
	global_load_lds_dwordx4 v[168:169], off
	v_lshl_add_u64 v[168:169], s[18:19], 0, v[138:139]
	s_add_i32 m0, s29, 0xe000
	s_nop 0
	global_load_lds_dwordx4 v[168:169], off
	s_waitcnt lgkmcnt(8)
	s_barrier
	s_waitcnt lgkmcnt(0)
	s_setprio 1
	s_waitcnt lgkmcnt(0)
	v_mfma_f32_16x16x32_bf16 v[124:127], v[152:155], v[172:175], v[124:127]
	v_mfma_f32_16x16x32_bf16 v[120:123], v[160:163], v[172:175], v[120:123]
	v_mfma_f32_16x16x32_bf16 v[116:119], v[152:155], v[180:183], v[116:119]
	v_mfma_f32_16x16x32_bf16 v[108:111], v[160:163], v[180:183], v[108:111]
	v_mfma_f32_16x16x32_bf16 v[100:103], v[152:155], v[188:191], v[100:103]
	v_mfma_f32_16x16x32_bf16 v[92:95], v[160:163], v[188:191], v[92:95]
	v_mfma_f32_16x16x32_bf16 v[84:87], v[152:155], v[196:199], v[84:87]
	v_mfma_f32_16x16x32_bf16 v[76:79], v[160:163], v[196:199], v[76:79]
	v_mfma_f32_16x16x32_bf16 v[124:127], v[156:159], v[176:179], v[124:127]
	v_mfma_f32_16x16x32_bf16 v[120:123], v[164:167], v[176:179], v[120:123]
	v_mfma_f32_16x16x32_bf16 v[116:119], v[156:159], v[184:187], v[116:119]
	v_mfma_f32_16x16x32_bf16 v[108:111], v[164:167], v[184:187], v[108:111]
	v_mfma_f32_16x16x32_bf16 v[100:103], v[156:159], v[192:195], v[100:103]
	v_mfma_f32_16x16x32_bf16 v[92:95], v[164:167], v[192:195], v[92:95]
	v_mfma_f32_16x16x32_bf16 v[84:87], v[156:159], v[200:203], v[84:87]
	v_mfma_f32_16x16x32_bf16 v[76:79], v[164:167], v[200:203], v[76:79]
	s_setprio 0
	s_barrier
	s_add_i32 s18, s36, s28
	v_lshl_add_u64 v[168:169], s[20:21], 0, v[132:133]
	s_mov_b32 m0, s18
	ds_read_b128 v[204:207], v151
	ds_read_b128 v[208:211], v151 offset:1024
	ds_read_b128 v[212:215], v151 offset:2048
	ds_read_b128 v[216:219], v151 offset:3072
	global_load_lds_dwordx4 v[168:169], off
	v_lshl_add_u64 v[220:221], s[20:21], 0, v[128:129]
	s_add_i32 m0, s18, 0x2000
	s_nop 0
	global_load_lds_dwordx4 v[220:221], off
	s_barrier
	s_waitcnt lgkmcnt(0)
	s_setprio 1
	s_waitcnt lgkmcnt(0)
	v_mfma_f32_16x16x32_bf16 v[112:115], v[204:207], v[172:175], v[112:115]
	v_mfma_f32_16x16x32_bf16 v[104:107], v[212:215], v[172:175], v[104:107]
	v_mfma_f32_16x16x32_bf16 v[96:99], v[204:207], v[180:183], v[96:99]
	v_mfma_f32_16x16x32_bf16 v[88:91], v[212:215], v[180:183], v[88:91]
	v_mfma_f32_16x16x32_bf16 v[80:83], v[204:207], v[188:191], v[80:83]
	v_mfma_f32_16x16x32_bf16 v[72:75], v[212:215], v[188:191], v[72:75]
	v_mfma_f32_16x16x32_bf16 v[68:71], v[204:207], v[196:199], v[68:71]
	v_mfma_f32_16x16x32_bf16 v[64:67], v[212:215], v[196:199], v[64:67]
	v_mfma_f32_16x16x32_bf16 v[112:115], v[208:211], v[176:179], v[112:115]
	v_mfma_f32_16x16x32_bf16 v[104:107], v[216:219], v[176:179], v[104:107]
	v_mfma_f32_16x16x32_bf16 v[96:99], v[208:211], v[184:187], v[96:99]
	v_mfma_f32_16x16x32_bf16 v[88:91], v[216:219], v[184:187], v[88:91]
	v_mfma_f32_16x16x32_bf16 v[80:83], v[208:211], v[192:195], v[80:83]
	v_mfma_f32_16x16x32_bf16 v[72:75], v[216:219], v[192:195], v[72:75]
	v_mfma_f32_16x16x32_bf16 v[68:71], v[208:211], v[200:203], v[68:71]
	v_mfma_f32_16x16x32_bf16 v[64:67], v[216:219], v[200:203], v[64:67]
	s_setprio 0
	s_mov_b32 m0, s29
	v_lshl_add_u64 v[222:223], s[22:23], 0, v[134:135]
	s_barrier
	ds_read_b128 v[172:175], v150 offset:16384
	ds_read_b128 v[176:179], v150 offset:17408
	ds_read_b128 v[180:183], v150 offset:18432
	ds_read_b128 v[184:187], v150 offset:19456
	ds_read_b128 v[188:191], v150 offset:20480
	ds_read_b128 v[192:195], v150 offset:21504
	ds_read_b128 v[196:199], v150 offset:22528
	ds_read_b128 v[200:203], v150 offset:23552
	global_load_lds_dwordx4 v[222:223], off
	v_lshl_add_u64 v[224:225], s[22:23], 0, v[130:131]
	s_mov_b32 m0, s30
	s_nop 0
	global_load_lds_dwordx4 v[224:225], off
	s_barrier
	s_waitcnt lgkmcnt(0)
	s_setprio 1
	s_waitcnt lgkmcnt(0)
	v_mfma_f32_16x16x32_bf16 v[60:63], v[152:155], v[172:175], v[60:63]
	v_mfma_f32_16x16x32_bf16 v[56:59], v[160:163], v[172:175], v[56:59]
	v_mfma_f32_16x16x32_bf16 v[52:55], v[152:155], v[180:183], v[52:55]
	v_mfma_f32_16x16x32_bf16 v[44:47], v[160:163], v[180:183], v[44:47]
	v_mfma_f32_16x16x32_bf16 v[36:39], v[152:155], v[188:191], v[36:39]
	v_mfma_f32_16x16x32_bf16 v[28:31], v[160:163], v[188:191], v[28:31]
	v_mfma_f32_16x16x32_bf16 v[20:23], v[152:155], v[196:199], v[20:23]
	v_mfma_f32_16x16x32_bf16 v[12:15], v[160:163], v[196:199], v[12:15]
	v_mfma_f32_16x16x32_bf16 v[60:63], v[156:159], v[176:179], v[60:63]
	v_mfma_f32_16x16x32_bf16 v[56:59], v[164:167], v[176:179], v[56:59]
	v_mfma_f32_16x16x32_bf16 v[52:55], v[156:159], v[184:187], v[52:55]
	v_mfma_f32_16x16x32_bf16 v[44:47], v[164:167], v[184:187], v[44:47]
	v_mfma_f32_16x16x32_bf16 v[36:39], v[156:159], v[192:195], v[36:39]
	v_mfma_f32_16x16x32_bf16 v[28:31], v[164:167], v[192:195], v[28:31]
	v_mfma_f32_16x16x32_bf16 v[20:23], v[156:159], v[200:203], v[20:23]
	v_mfma_f32_16x16x32_bf16 v[12:15], v[164:167], v[200:203], v[12:15]
	s_setprio 0
	s_barrier
	s_add_u32 s18, s20, 0x40000
	s_addc_u32 s19, s21, 0
	s_add_i32 s46, s37, s28
	v_lshl_add_u64 v[152:153], s[18:19], 0, v[132:133]
	s_mov_b32 m0, s46
	s_nop 0
	global_load_lds_dwordx4 v[152:153], off
	v_lshl_add_u64 v[152:153], s[18:19], 0, v[128:129]
	s_add_i32 m0, s46, 0x2000
	s_nop 0
	global_load_lds_dwordx4 v[152:153], off
	s_waitcnt vmcnt(6)
	s_barrier
	s_setprio 1
	v_mfma_f32_16x16x32_bf16 v[48:51], v[204:207], v[172:175], v[48:51]
	v_mfma_f32_16x16x32_bf16 v[40:43], v[212:215], v[172:175], v[40:43]
	v_mfma_f32_16x16x32_bf16 v[32:35], v[204:207], v[180:183], v[32:35]
	v_mfma_f32_16x16x32_bf16 v[24:27], v[212:215], v[180:183], v[24:27]
	v_mfma_f32_16x16x32_bf16 v[16:19], v[204:207], v[188:191], v[16:19]
	v_mfma_f32_16x16x32_bf16 v[8:11], v[212:215], v[188:191], v[8:11]
	v_mfma_f32_16x16x32_bf16 v[4:7], v[204:207], v[196:199], v[4:7]
	v_mfma_f32_16x16x32_bf16 v[0:3], v[212:215], v[196:199], v[0:3]
	v_mfma_f32_16x16x32_bf16 v[48:51], v[208:211], v[176:179], v[48:51]
	v_mfma_f32_16x16x32_bf16 v[40:43], v[216:219], v[176:179], v[40:43]
	v_mfma_f32_16x16x32_bf16 v[32:35], v[208:211], v[184:187], v[32:35]
	v_mfma_f32_16x16x32_bf16 v[24:27], v[216:219], v[184:187], v[24:27]
	v_mfma_f32_16x16x32_bf16 v[16:19], v[208:211], v[192:195], v[16:19]
	v_mfma_f32_16x16x32_bf16 v[8:11], v[216:219], v[192:195], v[8:11]
	v_mfma_f32_16x16x32_bf16 v[4:7], v[208:211], v[200:203], v[4:7]
	v_mfma_f32_16x16x32_bf16 v[0:3], v[216:219], v[200:203], v[0:3]
	s_setprio 0
	s_add_i32 s46, 0, 0x18000
	v_add_u32_e32 v164, s46, v148
	s_barrier
	ds_read_b128 v[152:155], v164
	ds_read_b128 v[156:159], v164 offset:1024
	ds_read_b128 v[160:163], v164 offset:2048
	ds_read_b128 v[164:167], v164 offset:3072
	s_add_u32 s18, s22, 0xea000
	s_addc_u32 s19, s23, 0
	s_mov_b32 m0, s31
	v_lshl_add_u64 v[204:205], s[18:19], 0, v[134:135]
	ds_read_b128 v[172:175], v150 offset:32768
	ds_read_b128 v[176:179], v150 offset:33792
	ds_read_b128 v[180:183], v150 offset:34816
	ds_read_b128 v[184:187], v150 offset:35840
	ds_read_b128 v[188:191], v150 offset:36864
	ds_read_b128 v[192:195], v150 offset:37888
	ds_read_b128 v[196:199], v150 offset:38912
	ds_read_b128 v[200:203], v150 offset:39936
	global_load_lds_dwordx4 v[204:205], off
	v_lshl_add_u64 v[204:205], s[18:19], 0, v[130:131]
	s_mov_b32 m0, s33
	s_nop 0
	global_load_lds_dwordx4 v[204:205], off
	s_waitcnt lgkmcnt(8)
	s_barrier
	s_waitcnt lgkmcnt(0)
	s_setprio 1
	s_waitcnt lgkmcnt(0)
	v_mfma_f32_16x16x32_bf16 v[124:127], v[152:155], v[172:175], v[124:127]
	v_mfma_f32_16x16x32_bf16 v[120:123], v[160:163], v[172:175], v[120:123]
	v_mfma_f32_16x16x32_bf16 v[116:119], v[152:155], v[180:183], v[116:119]
	v_mfma_f32_16x16x32_bf16 v[108:111], v[160:163], v[180:183], v[108:111]
	v_mfma_f32_16x16x32_bf16 v[100:103], v[152:155], v[188:191], v[100:103]
	v_mfma_f32_16x16x32_bf16 v[92:95], v[160:163], v[188:191], v[92:95]
	v_mfma_f32_16x16x32_bf16 v[84:87], v[152:155], v[196:199], v[84:87]
	v_mfma_f32_16x16x32_bf16 v[76:79], v[160:163], v[196:199], v[76:79]
	v_mfma_f32_16x16x32_bf16 v[124:127], v[156:159], v[176:179], v[124:127]
	v_mfma_f32_16x16x32_bf16 v[120:123], v[164:167], v[176:179], v[120:123]
	v_mfma_f32_16x16x32_bf16 v[116:119], v[156:159], v[184:187], v[116:119]
	v_mfma_f32_16x16x32_bf16 v[108:111], v[164:167], v[184:187], v[108:111]
	v_mfma_f32_16x16x32_bf16 v[100:103], v[156:159], v[192:195], v[100:103]
	v_mfma_f32_16x16x32_bf16 v[92:95], v[164:167], v[192:195], v[92:95]
	v_mfma_f32_16x16x32_bf16 v[84:87], v[156:159], v[200:203], v[84:87]
	v_mfma_f32_16x16x32_bf16 v[76:79], v[164:167], v[200:203], v[76:79]
	s_setprio 0
	s_barrier
	s_add_i32 s22, 0, 0x1c000
	s_add_i32 s18, s46, s28
	v_add_u32_e32 v171, s22, v148
	v_lshl_add_u64 v[168:169], v[168:169], 0, s[10:11]
	s_mov_b32 m0, s18
	ds_read_b128 v[204:207], v171
	ds_read_b128 v[208:211], v171 offset:1024
	ds_read_b128 v[212:215], v171 offset:2048
	ds_read_b128 v[216:219], v171 offset:3072
	global_load_lds_dwordx4 v[168:169], off
	v_lshl_add_u64 v[168:169], v[220:221], 0, s[10:11]
	s_add_i32 m0, s18, 0x2000
	s_nop 0
	global_load_lds_dwordx4 v[168:169], off
	s_barrier
	s_waitcnt lgkmcnt(0)
	s_setprio 1
	s_waitcnt lgkmcnt(0)
	v_mfma_f32_16x16x32_bf16 v[112:115], v[204:207], v[172:175], v[112:115]
	v_mfma_f32_16x16x32_bf16 v[104:107], v[212:215], v[172:175], v[104:107]
	v_mfma_f32_16x16x32_bf16 v[96:99], v[204:207], v[180:183], v[96:99]
	v_mfma_f32_16x16x32_bf16 v[88:91], v[212:215], v[180:183], v[88:91]
	v_mfma_f32_16x16x32_bf16 v[80:83], v[204:207], v[188:191], v[80:83]
	v_mfma_f32_16x16x32_bf16 v[72:75], v[212:215], v[188:191], v[72:75]
	v_mfma_f32_16x16x32_bf16 v[68:71], v[204:207], v[196:199], v[68:71]
	v_mfma_f32_16x16x32_bf16 v[64:67], v[212:215], v[196:199], v[64:67]
	v_mfma_f32_16x16x32_bf16 v[112:115], v[208:211], v[176:179], v[112:115]
	v_mfma_f32_16x16x32_bf16 v[104:107], v[216:219], v[176:179], v[104:107]
	v_mfma_f32_16x16x32_bf16 v[96:99], v[208:211], v[184:187], v[96:99]
	v_mfma_f32_16x16x32_bf16 v[88:91], v[216:219], v[184:187], v[88:91]
	v_mfma_f32_16x16x32_bf16 v[80:83], v[208:211], v[192:195], v[80:83]
	v_mfma_f32_16x16x32_bf16 v[72:75], v[216:219], v[192:195], v[72:75]
	v_mfma_f32_16x16x32_bf16 v[68:71], v[208:211], v[200:203], v[68:71]
	v_mfma_f32_16x16x32_bf16 v[64:67], v[216:219], v[200:203], v[64:67]
	s_setprio 0
	s_mov_b32 m0, s34
	v_lshl_add_u64 v[168:169], v[222:223], 0, s[10:11]
	s_barrier
	ds_read_b128 v[172:175], v150 offset:49152
	ds_read_b128 v[176:179], v150 offset:50176
	ds_read_b128 v[180:183], v150 offset:51200
	ds_read_b128 v[184:187], v150 offset:52224
	ds_read_b128 v[188:191], v150 offset:53248
	ds_read_b128 v[192:195], v150 offset:54272
	ds_read_b128 v[196:199], v150 offset:55296
	ds_read_b128 v[200:203], v150 offset:56320
	global_load_lds_dwordx4 v[168:169], off
	v_lshl_add_u64 v[168:169], v[224:225], 0, s[10:11]
	s_mov_b32 m0, s35
	s_nop 0
	global_load_lds_dwordx4 v[168:169], off
	s_barrier
	s_waitcnt lgkmcnt(0)
	s_setprio 1
	s_waitcnt lgkmcnt(0)
	v_mfma_f32_16x16x32_bf16 v[60:63], v[152:155], v[172:175], v[60:63]
	v_mfma_f32_16x16x32_bf16 v[56:59], v[160:163], v[172:175], v[56:59]
	v_mfma_f32_16x16x32_bf16 v[52:55], v[152:155], v[180:183], v[52:55]
	v_mfma_f32_16x16x32_bf16 v[44:47], v[160:163], v[180:183], v[44:47]
	v_mfma_f32_16x16x32_bf16 v[36:39], v[152:155], v[188:191], v[36:39]
	v_mfma_f32_16x16x32_bf16 v[28:31], v[160:163], v[188:191], v[28:31]
	v_mfma_f32_16x16x32_bf16 v[20:23], v[152:155], v[196:199], v[20:23]
	v_mfma_f32_16x16x32_bf16 v[12:15], v[160:163], v[196:199], v[12:15]
	v_mfma_f32_16x16x32_bf16 v[60:63], v[156:159], v[176:179], v[60:63]
	v_mfma_f32_16x16x32_bf16 v[56:59], v[164:167], v[176:179], v[56:59]
	v_mfma_f32_16x16x32_bf16 v[52:55], v[156:159], v[184:187], v[52:55]
	v_mfma_f32_16x16x32_bf16 v[44:47], v[164:167], v[184:187], v[44:47]
	v_mfma_f32_16x16x32_bf16 v[36:39], v[156:159], v[192:195], v[36:39]
	v_mfma_f32_16x16x32_bf16 v[28:31], v[164:167], v[192:195], v[28:31]
	v_mfma_f32_16x16x32_bf16 v[20:23], v[156:159], v[200:203], v[20:23]
	v_mfma_f32_16x16x32_bf16 v[12:15], v[164:167], v[200:203], v[12:15]
	s_setprio 0
	s_barrier
	s_add_u32 s18, s20, 0x40080
	s_addc_u32 s19, s21, 0
	s_add_i32 s20, s22, s28
	v_lshl_add_u64 v[152:153], s[18:19], 0, v[132:133]
	s_mov_b32 m0, s20
	s_nop 0
	global_load_lds_dwordx4 v[152:153], off
	v_lshl_add_u64 v[152:153], s[18:19], 0, v[128:129]
	s_add_i32 m0, s20, 0x2000
	s_nop 0
	global_load_lds_dwordx4 v[152:153], off
	s_waitcnt vmcnt(6)
	s_barrier
	s_setprio 1
	v_mfma_f32_16x16x32_bf16 v[48:51], v[204:207], v[172:175], v[48:51]
	v_mfma_f32_16x16x32_bf16 v[40:43], v[212:215], v[172:175], v[40:43]
	v_mfma_f32_16x16x32_bf16 v[32:35], v[204:207], v[180:183], v[32:35]
	v_mfma_f32_16x16x32_bf16 v[24:27], v[212:215], v[180:183], v[24:27]
	v_mfma_f32_16x16x32_bf16 v[16:19], v[204:207], v[188:191], v[16:19]
	v_mfma_f32_16x16x32_bf16 v[8:11], v[212:215], v[188:191], v[8:11]
	v_mfma_f32_16x16x32_bf16 v[4:7], v[204:207], v[196:199], v[4:7]
	v_mfma_f32_16x16x32_bf16 v[0:3], v[212:215], v[196:199], v[0:3]
	v_mfma_f32_16x16x32_bf16 v[48:51], v[208:211], v[176:179], v[48:51]
	v_mfma_f32_16x16x32_bf16 v[40:43], v[216:219], v[176:179], v[40:43]
	v_mfma_f32_16x16x32_bf16 v[32:35], v[208:211], v[184:187], v[32:35]
	v_mfma_f32_16x16x32_bf16 v[24:27], v[216:219], v[184:187], v[24:27]
	v_mfma_f32_16x16x32_bf16 v[16:19], v[208:211], v[192:195], v[16:19]
	v_mfma_f32_16x16x32_bf16 v[8:11], v[216:219], v[192:195], v[8:11]
	v_mfma_f32_16x16x32_bf16 v[4:7], v[208:211], v[200:203], v[4:7]
	v_mfma_f32_16x16x32_bf16 v[0:3], v[216:219], v[200:203], v[0:3]
	s_setprio 0
	s_add_i32 s45, s45, 2
	s_add_u32 s43, s43, 0x100
	s_addc_u32 s44, s44, 0
	s_cmp_gt_u32 s45, 13
	s_mov_b64 s[18:19], s[4:5]
	s_barrier
	s_cbranch_scc0 .LBB0_1051
	v_lshl_add_u32 v152, s41, 8, v147
	s_lshl_b32 s4, s40, 8
	v_ashrrev_i32_e32 v153, 31, v152
	s_ashr_i32 s5, s4, 31
	v_lshlrev_b64 v[154:155], 11, v[152:153]
	v_lshl_add_u64 v[154:155], s[6:7], 0, v[154:155]
	s_lshl_b64 s[4:5], s[4:5], 1
	v_lshl_add_u64 v[154:155], v[154:155], 0, s[4:5]
	v_lshl_add_u64 v[154:155], v[154:155], 0, s[8:9]
	v_lshl_add_u64 v[154:155], v[154:155], 0, v[136:137]
	v_mbcnt_lo_u32_b32 v237, -1, 0
	v_mbcnt_hi_u32_b32 v237, -1, v237
	v_bfe_i32 v237, v237, 4, 1
	v_and_b32_e32 v244, 24, v237
	v_add_co_u32_e32 v248, vcc, v244, v154
	s_nop 1
	v_addc_co_u32_e32 v249, vcc, 0, v155, vcc
	v_cvt_pk_bf16_f32 v124, v124, v125
	v_cvt_pk_bf16_f32 v125, v126, v127
	v_cvt_pk_bf16_f32 v120, v120, v121
	v_cvt_pk_bf16_f32 v121, v122, v123
	v_bfi_b32 v244, v237, v124, v120
	v_bfi_b32 v245, v237, v125, v121
	ds_swizzle_b32 v250, v244 offset:0x401f
	ds_swizzle_b32 v251, v245 offset:0x401f
	v_cvt_pk_bf16_f32 v112, v112, v113
	v_cvt_pk_bf16_f32 v113, v114, v115
	v_cvt_pk_bf16_f32 v104, v104, v105
	v_cvt_pk_bf16_f32 v105, v106, v107
	v_bfi_b32 v246, v237, v112, v104
	v_bfi_b32 v247, v237, v113, v105
	ds_swizzle_b32 v252, v246 offset:0x401f
	ds_swizzle_b32 v253, v247 offset:0x401f
	s_waitcnt lgkmcnt(0)
	v_bfi_b32 v240, v237, v250, v124
	v_bfi_b32 v241, v237, v251, v125
	v_bfi_b32 v242, v237, v120, v250
	v_bfi_b32 v243, v237, v121, v251
	global_store_dwordx4 v[248:249], v[240:243], off nt
	s_nop 1
	v_bfi_b32 v240, v237, v252, v112
	v_bfi_b32 v241, v237, v253, v113
	v_bfi_b32 v242, v237, v104, v252
	v_bfi_b32 v243, v237, v105, v253
	global_store_dwordx4 v[248:249], v[240:243], off offset:256 nt
	s_nop 1
	v_add_co_u32_e32 v238, vcc, 0x8000, v248
	s_nop 1
	v_addc_co_u32_e32 v239, vcc, 0, v249, vcc
	v_cvt_pk_bf16_f32 v116, v116, v117
	v_cvt_pk_bf16_f32 v117, v118, v119
	v_cvt_pk_bf16_f32 v108, v108, v109
	v_cvt_pk_bf16_f32 v109, v110, v111
	v_bfi_b32 v244, v237, v116, v108
	v_bfi_b32 v245, v237, v117, v109
	ds_swizzle_b32 v250, v244 offset:0x401f
	ds_swizzle_b32 v251, v245 offset:0x401f
	v_cvt_pk_bf16_f32 v96, v96, v97
	v_cvt_pk_bf16_f32 v97, v98, v99
	v_cvt_pk_bf16_f32 v88, v88, v89
	v_cvt_pk_bf16_f32 v89, v90, v91
	v_bfi_b32 v246, v237, v96, v88
	v_bfi_b32 v247, v237, v97, v89
	ds_swizzle_b32 v252, v246 offset:0x401f
	ds_swizzle_b32 v253, v247 offset:0x401f
	s_waitcnt lgkmcnt(0)
	v_bfi_b32 v240, v237, v250, v116
	v_bfi_b32 v241, v237, v251, v117
	v_bfi_b32 v242, v237, v108, v250
	v_bfi_b32 v243, v237, v109, v251
	global_store_dwordx4 v[238:239], v[240:243], off nt
	s_nop 1
	v_bfi_b32 v240, v237, v252, v96
	v_bfi_b32 v241, v237, v253, v97
	v_bfi_b32 v242, v237, v88, v252
	v_bfi_b32 v243, v237, v89, v253
	global_store_dwordx4 v[238:239], v[240:243], off offset:256 nt
	s_nop 1
	v_add_co_u32_e32 v238, vcc, 0x10000, v248
	s_nop 1
	v_addc_co_u32_e32 v239, vcc, 0, v249, vcc
	v_cvt_pk_bf16_f32 v100, v100, v101
	v_cvt_pk_bf16_f32 v101, v102, v103
	v_cvt_pk_bf16_f32 v92, v92, v93
	v_cvt_pk_bf16_f32 v93, v94, v95
	v_bfi_b32 v244, v237, v100, v92
	v_bfi_b32 v245, v237, v101, v93
	ds_swizzle_b32 v250, v244 offset:0x401f
	ds_swizzle_b32 v251, v245 offset:0x401f
	v_cvt_pk_bf16_f32 v80, v80, v81
	v_cvt_pk_bf16_f32 v81, v82, v83
	v_cvt_pk_bf16_f32 v72, v72, v73
	v_cvt_pk_bf16_f32 v73, v74, v75
	v_bfi_b32 v246, v237, v80, v72
	v_bfi_b32 v247, v237, v81, v73
	ds_swizzle_b32 v252, v246 offset:0x401f
	ds_swizzle_b32 v253, v247 offset:0x401f
	s_waitcnt lgkmcnt(0)
	v_bfi_b32 v240, v237, v250, v100
	v_bfi_b32 v241, v237, v251, v101
	v_bfi_b32 v242, v237, v92, v250
	v_bfi_b32 v243, v237, v93, v251
	global_store_dwordx4 v[238:239], v[240:243], off nt
	s_nop 1
	v_bfi_b32 v240, v237, v252, v80
	v_bfi_b32 v241, v237, v253, v81
	v_bfi_b32 v242, v237, v72, v252
	v_bfi_b32 v243, v237, v73, v253
	global_store_dwordx4 v[238:239], v[240:243], off offset:256 nt
	s_nop 1
	v_add_co_u32_e32 v238, vcc, 0x18000, v248
	s_nop 1
	v_addc_co_u32_e32 v239, vcc, 0, v249, vcc
	v_cvt_pk_bf16_f32 v84, v84, v85
	v_cvt_pk_bf16_f32 v85, v86, v87
	v_cvt_pk_bf16_f32 v76, v76, v77
	v_cvt_pk_bf16_f32 v77, v78, v79
	v_bfi_b32 v244, v237, v84, v76
	v_bfi_b32 v245, v237, v85, v77
	ds_swizzle_b32 v250, v244 offset:0x401f
	ds_swizzle_b32 v251, v245 offset:0x401f
	v_cvt_pk_bf16_f32 v68, v68, v69
	v_cvt_pk_bf16_f32 v69, v70, v71
	v_cvt_pk_bf16_f32 v64, v64, v65
	v_cvt_pk_bf16_f32 v65, v66, v67
	v_bfi_b32 v246, v237, v68, v64
	v_bfi_b32 v247, v237, v69, v65
	ds_swizzle_b32 v252, v246 offset:0x401f
	ds_swizzle_b32 v253, v247 offset:0x401f
	s_waitcnt lgkmcnt(0)
	v_bfi_b32 v240, v237, v250, v84
	v_bfi_b32 v241, v237, v251, v85
	v_bfi_b32 v242, v237, v76, v250
	v_bfi_b32 v243, v237, v77, v251
	global_store_dwordx4 v[238:239], v[240:243], off nt
	s_nop 1
	v_bfi_b32 v240, v237, v252, v68
	v_bfi_b32 v241, v237, v253, v69
	v_bfi_b32 v242, v237, v64, v252
	v_bfi_b32 v243, v237, v65, v253
	global_store_dwordx4 v[238:239], v[240:243], off offset:256 nt
	s_nop 1
	v_add_co_u32_e32 v238, vcc, 0x40000, v248
	s_nop 1
	v_addc_co_u32_e32 v239, vcc, 0, v249, vcc
	v_cvt_pk_bf16_f32 v60, v60, v61
	v_cvt_pk_bf16_f32 v61, v62, v63
	v_cvt_pk_bf16_f32 v56, v56, v57
	v_cvt_pk_bf16_f32 v57, v58, v59
	v_bfi_b32 v244, v237, v60, v56
	v_bfi_b32 v245, v237, v61, v57
	ds_swizzle_b32 v250, v244 offset:0x401f
	ds_swizzle_b32 v251, v245 offset:0x401f
	v_cvt_pk_bf16_f32 v48, v48, v49
	v_cvt_pk_bf16_f32 v49, v50, v51
	v_cvt_pk_bf16_f32 v40, v40, v41
	v_cvt_pk_bf16_f32 v41, v42, v43
	v_bfi_b32 v246, v237, v48, v40
	v_bfi_b32 v247, v237, v49, v41
	ds_swizzle_b32 v252, v246 offset:0x401f
	ds_swizzle_b32 v253, v247 offset:0x401f
	s_waitcnt lgkmcnt(0)
	v_bfi_b32 v240, v237, v250, v60
	v_bfi_b32 v241, v237, v251, v61
	v_bfi_b32 v242, v237, v56, v250
	v_bfi_b32 v243, v237, v57, v251
	global_store_dwordx4 v[238:239], v[240:243], off nt
	s_nop 1
	v_bfi_b32 v240, v237, v252, v48
	v_bfi_b32 v241, v237, v253, v49
	v_bfi_b32 v242, v237, v40, v252
	v_bfi_b32 v243, v237, v41, v253
	global_store_dwordx4 v[238:239], v[240:243], off offset:256 nt
	s_nop 1
	v_add_co_u32_e32 v238, vcc, 0x48000, v248
	s_nop 1
	v_addc_co_u32_e32 v239, vcc, 0, v249, vcc
	v_cvt_pk_bf16_f32 v52, v52, v53
	v_cvt_pk_bf16_f32 v53, v54, v55
	v_cvt_pk_bf16_f32 v44, v44, v45
	v_cvt_pk_bf16_f32 v45, v46, v47
	v_bfi_b32 v244, v237, v52, v44
	v_bfi_b32 v245, v237, v53, v45
	ds_swizzle_b32 v250, v244 offset:0x401f
	ds_swizzle_b32 v251, v245 offset:0x401f
	v_cvt_pk_bf16_f32 v32, v32, v33
	v_cvt_pk_bf16_f32 v33, v34, v35
	v_cvt_pk_bf16_f32 v24, v24, v25
	v_cvt_pk_bf16_f32 v25, v26, v27
	v_bfi_b32 v246, v237, v32, v24
	v_bfi_b32 v247, v237, v33, v25
	ds_swizzle_b32 v252, v246 offset:0x401f
	ds_swizzle_b32 v253, v247 offset:0x401f
	s_waitcnt lgkmcnt(0)
	v_bfi_b32 v240, v237, v250, v52
	v_bfi_b32 v241, v237, v251, v53
	v_bfi_b32 v242, v237, v44, v250
	v_bfi_b32 v243, v237, v45, v251
	global_store_dwordx4 v[238:239], v[240:243], off nt
	s_nop 1
	v_bfi_b32 v240, v237, v252, v32
	v_bfi_b32 v241, v237, v253, v33
	v_bfi_b32 v242, v237, v24, v252
	v_bfi_b32 v243, v237, v25, v253
	global_store_dwordx4 v[238:239], v[240:243], off offset:256 nt
	s_nop 1
	v_add_co_u32_e32 v238, vcc, 0x50000, v248
	s_nop 1
	v_addc_co_u32_e32 v239, vcc, 0, v249, vcc
	v_cvt_pk_bf16_f32 v36, v36, v37
	v_cvt_pk_bf16_f32 v37, v38, v39
	v_cvt_pk_bf16_f32 v28, v28, v29
	v_cvt_pk_bf16_f32 v29, v30, v31
	v_bfi_b32 v244, v237, v36, v28
	v_bfi_b32 v245, v237, v37, v29
	ds_swizzle_b32 v250, v244 offset:0x401f
	ds_swizzle_b32 v251, v245 offset:0x401f
	v_cvt_pk_bf16_f32 v16, v16, v17
	v_cvt_pk_bf16_f32 v17, v18, v19
	v_cvt_pk_bf16_f32 v8, v8, v9
	v_cvt_pk_bf16_f32 v9, v10, v11
	v_bfi_b32 v246, v237, v16, v8
	v_bfi_b32 v247, v237, v17, v9
	ds_swizzle_b32 v252, v246 offset:0x401f
	ds_swizzle_b32 v253, v247 offset:0x401f
	s_waitcnt lgkmcnt(0)
	v_bfi_b32 v240, v237, v250, v36
	v_bfi_b32 v241, v237, v251, v37
	v_bfi_b32 v242, v237, v28, v250
	v_bfi_b32 v243, v237, v29, v251
	global_store_dwordx4 v[238:239], v[240:243], off nt
	s_nop 1
	v_bfi_b32 v240, v237, v252, v16
	v_bfi_b32 v241, v237, v253, v17
	v_bfi_b32 v242, v237, v8, v252
	v_bfi_b32 v243, v237, v9, v253
	global_store_dwordx4 v[238:239], v[240:243], off offset:256 nt
	s_nop 1
	v_add_co_u32_e32 v238, vcc, 0x58000, v248
	s_nop 1
	v_addc_co_u32_e32 v239, vcc, 0, v249, vcc
	v_cvt_pk_bf16_f32 v20, v20, v21
	v_cvt_pk_bf16_f32 v21, v22, v23
	v_cvt_pk_bf16_f32 v12, v12, v13
	v_cvt_pk_bf16_f32 v13, v14, v15
	v_bfi_b32 v244, v237, v20, v12
	v_bfi_b32 v245, v237, v21, v13
	ds_swizzle_b32 v250, v244 offset:0x401f
	ds_swizzle_b32 v251, v245 offset:0x401f
	v_cvt_pk_bf16_f32 v4, v4, v5
	v_cvt_pk_bf16_f32 v5, v6, v7
	v_cvt_pk_bf16_f32 v0, v0, v1
	v_cvt_pk_bf16_f32 v1, v2, v3
	v_bfi_b32 v246, v237, v4, v0
	v_bfi_b32 v247, v237, v5, v1
	ds_swizzle_b32 v252, v246 offset:0x401f
	ds_swizzle_b32 v253, v247 offset:0x401f
	s_waitcnt lgkmcnt(0)
	v_bfi_b32 v240, v237, v250, v20
	v_bfi_b32 v241, v237, v251, v21
	v_bfi_b32 v242, v237, v12, v250
	v_bfi_b32 v243, v237, v13, v251
	global_store_dwordx4 v[238:239], v[240:243], off nt
	s_nop 1
	v_bfi_b32 v240, v237, v252, v4
	v_bfi_b32 v241, v237, v253, v5
	v_bfi_b32 v242, v237, v0, v252
	v_bfi_b32 v243, v237, v1, v253
	global_store_dwordx4 v[238:239], v[240:243], off offset:256 nt
	s_nop 1
	s_and_b64 vcc, exec, s[0:1]
	s_mov_b32 s40, s12
	s_mov_b32 s41, s39
	s_mov_b64 s[20:21], s[16:17]
	s_mov_b64 s[18:19], s[14:15]
	s_cbranch_vccz .LBB0_1046
	s_waitcnt vmcnt(0)
	s_cmpk_gt_u32 s3, 0xff
	s_cbranch_scc1 .LBB0_1055
	s_barrier

.Lupf_u0_entry:
	v_mbcnt_lo_u32_b32 v253, -1, 0
	v_mbcnt_hi_u32_b32 v253, -1, v253
	v_and_b32_e32 v254, 15, v253
	v_lshrrev_b32_e32 v255, 4, v253
	s_lshr_b32 s100, s3, 6
	s_lshr_b32 s101, s100, 2
	s_and_b32 s100, s100, 3
	s_lshl_b32 vcc_lo, s101, 6
	v_add_u32_e32 v251, vcc_lo, v254
	s_add_i32 vcc_hi, s98, -1
	v_add_u32_e32 v250, vcc_hi, v251
	v_mul_u32_u24_e32 v250, 0x1600, v250
	s_lshl_b32 vcc_lo, s28, 7
	s_lshl_b32 vcc_hi, s100, 5
	s_add_i32 vcc_lo, vcc_lo, vcc_hi
	v_lshl_add_u32 v253, v255, 2, vcc_lo
	v_and_b32_e32 v252, 1, v255
	v_lshlrev_b32_e32 v252, 1, v252
	v_lshrrev_b32_e32 v245, 1, v255
	v_or_b32_e32 v252, v252, v245
	v_lshl_add_u32 v252, v252, 3, vcc_lo
	v_lshl_add_u32 v250, v252, 1, v250
	v_lshlrev_b32_e32 v146, 2, v253
	v_add_u32_e32 v147, 0x5800, v146
	v_add_u32_e32 v168, 0xb000, v146
	v_add_u32_e32 v169, 0x2c00, v146
	v_add_u32_e32 v245, 0x8400, v146
	v_add_u32_e32 v252, 0xdc00, v146
	global_load_dwordx4 v[172:175], v146, s[62:63] offset:0
	global_load_dwordx4 v[176:179], v147, s[62:63] offset:0
	global_load_dwordx4 v[180:183], v168, s[62:63] offset:0
	global_load_dwordx4 v[188:191], v169, s[62:63] offset:0
	global_load_dwordx4 v[192:195], v245, s[62:63] offset:0
	global_load_dwordx4 v[196:199], v252, s[62:63] offset:0
	global_load_dwordx4 v[184:187], v146, s[64:65] offset:0
	global_load_dwordx4 v[200:203], v169, s[64:65] offset:0
	s_lshl_b32 s101, s101, 11
	s_lshl_b32 s100, s100, 7
	s_add_i32 s101, s101, s100
	s_add_i32 s101, s101, 0x20000
	v_lshl_add_u32 v249, v255, 4, s101
	v_add_u32_e32 v253, 0x400, v249
	v_cmp_eq_u32_e64 s[98:99], 0, v254
	v_cmp_eq_u32_e32 vcc, 15, v254
	s_nop 4
	s_mov_b64 exec, s[98:99]
	ds_write_b128 v253, v[124:127] offset:0
	ds_write_b128 v253, v[108:111] offset:64
	ds_write_b128 v253, v[112:115] offset:512
	ds_write_b128 v253, v[84:87] offset:576
	ds_write_b128 v253, v[72:75] offset:4096
	ds_write_b128 v253, v[44:47] offset:4160
	ds_write_b128 v253, v[48:51] offset:4608
	ds_write_b128 v253, v[20:23] offset:4672
	s_mov_b64 exec, vcc
	ds_write_b128 v253, v[104:107] offset:1024
	ds_write_b128 v253, v[76:79] offset:1088
	ds_write_b128 v253, v[80:83] offset:1536
	ds_write_b128 v253, v[52:55] offset:1600
	ds_write_b128 v253, v[40:43] offset:5120
	ds_write_b128 v253, v[12:15] offset:5184
	ds_write_b128 v253, v[16:19] offset:5632
	ds_write_b128 v253, v[0:3] offset:5696
	s_mov_b64 exec, -1
	s_waitcnt lgkmcnt(0)
	s_barrier
	ds_read_b128 v[204:207], v249 offset:0
	ds_read_b128 v[208:211], v249 offset:512
	ds_read_b128 v[160:163], v249 offset:3072
	ds_read_b128 v[164:167], v249 offset:3584
	s_waitcnt vmcnt(0) lgkmcnt(0)
	v_cndmask_b32_e32 v148, v124, v204, vcc
	v_cndmask_b32_e32 v149, v125, v205, vcc
	v_cndmask_b32_e32 v150, v126, v206, vcc
	v_cndmask_b32_e32 v151, v127, v207, vcc
	v_cndmask_b32_e64 v152, v124, v120, s[98:99]
	v_cndmask_b32_e64 v153, v125, v121, s[98:99]
	v_cndmask_b32_e64 v154, v126, v122, s[98:99]
	v_cndmask_b32_e64 v155, v127, v123, s[98:99]
	v_fma_f32 v156, v176, v124, v184
	v_fma_f32 v157, v177, v125, v185
	v_fma_f32 v158, v178, v126, v186
	v_fma_f32 v159, v179, v127, v187
	v_fmac_f32_dpp v156, v148, v172 row_ror:1 row_mask:0xf bank_mask:0xf
	v_fmac_f32_dpp v157, v149, v173 row_ror:1 row_mask:0xf bank_mask:0xf
	v_fmac_f32_dpp v158, v150, v174 row_ror:1 row_mask:0xf bank_mask:0xf
	v_fmac_f32_dpp v159, v151, v175 row_ror:1 row_mask:0xf bank_mask:0xf
	v_fmac_f32_dpp v156, v152, v180 row_ror:15 row_mask:0xf bank_mask:0xf
	v_fmac_f32_dpp v157, v153, v181 row_ror:15 row_mask:0xf bank_mask:0xf
	v_fmac_f32_dpp v158, v154, v182 row_ror:15 row_mask:0xf bank_mask:0xf
	v_fmac_f32_dpp v159, v155, v183 row_ror:15 row_mask:0xf bank_mask:0xf
	v_cndmask_b32_e32 v148, v112, v208, vcc
	v_cndmask_b32_e32 v149, v113, v209, vcc
	v_cndmask_b32_e32 v150, v114, v210, vcc
	v_cndmask_b32_e32 v151, v115, v211, vcc
	v_cndmask_b32_e64 v152, v112, v100, s[98:99]
	v_cndmask_b32_e64 v153, v113, v101, s[98:99]
	v_cndmask_b32_e64 v154, v114, v102, s[98:99]
	v_cndmask_b32_e64 v155, v115, v103, s[98:99]
	v_fma_f32 v237, v192, v112, v200
	v_fma_f32 v238, v193, v113, v201
	v_fma_f32 v239, v194, v114, v202
	v_fma_f32 v240, v195, v115, v203
	v_fmac_f32_dpp v237, v148, v188 row_ror:1 row_mask:0xf bank_mask:0xf
	v_fmac_f32_dpp v238, v149, v189 row_ror:1 row_mask:0xf bank_mask:0xf
	v_fmac_f32_dpp v239, v150, v190 row_ror:1 row_mask:0xf bank_mask:0xf
	v_fmac_f32_dpp v240, v151, v191 row_ror:1 row_mask:0xf bank_mask:0xf
	v_fmac_f32_dpp v237, v152, v196 row_ror:15 row_mask:0xf bank_mask:0xf
	v_fmac_f32_dpp v238, v153, v197 row_ror:15 row_mask:0xf bank_mask:0xf
	v_fmac_f32_dpp v239, v154, v198 row_ror:15 row_mask:0xf bank_mask:0xf
	v_fmac_f32_dpp v240, v155, v199 row_ror:15 row_mask:0xf bank_mask:0xf
	v_mul_f32_e32 v148, 0xbfb8aa3b, v156
	v_mul_f32_e32 v149, 0xbfb8aa3b, v157
	v_mul_f32_e32 v150, 0xbfb8aa3b, v158
	v_mul_f32_e32 v151, 0xbfb8aa3b, v159
	v_exp_f32_e32 v148, v148
	v_exp_f32_e32 v149, v149
	v_exp_f32_e32 v150, v150
	v_exp_f32_e32 v151, v151
	v_add_f32_e32 v148, 1.0, v148
	v_add_f32_e32 v149, 1.0, v149
	v_add_f32_e32 v150, 1.0, v150
	v_add_f32_e32 v151, 1.0, v151
	v_rcp_f32_e32 v148, v148
	v_rcp_f32_e32 v149, v149
	v_rcp_f32_e32 v150, v150
	v_rcp_f32_e32 v151, v151
	v_mul_f32_e32 v156, v156, v148
	v_mul_f32_e32 v157, v157, v149
	v_mul_f32_e32 v158, v158, v150
	v_mul_f32_e32 v159, v159, v151
	v_mul_f32_e32 v156, v156, v237
	v_mul_f32_e32 v157, v157, v238
	v_mul_f32_e32 v158, v158, v239
	v_mul_f32_e32 v159, v159, v240
	v_cvt_pk_bf16_f32 v241, v156, v157
	v_cvt_pk_bf16_f32 v242, v158, v159
	ds_read_b128 v[204:207], v249 offset:4096
	ds_read_b128 v[208:211], v249 offset:4608
	v_cndmask_b32_e32 v148, v120, v124, vcc
	v_cndmask_b32_e32 v149, v121, v125, vcc
	v_cndmask_b32_e32 v150, v122, v126, vcc
	v_cndmask_b32_e32 v151, v123, v127, vcc
	v_cndmask_b32_e64 v152, v120, v116, s[98:99]
	v_cndmask_b32_e64 v153, v121, v117, s[98:99]
	v_cndmask_b32_e64 v154, v122, v118, s[98:99]
	v_cndmask_b32_e64 v155, v123, v119, s[98:99]
	v_fma_f32 v156, v176, v120, v184
	v_fma_f32 v157, v177, v121, v185
	v_fma_f32 v158, v178, v122, v186
	v_fma_f32 v159, v179, v123, v187
	v_fmac_f32_dpp v156, v148, v172 row_ror:1 row_mask:0xf bank_mask:0xf
	v_fmac_f32_dpp v157, v149, v173 row_ror:1 row_mask:0xf bank_mask:0xf
	v_fmac_f32_dpp v158, v150, v174 row_ror:1 row_mask:0xf bank_mask:0xf
	v_fmac_f32_dpp v159, v151, v175 row_ror:1 row_mask:0xf bank_mask:0xf
	v_fmac_f32_dpp v156, v152, v180 row_ror:15 row_mask:0xf bank_mask:0xf
	v_fmac_f32_dpp v157, v153, v181 row_ror:15 row_mask:0xf bank_mask:0xf
	v_fmac_f32_dpp v158, v154, v182 row_ror:15 row_mask:0xf bank_mask:0xf
	v_fmac_f32_dpp v159, v155, v183 row_ror:15 row_mask:0xf bank_mask:0xf
	v_cndmask_b32_e32 v148, v100, v112, vcc
	v_cndmask_b32_e32 v149, v101, v113, vcc
	v_cndmask_b32_e32 v150, v102, v114, vcc
	v_cndmask_b32_e32 v151, v103, v115, vcc
	v_cndmask_b32_e64 v152, v100, v92, s[98:99]
	v_cndmask_b32_e64 v153, v101, v93, s[98:99]
	v_cndmask_b32_e64 v154, v102, v94, s[98:99]
	v_cndmask_b32_e64 v155, v103, v95, s[98:99]
	v_fma_f32 v237, v192, v100, v200
	v_fma_f32 v238, v193, v101, v201
	v_fma_f32 v239, v194, v102, v202
	v_fma_f32 v240, v195, v103, v203
	v_fmac_f32_dpp v237, v148, v188 row_ror:1 row_mask:0xf bank_mask:0xf
	v_fmac_f32_dpp v238, v149, v189 row_ror:1 row_mask:0xf bank_mask:0xf
	v_fmac_f32_dpp v239, v150, v190 row_ror:1 row_mask:0xf bank_mask:0xf
	v_fmac_f32_dpp v240, v151, v191 row_ror:1 row_mask:0xf bank_mask:0xf
	v_fmac_f32_dpp v237, v152, v196 row_ror:15 row_mask:0xf bank_mask:0xf
	v_fmac_f32_dpp v238, v153, v197 row_ror:15 row_mask:0xf bank_mask:0xf
	v_fmac_f32_dpp v239, v154, v198 row_ror:15 row_mask:0xf bank_mask:0xf
	v_fmac_f32_dpp v240, v155, v199 row_ror:15 row_mask:0xf bank_mask:0xf
	v_mul_f32_e32 v148, 0xbfb8aa3b, v156
	v_mul_f32_e32 v149, 0xbfb8aa3b, v157
	v_mul_f32_e32 v150, 0xbfb8aa3b, v158
	v_mul_f32_e32 v151, 0xbfb8aa3b, v159
	v_exp_f32_e32 v148, v148
	v_exp_f32_e32 v149, v149
	v_exp_f32_e32 v150, v150
	v_exp_f32_e32 v151, v151
	v_add_f32_e32 v148, 1.0, v148
	v_add_f32_e32 v149, 1.0, v149
	v_add_f32_e32 v150, 1.0, v150
	v_add_f32_e32 v151, 1.0, v151
	v_rcp_f32_e32 v148, v148
	v_rcp_f32_e32 v149, v149
	v_rcp_f32_e32 v150, v150
	v_rcp_f32_e32 v151, v151
	v_mul_f32_e32 v156, v156, v148
	v_mul_f32_e32 v157, v157, v149
	v_mul_f32_e32 v158, v158, v150
	v_mul_f32_e32 v159, v159, v151
	v_mul_f32_e32 v156, v156, v237
	v_mul_f32_e32 v157, v157, v238
	v_mul_f32_e32 v158, v158, v239
	v_mul_f32_e32 v159, v159, v240
	v_cvt_pk_bf16_f32 v243, v156, v157
	v_cvt_pk_bf16_f32 v244, v158, v159
	v_cndmask_b32_e32 v148, v116, v120, vcc
	v_cndmask_b32_e32 v149, v117, v121, vcc
	v_cndmask_b32_e32 v150, v118, v122, vcc
	v_cndmask_b32_e32 v151, v119, v123, vcc
	v_cndmask_b32_e64 v152, v116, v104, s[98:99]
	v_cndmask_b32_e64 v153, v117, v105, s[98:99]
	v_cndmask_b32_e64 v154, v118, v106, s[98:99]
	v_cndmask_b32_e64 v155, v119, v107, s[98:99]
	v_fma_f32 v156, v176, v116, v184
	v_fma_f32 v157, v177, v117, v185
	v_fma_f32 v158, v178, v118, v186
	v_fma_f32 v159, v179, v119, v187
	v_fmac_f32_dpp v156, v148, v172 row_ror:1 row_mask:0xf bank_mask:0xf
	v_fmac_f32_dpp v157, v149, v173 row_ror:1 row_mask:0xf bank_mask:0xf
	v_fmac_f32_dpp v158, v150, v174 row_ror:1 row_mask:0xf bank_mask:0xf
	v_fmac_f32_dpp v159, v151, v175 row_ror:1 row_mask:0xf bank_mask:0xf
	v_fmac_f32_dpp v156, v152, v180 row_ror:15 row_mask:0xf bank_mask:0xf
	v_fmac_f32_dpp v157, v153, v181 row_ror:15 row_mask:0xf bank_mask:0xf
	v_fmac_f32_dpp v158, v154, v182 row_ror:15 row_mask:0xf bank_mask:0xf
	v_fmac_f32_dpp v159, v155, v183 row_ror:15 row_mask:0xf bank_mask:0xf
	v_cndmask_b32_e32 v148, v92, v100, vcc
	v_cndmask_b32_e32 v149, v93, v101, vcc
	v_cndmask_b32_e32 v150, v94, v102, vcc
	v_cndmask_b32_e32 v151, v95, v103, vcc
	v_cndmask_b32_e64 v152, v92, v80, s[98:99]
	v_cndmask_b32_e64 v153, v93, v81, s[98:99]
	v_cndmask_b32_e64 v154, v94, v82, s[98:99]
	v_cndmask_b32_e64 v155, v95, v83, s[98:99]
	v_fma_f32 v237, v192, v92, v200
	v_fma_f32 v238, v193, v93, v201
	v_fma_f32 v239, v194, v94, v202
	v_fma_f32 v240, v195, v95, v203
	v_fmac_f32_dpp v237, v148, v188 row_ror:1 row_mask:0xf bank_mask:0xf
	v_fmac_f32_dpp v238, v149, v189 row_ror:1 row_mask:0xf bank_mask:0xf
	v_fmac_f32_dpp v239, v150, v190 row_ror:1 row_mask:0xf bank_mask:0xf
	v_fmac_f32_dpp v240, v151, v191 row_ror:1 row_mask:0xf bank_mask:0xf
	v_fmac_f32_dpp v237, v152, v196 row_ror:15 row_mask:0xf bank_mask:0xf
	v_fmac_f32_dpp v238, v153, v197 row_ror:15 row_mask:0xf bank_mask:0xf
	v_fmac_f32_dpp v239, v154, v198 row_ror:15 row_mask:0xf bank_mask:0xf
	v_fmac_f32_dpp v240, v155, v199 row_ror:15 row_mask:0xf bank_mask:0xf
	v_mul_f32_e32 v148, 0xbfb8aa3b, v156
	v_mul_f32_e32 v149, 0xbfb8aa3b, v157
	v_mul_f32_e32 v150, 0xbfb8aa3b, v158
	v_mul_f32_e32 v151, 0xbfb8aa3b, v159
	v_exp_f32_e32 v148, v148
	v_exp_f32_e32 v149, v149
	v_exp_f32_e32 v150, v150
	v_exp_f32_e32 v151, v151
	v_add_f32_e32 v148, 1.0, v148
	v_add_f32_e32 v149, 1.0, v149
	v_add_f32_e32 v150, 1.0, v150
	v_add_f32_e32 v151, 1.0, v151
	v_rcp_f32_e32 v148, v148
	v_rcp_f32_e32 v149, v149
	v_rcp_f32_e32 v150, v150
	v_rcp_f32_e32 v151, v151
	v_mul_f32_e32 v156, v156, v148
	v_mul_f32_e32 v157, v157, v149
	v_mul_f32_e32 v158, v158, v150
	v_mul_f32_e32 v159, v159, v151
	v_mul_f32_e32 v156, v156, v237
	v_mul_f32_e32 v157, v157, v238
	v_mul_f32_e32 v158, v158, v239
	v_mul_f32_e32 v159, v159, v240
	v_cvt_pk_bf16_f32 v253, v156, v157
	v_cvt_pk_bf16_f32 v254, v158, v159
	v_cndmask_b32_e32 v148, v104, v116, vcc
	v_cndmask_b32_e32 v149, v105, v117, vcc
	v_cndmask_b32_e32 v150, v106, v118, vcc
	v_cndmask_b32_e32 v151, v107, v119, vcc
	v_cndmask_b32_e64 v152, v104, v160, s[98:99]
	v_cndmask_b32_e64 v153, v105, v161, s[98:99]
	v_cndmask_b32_e64 v154, v106, v162, s[98:99]
	v_cndmask_b32_e64 v155, v107, v163, s[98:99]
	v_fma_f32 v156, v176, v104, v184
	v_fma_f32 v157, v177, v105, v185
	v_fma_f32 v158, v178, v106, v186
	v_fma_f32 v159, v179, v107, v187
	v_fmac_f32_dpp v156, v148, v172 row_ror:1 row_mask:0xf bank_mask:0xf
	v_fmac_f32_dpp v157, v149, v173 row_ror:1 row_mask:0xf bank_mask:0xf
	v_fmac_f32_dpp v158, v150, v174 row_ror:1 row_mask:0xf bank_mask:0xf
	v_fmac_f32_dpp v159, v151, v175 row_ror:1 row_mask:0xf bank_mask:0xf
	v_fmac_f32_dpp v156, v152, v180 row_ror:15 row_mask:0xf bank_mask:0xf
	v_fmac_f32_dpp v157, v153, v181 row_ror:15 row_mask:0xf bank_mask:0xf
	v_fmac_f32_dpp v158, v154, v182 row_ror:15 row_mask:0xf bank_mask:0xf
	v_fmac_f32_dpp v159, v155, v183 row_ror:15 row_mask:0xf bank_mask:0xf
	v_cndmask_b32_e32 v148, v80, v92, vcc
	v_cndmask_b32_e32 v149, v81, v93, vcc
	v_cndmask_b32_e32 v150, v82, v94, vcc
	v_cndmask_b32_e32 v151, v83, v95, vcc
	v_cndmask_b32_e64 v152, v80, v164, s[98:99]
	v_cndmask_b32_e64 v153, v81, v165, s[98:99]
	v_cndmask_b32_e64 v154, v82, v166, s[98:99]
	v_cndmask_b32_e64 v155, v83, v167, s[98:99]
	v_fma_f32 v237, v192, v80, v200
	v_fma_f32 v238, v193, v81, v201
	v_fma_f32 v239, v194, v82, v202
	v_fma_f32 v240, v195, v83, v203
	v_fmac_f32_dpp v237, v148, v188 row_ror:1 row_mask:0xf bank_mask:0xf
	v_fmac_f32_dpp v238, v149, v189 row_ror:1 row_mask:0xf bank_mask:0xf
	v_fmac_f32_dpp v239, v150, v190 row_ror:1 row_mask:0xf bank_mask:0xf
	v_fmac_f32_dpp v240, v151, v191 row_ror:1 row_mask:0xf bank_mask:0xf
	v_fmac_f32_dpp v237, v152, v196 row_ror:15 row_mask:0xf bank_mask:0xf
	v_fmac_f32_dpp v238, v153, v197 row_ror:15 row_mask:0xf bank_mask:0xf
	v_fmac_f32_dpp v239, v154, v198 row_ror:15 row_mask:0xf bank_mask:0xf
	v_fmac_f32_dpp v240, v155, v199 row_ror:15 row_mask:0xf bank_mask:0xf
	v_mul_f32_e32 v148, 0xbfb8aa3b, v156
	v_mul_f32_e32 v149, 0xbfb8aa3b, v157
	v_mul_f32_e32 v150, 0xbfb8aa3b, v158
	v_mul_f32_e32 v151, 0xbfb8aa3b, v159
	v_exp_f32_e32 v148, v148
	v_exp_f32_e32 v149, v149
	v_exp_f32_e32 v150, v150
	v_exp_f32_e32 v151, v151
	v_add_f32_e32 v148, 1.0, v148
	v_add_f32_e32 v149, 1.0, v149
	v_add_f32_e32 v150, 1.0, v150
	v_add_f32_e32 v151, 1.0, v151
	v_rcp_f32_e32 v148, v148
	v_rcp_f32_e32 v149, v149
	v_rcp_f32_e32 v150, v150
	v_rcp_f32_e32 v151, v151
	v_mul_f32_e32 v156, v156, v148
	v_mul_f32_e32 v157, v157, v149
	v_mul_f32_e32 v158, v158, v150
	v_mul_f32_e32 v159, v159, v151
	v_mul_f32_e32 v156, v156, v237
	v_mul_f32_e32 v157, v157, v238
	v_mul_f32_e32 v158, v158, v239
	v_mul_f32_e32 v159, v159, v240
	v_cvt_pk_bf16_f32 v255, v156, v157
	v_cvt_pk_bf16_f32 v246, v158, v159
	global_load_dwordx4 v[124:127], v146, s[62:63] offset:64
	global_load_dwordx4 v[120:123], v147, s[62:63] offset:64
	global_load_dwordx4 v[116:119], v168, s[62:63] offset:64
	global_load_dwordx4 v[112:115], v169, s[62:63] offset:64
	global_load_dwordx4 v[100:103], v245, s[62:63] offset:64
	global_load_dwordx4 v[92:95], v252, s[62:63] offset:64
	global_load_dwordx4 v[104:107], v146, s[64:65] offset:64
	global_load_dwordx4 v[80:83], v169, s[64:65] offset:64
	ds_read_b128 v[160:163], v249 offset:7168
	ds_read_b128 v[164:167], v249 offset:7680
	s_waitcnt lgkmcnt(2)
	v_cndmask_b32_e32 v148, v72, v204, vcc
	v_cndmask_b32_e32 v149, v73, v205, vcc
	v_cndmask_b32_e32 v150, v74, v206, vcc
	v_cndmask_b32_e32 v151, v75, v207, vcc
	v_cndmask_b32_e64 v152, v72, v64, s[98:99]
	v_cndmask_b32_e64 v153, v73, v65, s[98:99]
	v_cndmask_b32_e64 v154, v74, v66, s[98:99]
	v_cndmask_b32_e64 v155, v75, v67, s[98:99]
	v_fma_f32 v156, v176, v72, v184
	v_fma_f32 v157, v177, v73, v185
	v_fma_f32 v158, v178, v74, v186
	v_fma_f32 v159, v179, v75, v187
	v_fmac_f32_dpp v156, v148, v172 row_ror:1 row_mask:0xf bank_mask:0xf
	v_fmac_f32_dpp v157, v149, v173 row_ror:1 row_mask:0xf bank_mask:0xf
	v_fmac_f32_dpp v158, v150, v174 row_ror:1 row_mask:0xf bank_mask:0xf
	v_fmac_f32_dpp v159, v151, v175 row_ror:1 row_mask:0xf bank_mask:0xf
	v_fmac_f32_dpp v156, v152, v180 row_ror:15 row_mask:0xf bank_mask:0xf
	v_fmac_f32_dpp v157, v153, v181 row_ror:15 row_mask:0xf bank_mask:0xf
	v_fmac_f32_dpp v158, v154, v182 row_ror:15 row_mask:0xf bank_mask:0xf
	v_fmac_f32_dpp v159, v155, v183 row_ror:15 row_mask:0xf bank_mask:0xf
	v_cndmask_b32_e32 v148, v48, v208, vcc
	v_cndmask_b32_e32 v149, v49, v209, vcc
	v_cndmask_b32_e32 v150, v50, v210, vcc
	v_cndmask_b32_e32 v151, v51, v211, vcc
	v_cndmask_b32_e64 v152, v48, v36, s[98:99]
	v_cndmask_b32_e64 v153, v49, v37, s[98:99]
	v_cndmask_b32_e64 v154, v50, v38, s[98:99]
	v_cndmask_b32_e64 v155, v51, v39, s[98:99]
	v_fma_f32 v237, v192, v48, v200
	v_fma_f32 v238, v193, v49, v201
	v_fma_f32 v239, v194, v50, v202
	v_fma_f32 v240, v195, v51, v203
	v_fmac_f32_dpp v237, v148, v188 row_ror:1 row_mask:0xf bank_mask:0xf
	v_fmac_f32_dpp v238, v149, v189 row_ror:1 row_mask:0xf bank_mask:0xf
	v_fmac_f32_dpp v239, v150, v190 row_ror:1 row_mask:0xf bank_mask:0xf
	v_fmac_f32_dpp v240, v151, v191 row_ror:1 row_mask:0xf bank_mask:0xf
	v_fmac_f32_dpp v237, v152, v196 row_ror:15 row_mask:0xf bank_mask:0xf
	v_fmac_f32_dpp v238, v153, v197 row_ror:15 row_mask:0xf bank_mask:0xf
	v_fmac_f32_dpp v239, v154, v198 row_ror:15 row_mask:0xf bank_mask:0xf
	v_fmac_f32_dpp v240, v155, v199 row_ror:15 row_mask:0xf bank_mask:0xf
	v_mul_f32_e32 v148, 0xbfb8aa3b, v156
	v_mul_f32_e32 v149, 0xbfb8aa3b, v157
	v_mul_f32_e32 v150, 0xbfb8aa3b, v158
	v_mul_f32_e32 v151, 0xbfb8aa3b, v159
	v_exp_f32_e32 v148, v148
	v_exp_f32_e32 v149, v149
	v_exp_f32_e32 v150, v150
	v_exp_f32_e32 v151, v151
	v_add_f32_e32 v148, 1.0, v148
	v_add_f32_e32 v149, 1.0, v149
	v_add_f32_e32 v150, 1.0, v150
	v_add_f32_e32 v151, 1.0, v151
	v_rcp_f32_e32 v148, v148
	v_rcp_f32_e32 v149, v149
	v_rcp_f32_e32 v150, v150
	v_rcp_f32_e32 v151, v151
	v_mul_f32_e32 v156, v156, v148
	v_mul_f32_e32 v157, v157, v149
	v_mul_f32_e32 v158, v158, v150
	v_mul_f32_e32 v159, v159, v151
	v_mul_f32_e32 v156, v156, v237
	v_mul_f32_e32 v157, v157, v238
	v_mul_f32_e32 v158, v158, v239
	v_mul_f32_e32 v159, v159, v240
	v_cvt_pk_bf16_f32 v247, v156, v157
	v_cvt_pk_bf16_f32 v248, v158, v159
	ds_read_b128 v[204:207], v249 offset:64
	ds_read_b128 v[208:211], v249 offset:576
	v_cndmask_b32_e32 v148, v64, v72, vcc
	v_cndmask_b32_e32 v149, v65, v73, vcc
	v_cndmask_b32_e32 v150, v66, v74, vcc
	v_cndmask_b32_e32 v151, v67, v75, vcc
	v_cndmask_b32_e64 v152, v64, v56, s[98:99]
	v_cndmask_b32_e64 v153, v65, v57, s[98:99]
	v_cndmask_b32_e64 v154, v66, v58, s[98:99]
	v_cndmask_b32_e64 v155, v67, v59, s[98:99]
	v_fma_f32 v156, v176, v64, v184
	v_fma_f32 v157, v177, v65, v185
	v_fma_f32 v158, v178, v66, v186
	v_fma_f32 v159, v179, v67, v187
	v_fmac_f32_dpp v156, v148, v172 row_ror:1 row_mask:0xf bank_mask:0xf
	v_fmac_f32_dpp v157, v149, v173 row_ror:1 row_mask:0xf bank_mask:0xf
	v_fmac_f32_dpp v158, v150, v174 row_ror:1 row_mask:0xf bank_mask:0xf
	v_fmac_f32_dpp v159, v151, v175 row_ror:1 row_mask:0xf bank_mask:0xf
	v_fmac_f32_dpp v156, v152, v180 row_ror:15 row_mask:0xf bank_mask:0xf
	v_fmac_f32_dpp v157, v153, v181 row_ror:15 row_mask:0xf bank_mask:0xf
	v_fmac_f32_dpp v158, v154, v182 row_ror:15 row_mask:0xf bank_mask:0xf
	v_fmac_f32_dpp v159, v155, v183 row_ror:15 row_mask:0xf bank_mask:0xf
	v_cndmask_b32_e32 v148, v36, v48, vcc
	v_cndmask_b32_e32 v149, v37, v49, vcc
	v_cndmask_b32_e32 v150, v38, v50, vcc
	v_cndmask_b32_e32 v151, v39, v51, vcc
	v_cndmask_b32_e64 v152, v36, v28, s[98:99]
	v_cndmask_b32_e64 v153, v37, v29, s[98:99]
	v_cndmask_b32_e64 v154, v38, v30, s[98:99]
	v_cndmask_b32_e64 v155, v39, v31, s[98:99]
	v_fma_f32 v237, v192, v36, v200
	v_fma_f32 v238, v193, v37, v201
	v_fma_f32 v239, v194, v38, v202
	v_fma_f32 v240, v195, v39, v203
	v_fmac_f32_dpp v237, v148, v188 row_ror:1 row_mask:0xf bank_mask:0xf
	v_fmac_f32_dpp v238, v149, v189 row_ror:1 row_mask:0xf bank_mask:0xf
	v_fmac_f32_dpp v239, v150, v190 row_ror:1 row_mask:0xf bank_mask:0xf
	v_fmac_f32_dpp v240, v151, v191 row_ror:1 row_mask:0xf bank_mask:0xf
	v_fmac_f32_dpp v237, v152, v196 row_ror:15 row_mask:0xf bank_mask:0xf
	v_fmac_f32_dpp v238, v153, v197 row_ror:15 row_mask:0xf bank_mask:0xf
	v_fmac_f32_dpp v239, v154, v198 row_ror:15 row_mask:0xf bank_mask:0xf
	v_fmac_f32_dpp v240, v155, v199 row_ror:15 row_mask:0xf bank_mask:0xf
	v_mul_f32_e32 v148, 0xbfb8aa3b, v156
	v_mul_f32_e32 v149, 0xbfb8aa3b, v157
	v_mul_f32_e32 v150, 0xbfb8aa3b, v158
	v_mul_f32_e32 v151, 0xbfb8aa3b, v159
	v_exp_f32_e32 v148, v148
	v_exp_f32_e32 v149, v149
	v_exp_f32_e32 v150, v150
	v_exp_f32_e32 v151, v151
	v_add_f32_e32 v148, 1.0, v148
	v_add_f32_e32 v149, 1.0, v149
	v_add_f32_e32 v150, 1.0, v150
	v_add_f32_e32 v151, 1.0, v151
	v_rcp_f32_e32 v148, v148
	v_rcp_f32_e32 v149, v149
	v_rcp_f32_e32 v150, v150
	v_rcp_f32_e32 v151, v151
	v_mul_f32_e32 v156, v156, v148
	v_mul_f32_e32 v157, v157, v149
	v_mul_f32_e32 v158, v158, v150
	v_mul_f32_e32 v159, v159, v151
	v_mul_f32_e32 v156, v156, v237
	v_mul_f32_e32 v157, v157, v238
	v_mul_f32_e32 v158, v158, v239
	v_mul_f32_e32 v159, v159, v240
	v_cvt_pk_bf16_f32 v72, v156, v157
	v_cvt_pk_bf16_f32 v73, v158, v159
	v_cndmask_b32_e32 v148, v56, v64, vcc
	v_cndmask_b32_e32 v149, v57, v65, vcc
	v_cndmask_b32_e32 v150, v58, v66, vcc
	v_cndmask_b32_e32 v151, v59, v67, vcc
	v_cndmask_b32_e64 v152, v56, v40, s[98:99]
	v_cndmask_b32_e64 v153, v57, v41, s[98:99]
	v_cndmask_b32_e64 v154, v58, v42, s[98:99]
	v_cndmask_b32_e64 v155, v59, v43, s[98:99]
	v_fma_f32 v156, v176, v56, v184
	v_fma_f32 v157, v177, v57, v185
	v_fma_f32 v158, v178, v58, v186
	v_fma_f32 v159, v179, v59, v187
	v_fmac_f32_dpp v156, v148, v172 row_ror:1 row_mask:0xf bank_mask:0xf
	v_fmac_f32_dpp v157, v149, v173 row_ror:1 row_mask:0xf bank_mask:0xf
	v_fmac_f32_dpp v158, v150, v174 row_ror:1 row_mask:0xf bank_mask:0xf
	v_fmac_f32_dpp v159, v151, v175 row_ror:1 row_mask:0xf bank_mask:0xf
	v_fmac_f32_dpp v156, v152, v180 row_ror:15 row_mask:0xf bank_mask:0xf
	v_fmac_f32_dpp v157, v153, v181 row_ror:15 row_mask:0xf bank_mask:0xf
	v_fmac_f32_dpp v158, v154, v182 row_ror:15 row_mask:0xf bank_mask:0xf
	v_fmac_f32_dpp v159, v155, v183 row_ror:15 row_mask:0xf bank_mask:0xf
	v_cndmask_b32_e32 v148, v28, v36, vcc
	v_cndmask_b32_e32 v149, v29, v37, vcc
	v_cndmask_b32_e32 v150, v30, v38, vcc
	v_cndmask_b32_e32 v151, v31, v39, vcc
	v_cndmask_b32_e64 v152, v28, v16, s[98:99]
	v_cndmask_b32_e64 v153, v29, v17, s[98:99]
	v_cndmask_b32_e64 v154, v30, v18, s[98:99]
	v_cndmask_b32_e64 v155, v31, v19, s[98:99]
	v_fma_f32 v237, v192, v28, v200
	v_fma_f32 v238, v193, v29, v201
	v_fma_f32 v239, v194, v30, v202
	v_fma_f32 v240, v195, v31, v203
	v_fmac_f32_dpp v237, v148, v188 row_ror:1 row_mask:0xf bank_mask:0xf
	v_fmac_f32_dpp v238, v149, v189 row_ror:1 row_mask:0xf bank_mask:0xf
	v_fmac_f32_dpp v239, v150, v190 row_ror:1 row_mask:0xf bank_mask:0xf
	v_fmac_f32_dpp v240, v151, v191 row_ror:1 row_mask:0xf bank_mask:0xf
	v_fmac_f32_dpp v237, v152, v196 row_ror:15 row_mask:0xf bank_mask:0xf
	v_fmac_f32_dpp v238, v153, v197 row_ror:15 row_mask:0xf bank_mask:0xf
	v_fmac_f32_dpp v239, v154, v198 row_ror:15 row_mask:0xf bank_mask:0xf
	v_fmac_f32_dpp v240, v155, v199 row_ror:15 row_mask:0xf bank_mask:0xf
	v_mul_f32_e32 v148, 0xbfb8aa3b, v156
	v_mul_f32_e32 v149, 0xbfb8aa3b, v157
	v_mul_f32_e32 v150, 0xbfb8aa3b, v158
	v_mul_f32_e32 v151, 0xbfb8aa3b, v159
	v_exp_f32_e32 v148, v148
	v_exp_f32_e32 v149, v149
	v_exp_f32_e32 v150, v150
	v_exp_f32_e32 v151, v151
	v_add_f32_e32 v148, 1.0, v148
	v_add_f32_e32 v149, 1.0, v149
	v_add_f32_e32 v150, 1.0, v150
	v_add_f32_e32 v151, 1.0, v151
	v_rcp_f32_e32 v148, v148
	v_rcp_f32_e32 v149, v149
	v_rcp_f32_e32 v150, v150
	v_rcp_f32_e32 v151, v151
	v_mul_f32_e32 v156, v156, v148
	v_mul_f32_e32 v157, v157, v149
	v_mul_f32_e32 v158, v158, v150
	v_mul_f32_e32 v159, v159, v151
	v_mul_f32_e32 v156, v156, v237
	v_mul_f32_e32 v157, v157, v238
	v_mul_f32_e32 v158, v158, v239
	v_mul_f32_e32 v159, v159, v240
	v_cvt_pk_bf16_f32 v74, v156, v157
	v_cvt_pk_bf16_f32 v75, v158, v159
	s_waitcnt lgkmcnt(2)
	v_cndmask_b32_e32 v148, v40, v56, vcc
	v_cndmask_b32_e32 v149, v41, v57, vcc
	v_cndmask_b32_e32 v150, v42, v58, vcc
	v_cndmask_b32_e32 v151, v43, v59, vcc
	v_cndmask_b32_e64 v152, v40, v160, s[98:99]
	v_cndmask_b32_e64 v153, v41, v161, s[98:99]
	v_cndmask_b32_e64 v154, v42, v162, s[98:99]
	v_cndmask_b32_e64 v155, v43, v163, s[98:99]
	v_fma_f32 v156, v176, v40, v184
	v_fma_f32 v157, v177, v41, v185
	v_fma_f32 v158, v178, v42, v186
	v_fma_f32 v159, v179, v43, v187
	v_fmac_f32_dpp v156, v148, v172 row_ror:1 row_mask:0xf bank_mask:0xf
	v_fmac_f32_dpp v157, v149, v173 row_ror:1 row_mask:0xf bank_mask:0xf
	v_fmac_f32_dpp v158, v150, v174 row_ror:1 row_mask:0xf bank_mask:0xf
	v_fmac_f32_dpp v159, v151, v175 row_ror:1 row_mask:0xf bank_mask:0xf
	v_fmac_f32_dpp v156, v152, v180 row_ror:15 row_mask:0xf bank_mask:0xf
	v_fmac_f32_dpp v157, v153, v181 row_ror:15 row_mask:0xf bank_mask:0xf
	v_fmac_f32_dpp v158, v154, v182 row_ror:15 row_mask:0xf bank_mask:0xf
	v_fmac_f32_dpp v159, v155, v183 row_ror:15 row_mask:0xf bank_mask:0xf
	v_cndmask_b32_e32 v148, v16, v28, vcc
	v_cndmask_b32_e32 v149, v17, v29, vcc
	v_cndmask_b32_e32 v150, v18, v30, vcc
	v_cndmask_b32_e32 v151, v19, v31, vcc
	v_cndmask_b32_e64 v152, v16, v164, s[98:99]
	v_cndmask_b32_e64 v153, v17, v165, s[98:99]
	v_cndmask_b32_e64 v154, v18, v166, s[98:99]
	v_cndmask_b32_e64 v155, v19, v167, s[98:99]
	v_fma_f32 v237, v192, v16, v200
	v_fma_f32 v238, v193, v17, v201
	v_fma_f32 v239, v194, v18, v202
	v_fma_f32 v240, v195, v19, v203
	v_fmac_f32_dpp v237, v148, v188 row_ror:1 row_mask:0xf bank_mask:0xf
	v_fmac_f32_dpp v238, v149, v189 row_ror:1 row_mask:0xf bank_mask:0xf
	v_fmac_f32_dpp v239, v150, v190 row_ror:1 row_mask:0xf bank_mask:0xf
	v_fmac_f32_dpp v240, v151, v191 row_ror:1 row_mask:0xf bank_mask:0xf
	v_fmac_f32_dpp v237, v152, v196 row_ror:15 row_mask:0xf bank_mask:0xf
	v_fmac_f32_dpp v238, v153, v197 row_ror:15 row_mask:0xf bank_mask:0xf
	v_fmac_f32_dpp v239, v154, v198 row_ror:15 row_mask:0xf bank_mask:0xf
	v_fmac_f32_dpp v240, v155, v199 row_ror:15 row_mask:0xf bank_mask:0xf
	v_mul_f32_e32 v148, 0xbfb8aa3b, v156
	v_mul_f32_e32 v149, 0xbfb8aa3b, v157
	v_mul_f32_e32 v150, 0xbfb8aa3b, v158
	v_mul_f32_e32 v151, 0xbfb8aa3b, v159
	v_exp_f32_e32 v148, v148
	v_exp_f32_e32 v149, v149
	v_exp_f32_e32 v150, v150
	v_exp_f32_e32 v151, v151
	v_add_f32_e32 v148, 1.0, v148
	v_add_f32_e32 v149, 1.0, v149
	v_add_f32_e32 v150, 1.0, v150
	v_add_f32_e32 v151, 1.0, v151
	v_rcp_f32_e32 v148, v148
	v_rcp_f32_e32 v149, v149
	v_rcp_f32_e32 v150, v150
	v_rcp_f32_e32 v151, v151
	v_mul_f32_e32 v156, v156, v148
	v_mul_f32_e32 v157, v157, v149
	v_mul_f32_e32 v158, v158, v150
	v_mul_f32_e32 v159, v159, v151
	v_mul_f32_e32 v156, v156, v237
	v_mul_f32_e32 v157, v157, v238
	v_mul_f32_e32 v158, v158, v239
	v_mul_f32_e32 v159, v159, v240
	v_cvt_pk_bf16_f32 v48, v156, v157
	v_cvt_pk_bf16_f32 v49, v158, v159
	ds_read_b128 v[160:163], v249 offset:3136
	ds_read_b128 v[164:167], v249 offset:3648
	s_waitcnt vmcnt(0) lgkmcnt(0)
	v_mbcnt_lo_u32_b32 v146, -1, 0
	v_mbcnt_hi_u32_b32 v146, -1, v146
	v_bfe_i32 v146, v146, 4, 1
	v_cndmask_b32_e32 v148, v108, v204, vcc
	v_cndmask_b32_e32 v149, v109, v205, vcc
	v_cndmask_b32_e32 v150, v110, v206, vcc
	v_cndmask_b32_e32 v151, v111, v207, vcc
	v_cndmask_b32_e64 v152, v108, v96, s[98:99]
	v_cndmask_b32_e64 v153, v109, v97, s[98:99]
	v_cndmask_b32_e64 v154, v110, v98, s[98:99]
	v_cndmask_b32_e64 v155, v111, v99, s[98:99]
	v_fma_f32 v156, v120, v108, v104
	v_fma_f32 v157, v121, v109, v105
	v_fma_f32 v158, v122, v110, v106
	v_fma_f32 v159, v123, v111, v107
	v_fmac_f32_dpp v156, v148, v124 row_ror:1 row_mask:0xf bank_mask:0xf
	v_fmac_f32_dpp v157, v149, v125 row_ror:1 row_mask:0xf bank_mask:0xf
	v_fmac_f32_dpp v158, v150, v126 row_ror:1 row_mask:0xf bank_mask:0xf
	v_fmac_f32_dpp v159, v151, v127 row_ror:1 row_mask:0xf bank_mask:0xf
	v_fmac_f32_dpp v156, v152, v116 row_ror:15 row_mask:0xf bank_mask:0xf
	v_fmac_f32_dpp v157, v153, v117 row_ror:15 row_mask:0xf bank_mask:0xf
	v_fmac_f32_dpp v158, v154, v118 row_ror:15 row_mask:0xf bank_mask:0xf
	v_fmac_f32_dpp v159, v155, v119 row_ror:15 row_mask:0xf bank_mask:0xf
	v_cndmask_b32_e32 v148, v84, v208, vcc
	v_cndmask_b32_e32 v149, v85, v209, vcc
	v_cndmask_b32_e32 v150, v86, v210, vcc
	v_cndmask_b32_e32 v151, v87, v211, vcc
	v_cndmask_b32_e64 v152, v84, v68, s[98:99]
	v_cndmask_b32_e64 v153, v85, v69, s[98:99]
	v_cndmask_b32_e64 v154, v86, v70, s[98:99]
	v_cndmask_b32_e64 v155, v87, v71, s[98:99]
	v_fma_f32 v237, v100, v84, v80
	v_fma_f32 v238, v101, v85, v81
	v_fma_f32 v239, v102, v86, v82
	v_fma_f32 v240, v103, v87, v83
	v_fmac_f32_dpp v237, v148, v112 row_ror:1 row_mask:0xf bank_mask:0xf
	v_fmac_f32_dpp v238, v149, v113 row_ror:1 row_mask:0xf bank_mask:0xf
	v_fmac_f32_dpp v239, v150, v114 row_ror:1 row_mask:0xf bank_mask:0xf
	v_fmac_f32_dpp v240, v151, v115 row_ror:1 row_mask:0xf bank_mask:0xf
	v_fmac_f32_dpp v237, v152, v92 row_ror:15 row_mask:0xf bank_mask:0xf
	v_fmac_f32_dpp v238, v153, v93 row_ror:15 row_mask:0xf bank_mask:0xf
	v_fmac_f32_dpp v239, v154, v94 row_ror:15 row_mask:0xf bank_mask:0xf
	v_fmac_f32_dpp v240, v155, v95 row_ror:15 row_mask:0xf bank_mask:0xf
	v_mul_f32_e32 v148, 0xbfb8aa3b, v156
	v_mul_f32_e32 v149, 0xbfb8aa3b, v157
	v_mul_f32_e32 v150, 0xbfb8aa3b, v158
	v_mul_f32_e32 v151, 0xbfb8aa3b, v159
	v_exp_f32_e32 v148, v148
	v_exp_f32_e32 v149, v149
	v_exp_f32_e32 v150, v150
	v_exp_f32_e32 v151, v151
	v_add_f32_e32 v148, 1.0, v148
	v_add_f32_e32 v149, 1.0, v149
	v_add_f32_e32 v150, 1.0, v150
	v_add_f32_e32 v151, 1.0, v151
	v_rcp_f32_e32 v148, v148
	v_rcp_f32_e32 v149, v149
	v_rcp_f32_e32 v150, v150
	v_rcp_f32_e32 v151, v151
	v_mul_f32_e32 v156, v156, v148
	v_mul_f32_e32 v157, v157, v149
	v_mul_f32_e32 v158, v158, v150
	v_mul_f32_e32 v159, v159, v151
	v_mul_f32_e32 v156, v156, v237
	v_mul_f32_e32 v157, v157, v238
	v_mul_f32_e32 v158, v158, v239
	v_mul_f32_e32 v159, v159, v240
	v_cvt_pk_bf16_f32 v40, v156, v157
	v_cvt_pk_bf16_f32 v41, v158, v159
	v_bfi_b32 v18, v146, v241, v40
	v_bfi_b32 v19, v146, v242, v41
	ds_swizzle_b32 v16, v18 offset:0x401f
	ds_swizzle_b32 v17, v19 offset:0x401f
	v_mov_b32_e32 v42, v250
	v_lshrrev_b32_e32 v152, 6, v251
	s_nop 1
	v_readfirstlane_b32 s100, v152
	s_waitcnt lgkmcnt(0)
	v_bfi_b32 v148, v146, v16, v241
	v_bfi_b32 v149, v146, v17, v242
	v_bfi_b32 v150, v146, v40, v16
	v_bfi_b32 v151, v146, v41, v17
	s_cmp_eq_u32 s100, 0
	s_cselect_b64 s[100:101], s[98:99], 0
	s_andn2_b64 exec, exec, s[100:101]
	global_store_dwordx4 v42, v[148:151], s[14:15] nt
	s_mov_b64 exec, -1
	s_nop 1
	ds_read_b128 v[204:207], v249 offset:4160
	ds_read_b128 v[208:211], v249 offset:4672
	v_cndmask_b32_e32 v148, v96, v108, vcc
	v_cndmask_b32_e32 v149, v97, v109, vcc
	v_cndmask_b32_e32 v150, v98, v110, vcc
	v_cndmask_b32_e32 v151, v99, v111, vcc
	v_cndmask_b32_e64 v152, v96, v88, s[98:99]
	v_cndmask_b32_e64 v153, v97, v89, s[98:99]
	v_cndmask_b32_e64 v154, v98, v90, s[98:99]
	v_cndmask_b32_e64 v155, v99, v91, s[98:99]
	v_fma_f32 v156, v120, v96, v104
	v_fma_f32 v157, v121, v97, v105
	v_fma_f32 v158, v122, v98, v106
	v_fma_f32 v159, v123, v99, v107
	v_fmac_f32_dpp v156, v148, v124 row_ror:1 row_mask:0xf bank_mask:0xf
	v_fmac_f32_dpp v157, v149, v125 row_ror:1 row_mask:0xf bank_mask:0xf
	v_fmac_f32_dpp v158, v150, v126 row_ror:1 row_mask:0xf bank_mask:0xf
	v_fmac_f32_dpp v159, v151, v127 row_ror:1 row_mask:0xf bank_mask:0xf
	v_fmac_f32_dpp v156, v152, v116 row_ror:15 row_mask:0xf bank_mask:0xf
	v_fmac_f32_dpp v157, v153, v117 row_ror:15 row_mask:0xf bank_mask:0xf
	v_fmac_f32_dpp v158, v154, v118 row_ror:15 row_mask:0xf bank_mask:0xf
	v_fmac_f32_dpp v159, v155, v119 row_ror:15 row_mask:0xf bank_mask:0xf
	v_cndmask_b32_e32 v148, v68, v84, vcc
	v_cndmask_b32_e32 v149, v69, v85, vcc
	v_cndmask_b32_e32 v150, v70, v86, vcc
	v_cndmask_b32_e32 v151, v71, v87, vcc
	v_cndmask_b32_e64 v152, v68, v60, s[98:99]
	v_cndmask_b32_e64 v153, v69, v61, s[98:99]
	v_cndmask_b32_e64 v154, v70, v62, s[98:99]
	v_cndmask_b32_e64 v155, v71, v63, s[98:99]
	v_fma_f32 v237, v100, v68, v80
	v_fma_f32 v238, v101, v69, v81
	v_fma_f32 v239, v102, v70, v82
	v_fma_f32 v240, v103, v71, v83
	v_fmac_f32_dpp v237, v148, v112 row_ror:1 row_mask:0xf bank_mask:0xf
	v_fmac_f32_dpp v238, v149, v113 row_ror:1 row_mask:0xf bank_mask:0xf
	v_fmac_f32_dpp v239, v150, v114 row_ror:1 row_mask:0xf bank_mask:0xf
	v_fmac_f32_dpp v240, v151, v115 row_ror:1 row_mask:0xf bank_mask:0xf
	v_fmac_f32_dpp v237, v152, v92 row_ror:15 row_mask:0xf bank_mask:0xf
	v_fmac_f32_dpp v238, v153, v93 row_ror:15 row_mask:0xf bank_mask:0xf
	v_fmac_f32_dpp v239, v154, v94 row_ror:15 row_mask:0xf bank_mask:0xf
	v_fmac_f32_dpp v240, v155, v95 row_ror:15 row_mask:0xf bank_mask:0xf
	v_mul_f32_e32 v148, 0xbfb8aa3b, v156
	v_mul_f32_e32 v149, 0xbfb8aa3b, v157
	v_mul_f32_e32 v150, 0xbfb8aa3b, v158
	v_mul_f32_e32 v151, 0xbfb8aa3b, v159
	v_exp_f32_e32 v148, v148
	v_exp_f32_e32 v149, v149
	v_exp_f32_e32 v150, v150
	v_exp_f32_e32 v151, v151
	v_add_f32_e32 v148, 1.0, v148
	v_add_f32_e32 v149, 1.0, v149
	v_add_f32_e32 v150, 1.0, v150
	v_add_f32_e32 v151, 1.0, v151
	v_rcp_f32_e32 v148, v148
	v_rcp_f32_e32 v149, v149
	v_rcp_f32_e32 v150, v150
	v_rcp_f32_e32 v151, v151
	v_mul_f32_e32 v156, v156, v148
	v_mul_f32_e32 v157, v157, v149
	v_mul_f32_e32 v158, v158, v150
	v_mul_f32_e32 v159, v159, v151
	v_mul_f32_e32 v156, v156, v237
	v_mul_f32_e32 v157, v157, v238
	v_mul_f32_e32 v158, v158, v239
	v_mul_f32_e32 v159, v159, v240
	v_cvt_pk_bf16_f32 v40, v156, v157
	v_cvt_pk_bf16_f32 v41, v158, v159
	v_bfi_b32 v18, v146, v243, v40
	v_bfi_b32 v19, v146, v244, v41
	ds_swizzle_b32 v16, v18 offset:0x401f
	ds_swizzle_b32 v17, v19 offset:0x401f
	v_add_u32_e32 v42, 0x16000, v250
	s_waitcnt lgkmcnt(0)
	v_bfi_b32 v148, v146, v16, v243
	v_bfi_b32 v149, v146, v17, v244
	v_bfi_b32 v150, v146, v40, v16
	v_bfi_b32 v151, v146, v41, v17
	global_store_dwordx4 v42, v[148:151], s[14:15] nt
	s_nop 1
	v_cndmask_b32_e32 v148, v88, v96, vcc
	v_cndmask_b32_e32 v149, v89, v97, vcc
	v_cndmask_b32_e32 v150, v90, v98, vcc
	v_cndmask_b32_e32 v151, v91, v99, vcc
	v_cndmask_b32_e64 v152, v88, v76, s[98:99]
	v_cndmask_b32_e64 v153, v89, v77, s[98:99]
	v_cndmask_b32_e64 v154, v90, v78, s[98:99]
	v_cndmask_b32_e64 v155, v91, v79, s[98:99]
	v_fma_f32 v156, v120, v88, v104
	v_fma_f32 v157, v121, v89, v105
	v_fma_f32 v158, v122, v90, v106
	v_fma_f32 v159, v123, v91, v107
	v_fmac_f32_dpp v156, v148, v124 row_ror:1 row_mask:0xf bank_mask:0xf
	v_fmac_f32_dpp v157, v149, v125 row_ror:1 row_mask:0xf bank_mask:0xf
	v_fmac_f32_dpp v158, v150, v126 row_ror:1 row_mask:0xf bank_mask:0xf
	v_fmac_f32_dpp v159, v151, v127 row_ror:1 row_mask:0xf bank_mask:0xf
	v_fmac_f32_dpp v156, v152, v116 row_ror:15 row_mask:0xf bank_mask:0xf
	v_fmac_f32_dpp v157, v153, v117 row_ror:15 row_mask:0xf bank_mask:0xf
	v_fmac_f32_dpp v158, v154, v118 row_ror:15 row_mask:0xf bank_mask:0xf
	v_fmac_f32_dpp v159, v155, v119 row_ror:15 row_mask:0xf bank_mask:0xf
	v_cndmask_b32_e32 v148, v60, v68, vcc
	v_cndmask_b32_e32 v149, v61, v69, vcc
	v_cndmask_b32_e32 v150, v62, v70, vcc
	v_cndmask_b32_e32 v151, v63, v71, vcc
	v_cndmask_b32_e64 v152, v60, v52, s[98:99]
	v_cndmask_b32_e64 v153, v61, v53, s[98:99]
	v_cndmask_b32_e64 v154, v62, v54, s[98:99]
	v_cndmask_b32_e64 v155, v63, v55, s[98:99]
	v_fma_f32 v237, v100, v60, v80
	v_fma_f32 v238, v101, v61, v81
	v_fma_f32 v239, v102, v62, v82
	v_fma_f32 v240, v103, v63, v83
	v_fmac_f32_dpp v237, v148, v112 row_ror:1 row_mask:0xf bank_mask:0xf
	v_fmac_f32_dpp v238, v149, v113 row_ror:1 row_mask:0xf bank_mask:0xf
	v_fmac_f32_dpp v239, v150, v114 row_ror:1 row_mask:0xf bank_mask:0xf
	v_fmac_f32_dpp v240, v151, v115 row_ror:1 row_mask:0xf bank_mask:0xf
	v_fmac_f32_dpp v237, v152, v92 row_ror:15 row_mask:0xf bank_mask:0xf
	v_fmac_f32_dpp v238, v153, v93 row_ror:15 row_mask:0xf bank_mask:0xf
	v_fmac_f32_dpp v239, v154, v94 row_ror:15 row_mask:0xf bank_mask:0xf
	v_fmac_f32_dpp v240, v155, v95 row_ror:15 row_mask:0xf bank_mask:0xf
	v_mul_f32_e32 v148, 0xbfb8aa3b, v156
	v_mul_f32_e32 v149, 0xbfb8aa3b, v157
	v_mul_f32_e32 v150, 0xbfb8aa3b, v158
	v_mul_f32_e32 v151, 0xbfb8aa3b, v159
	v_exp_f32_e32 v148, v148
	v_exp_f32_e32 v149, v149
	v_exp_f32_e32 v150, v150
	v_exp_f32_e32 v151, v151
	v_add_f32_e32 v148, 1.0, v148
	v_add_f32_e32 v149, 1.0, v149
	v_add_f32_e32 v150, 1.0, v150
	v_add_f32_e32 v151, 1.0, v151
	v_rcp_f32_e32 v148, v148
	v_rcp_f32_e32 v149, v149
	v_rcp_f32_e32 v150, v150
	v_rcp_f32_e32 v151, v151
	v_mul_f32_e32 v156, v156, v148
	v_mul_f32_e32 v157, v157, v149
	v_mul_f32_e32 v158, v158, v150
	v_mul_f32_e32 v159, v159, v151
	v_mul_f32_e32 v156, v156, v237
	v_mul_f32_e32 v157, v157, v238
	v_mul_f32_e32 v158, v158, v239
	v_mul_f32_e32 v159, v159, v240
	v_cvt_pk_bf16_f32 v40, v156, v157
	v_cvt_pk_bf16_f32 v41, v158, v159
	v_bfi_b32 v18, v146, v253, v40
	v_bfi_b32 v19, v146, v254, v41
	ds_swizzle_b32 v16, v18 offset:0x401f
	ds_swizzle_b32 v17, v19 offset:0x401f
	v_add_u32_e32 v42, 0x2c000, v250
	s_waitcnt lgkmcnt(0)
	v_bfi_b32 v148, v146, v16, v253
	v_bfi_b32 v149, v146, v17, v254
	v_bfi_b32 v150, v146, v40, v16
	v_bfi_b32 v151, v146, v41, v17
	global_store_dwordx4 v42, v[148:151], s[14:15] nt
	s_nop 1
	v_cndmask_b32_e32 v148, v76, v88, vcc
	v_cndmask_b32_e32 v149, v77, v89, vcc
	v_cndmask_b32_e32 v150, v78, v90, vcc
	v_cndmask_b32_e32 v151, v79, v91, vcc
	v_cndmask_b32_e64 v152, v76, v160, s[98:99]
	v_cndmask_b32_e64 v153, v77, v161, s[98:99]
	v_cndmask_b32_e64 v154, v78, v162, s[98:99]
	v_cndmask_b32_e64 v155, v79, v163, s[98:99]
	v_fma_f32 v156, v120, v76, v104
	v_fma_f32 v157, v121, v77, v105
	v_fma_f32 v158, v122, v78, v106
	v_fma_f32 v159, v123, v79, v107
	v_fmac_f32_dpp v156, v148, v124 row_ror:1 row_mask:0xf bank_mask:0xf
	v_fmac_f32_dpp v157, v149, v125 row_ror:1 row_mask:0xf bank_mask:0xf
	v_fmac_f32_dpp v158, v150, v126 row_ror:1 row_mask:0xf bank_mask:0xf
	v_fmac_f32_dpp v159, v151, v127 row_ror:1 row_mask:0xf bank_mask:0xf
	v_fmac_f32_dpp v156, v152, v116 row_ror:15 row_mask:0xf bank_mask:0xf
	v_fmac_f32_dpp v157, v153, v117 row_ror:15 row_mask:0xf bank_mask:0xf
	v_fmac_f32_dpp v158, v154, v118 row_ror:15 row_mask:0xf bank_mask:0xf
	v_fmac_f32_dpp v159, v155, v119 row_ror:15 row_mask:0xf bank_mask:0xf
	v_cndmask_b32_e32 v148, v52, v60, vcc
	v_cndmask_b32_e32 v149, v53, v61, vcc
	v_cndmask_b32_e32 v150, v54, v62, vcc
	v_cndmask_b32_e32 v151, v55, v63, vcc
	v_cndmask_b32_e64 v152, v52, v164, s[98:99]
	v_cndmask_b32_e64 v153, v53, v165, s[98:99]
	v_cndmask_b32_e64 v154, v54, v166, s[98:99]
	v_cndmask_b32_e64 v155, v55, v167, s[98:99]
	v_fma_f32 v237, v100, v52, v80
	v_fma_f32 v238, v101, v53, v81
	v_fma_f32 v239, v102, v54, v82
	v_fma_f32 v240, v103, v55, v83
	v_fmac_f32_dpp v237, v148, v112 row_ror:1 row_mask:0xf bank_mask:0xf
	v_fmac_f32_dpp v238, v149, v113 row_ror:1 row_mask:0xf bank_mask:0xf
	v_fmac_f32_dpp v239, v150, v114 row_ror:1 row_mask:0xf bank_mask:0xf
	v_fmac_f32_dpp v240, v151, v115 row_ror:1 row_mask:0xf bank_mask:0xf
	v_fmac_f32_dpp v237, v152, v92 row_ror:15 row_mask:0xf bank_mask:0xf
	v_fmac_f32_dpp v238, v153, v93 row_ror:15 row_mask:0xf bank_mask:0xf
	v_fmac_f32_dpp v239, v154, v94 row_ror:15 row_mask:0xf bank_mask:0xf
	v_fmac_f32_dpp v240, v155, v95 row_ror:15 row_mask:0xf bank_mask:0xf
	v_mul_f32_e32 v148, 0xbfb8aa3b, v156
	v_mul_f32_e32 v149, 0xbfb8aa3b, v157
	v_mul_f32_e32 v150, 0xbfb8aa3b, v158
	v_mul_f32_e32 v151, 0xbfb8aa3b, v159
	v_exp_f32_e32 v148, v148
	v_exp_f32_e32 v149, v149
	v_exp_f32_e32 v150, v150
	v_exp_f32_e32 v151, v151
	v_add_f32_e32 v148, 1.0, v148
	v_add_f32_e32 v149, 1.0, v149
	v_add_f32_e32 v150, 1.0, v150
	v_add_f32_e32 v151, 1.0, v151
	v_rcp_f32_e32 v148, v148
	v_rcp_f32_e32 v149, v149
	v_rcp_f32_e32 v150, v150
	v_rcp_f32_e32 v151, v151
	v_mul_f32_e32 v156, v156, v148
	v_mul_f32_e32 v157, v157, v149
	v_mul_f32_e32 v158, v158, v150
	v_mul_f32_e32 v159, v159, v151
	v_mul_f32_e32 v156, v156, v237
	v_mul_f32_e32 v157, v157, v238
	v_mul_f32_e32 v158, v158, v239
	v_mul_f32_e32 v159, v159, v240
	v_cvt_pk_bf16_f32 v40, v156, v157
	v_cvt_pk_bf16_f32 v41, v158, v159
	v_bfi_b32 v18, v146, v255, v40
	v_bfi_b32 v19, v146, v246, v41
	ds_swizzle_b32 v16, v18 offset:0x401f
	ds_swizzle_b32 v17, v19 offset:0x401f
	v_add_u32_e32 v42, 0x42000, v250
	s_waitcnt lgkmcnt(0)
	v_bfi_b32 v148, v146, v16, v255
	v_bfi_b32 v149, v146, v17, v246
	v_bfi_b32 v150, v146, v40, v16
	v_bfi_b32 v151, v146, v41, v17
	global_store_dwordx4 v42, v[148:151], s[14:15] nt
	s_nop 1
	ds_read_b128 v[160:163], v249 offset:7232
	ds_read_b128 v[164:167], v249 offset:7744
	s_waitcnt lgkmcnt(2)
	v_cndmask_b32_e32 v148, v44, v204, vcc
	v_cndmask_b32_e32 v149, v45, v205, vcc
	v_cndmask_b32_e32 v150, v46, v206, vcc
	v_cndmask_b32_e32 v151, v47, v207, vcc
	v_cndmask_b32_e64 v152, v44, v32, s[98:99]
	v_cndmask_b32_e64 v153, v45, v33, s[98:99]
	v_cndmask_b32_e64 v154, v46, v34, s[98:99]
	v_cndmask_b32_e64 v155, v47, v35, s[98:99]
	v_fma_f32 v156, v120, v44, v104
	v_fma_f32 v157, v121, v45, v105
	v_fma_f32 v158, v122, v46, v106
	v_fma_f32 v159, v123, v47, v107
	v_fmac_f32_dpp v156, v148, v124 row_ror:1 row_mask:0xf bank_mask:0xf
	v_fmac_f32_dpp v157, v149, v125 row_ror:1 row_mask:0xf bank_mask:0xf
	v_fmac_f32_dpp v158, v150, v126 row_ror:1 row_mask:0xf bank_mask:0xf
	v_fmac_f32_dpp v159, v151, v127 row_ror:1 row_mask:0xf bank_mask:0xf
	v_fmac_f32_dpp v156, v152, v116 row_ror:15 row_mask:0xf bank_mask:0xf
	v_fmac_f32_dpp v157, v153, v117 row_ror:15 row_mask:0xf bank_mask:0xf
	v_fmac_f32_dpp v158, v154, v118 row_ror:15 row_mask:0xf bank_mask:0xf
	v_fmac_f32_dpp v159, v155, v119 row_ror:15 row_mask:0xf bank_mask:0xf
	v_cndmask_b32_e32 v148, v20, v208, vcc
	v_cndmask_b32_e32 v149, v21, v209, vcc
	v_cndmask_b32_e32 v150, v22, v210, vcc
	v_cndmask_b32_e32 v151, v23, v211, vcc
	v_cndmask_b32_e64 v152, v20, v8, s[98:99]
	v_cndmask_b32_e64 v153, v21, v9, s[98:99]
	v_cndmask_b32_e64 v154, v22, v10, s[98:99]
	v_cndmask_b32_e64 v155, v23, v11, s[98:99]
	v_fma_f32 v237, v100, v20, v80
	v_fma_f32 v238, v101, v21, v81
	v_fma_f32 v239, v102, v22, v82
	v_fma_f32 v240, v103, v23, v83
	v_fmac_f32_dpp v237, v148, v112 row_ror:1 row_mask:0xf bank_mask:0xf
	v_fmac_f32_dpp v238, v149, v113 row_ror:1 row_mask:0xf bank_mask:0xf
	v_fmac_f32_dpp v239, v150, v114 row_ror:1 row_mask:0xf bank_mask:0xf
	v_fmac_f32_dpp v240, v151, v115 row_ror:1 row_mask:0xf bank_mask:0xf
	v_fmac_f32_dpp v237, v152, v92 row_ror:15 row_mask:0xf bank_mask:0xf
	v_fmac_f32_dpp v238, v153, v93 row_ror:15 row_mask:0xf bank_mask:0xf
	v_fmac_f32_dpp v239, v154, v94 row_ror:15 row_mask:0xf bank_mask:0xf
	v_fmac_f32_dpp v240, v155, v95 row_ror:15 row_mask:0xf bank_mask:0xf
	v_mul_f32_e32 v148, 0xbfb8aa3b, v156
	v_mul_f32_e32 v149, 0xbfb8aa3b, v157
	v_mul_f32_e32 v150, 0xbfb8aa3b, v158
	v_mul_f32_e32 v151, 0xbfb8aa3b, v159
	v_exp_f32_e32 v148, v148
	v_exp_f32_e32 v149, v149
	v_exp_f32_e32 v150, v150
	v_exp_f32_e32 v151, v151
	v_add_f32_e32 v148, 1.0, v148
	v_add_f32_e32 v149, 1.0, v149
	v_add_f32_e32 v150, 1.0, v150
	v_add_f32_e32 v151, 1.0, v151
	v_rcp_f32_e32 v148, v148
	v_rcp_f32_e32 v149, v149
	v_rcp_f32_e32 v150, v150
	v_rcp_f32_e32 v151, v151
	v_mul_f32_e32 v156, v156, v148
	v_mul_f32_e32 v157, v157, v149
	v_mul_f32_e32 v158, v158, v150
	v_mul_f32_e32 v159, v159, v151
	v_mul_f32_e32 v156, v156, v237
	v_mul_f32_e32 v157, v157, v238
	v_mul_f32_e32 v158, v158, v239
	v_mul_f32_e32 v159, v159, v240
	v_cvt_pk_bf16_f32 v40, v156, v157
	v_cvt_pk_bf16_f32 v41, v158, v159
	v_bfi_b32 v18, v146, v247, v40
	v_bfi_b32 v19, v146, v248, v41
	ds_swizzle_b32 v16, v18 offset:0x401f
	ds_swizzle_b32 v17, v19 offset:0x401f
	v_add_u32_e32 v42, 0xb0000, v250
	s_waitcnt lgkmcnt(0)
	v_bfi_b32 v148, v146, v16, v247
	v_bfi_b32 v149, v146, v17, v248
	v_bfi_b32 v150, v146, v40, v16
	v_bfi_b32 v151, v146, v41, v17
	global_store_dwordx4 v42, v[148:151], s[14:15] nt
	s_nop 1
	v_cndmask_b32_e32 v148, v32, v44, vcc
	v_cndmask_b32_e32 v149, v33, v45, vcc
	v_cndmask_b32_e32 v150, v34, v46, vcc
	v_cndmask_b32_e32 v151, v35, v47, vcc
	v_cndmask_b32_e64 v152, v32, v24, s[98:99]
	v_cndmask_b32_e64 v153, v33, v25, s[98:99]
	v_cndmask_b32_e64 v154, v34, v26, s[98:99]
	v_cndmask_b32_e64 v155, v35, v27, s[98:99]
	v_fma_f32 v156, v120, v32, v104
	v_fma_f32 v157, v121, v33, v105
	v_fma_f32 v158, v122, v34, v106
	v_fma_f32 v159, v123, v35, v107
	v_fmac_f32_dpp v156, v148, v124 row_ror:1 row_mask:0xf bank_mask:0xf
	v_fmac_f32_dpp v157, v149, v125 row_ror:1 row_mask:0xf bank_mask:0xf
	v_fmac_f32_dpp v158, v150, v126 row_ror:1 row_mask:0xf bank_mask:0xf
	v_fmac_f32_dpp v159, v151, v127 row_ror:1 row_mask:0xf bank_mask:0xf
	v_fmac_f32_dpp v156, v152, v116 row_ror:15 row_mask:0xf bank_mask:0xf
	v_fmac_f32_dpp v157, v153, v117 row_ror:15 row_mask:0xf bank_mask:0xf
	v_fmac_f32_dpp v158, v154, v118 row_ror:15 row_mask:0xf bank_mask:0xf
	v_fmac_f32_dpp v159, v155, v119 row_ror:15 row_mask:0xf bank_mask:0xf
	v_cndmask_b32_e32 v148, v8, v20, vcc
	v_cndmask_b32_e32 v149, v9, v21, vcc
	v_cndmask_b32_e32 v150, v10, v22, vcc
	v_cndmask_b32_e32 v151, v11, v23, vcc
	v_cndmask_b32_e64 v152, v8, v4, s[98:99]
	v_cndmask_b32_e64 v153, v9, v5, s[98:99]
	v_cndmask_b32_e64 v154, v10, v6, s[98:99]
	v_cndmask_b32_e64 v155, v11, v7, s[98:99]
	v_fma_f32 v237, v100, v8, v80
	v_fma_f32 v238, v101, v9, v81
	v_fma_f32 v239, v102, v10, v82
	v_fma_f32 v240, v103, v11, v83
	v_fmac_f32_dpp v237, v148, v112 row_ror:1 row_mask:0xf bank_mask:0xf
	v_fmac_f32_dpp v238, v149, v113 row_ror:1 row_mask:0xf bank_mask:0xf
	v_fmac_f32_dpp v239, v150, v114 row_ror:1 row_mask:0xf bank_mask:0xf
	v_fmac_f32_dpp v240, v151, v115 row_ror:1 row_mask:0xf bank_mask:0xf
	v_fmac_f32_dpp v237, v152, v92 row_ror:15 row_mask:0xf bank_mask:0xf
	v_fmac_f32_dpp v238, v153, v93 row_ror:15 row_mask:0xf bank_mask:0xf
	v_fmac_f32_dpp v239, v154, v94 row_ror:15 row_mask:0xf bank_mask:0xf
	v_fmac_f32_dpp v240, v155, v95 row_ror:15 row_mask:0xf bank_mask:0xf
	v_mul_f32_e32 v148, 0xbfb8aa3b, v156
	v_mul_f32_e32 v149, 0xbfb8aa3b, v157
	v_mul_f32_e32 v150, 0xbfb8aa3b, v158
	v_mul_f32_e32 v151, 0xbfb8aa3b, v159
	v_exp_f32_e32 v148, v148
	v_exp_f32_e32 v149, v149
	v_exp_f32_e32 v150, v150
	v_exp_f32_e32 v151, v151
	v_add_f32_e32 v148, 1.0, v148
	v_add_f32_e32 v149, 1.0, v149
	v_add_f32_e32 v150, 1.0, v150
	v_add_f32_e32 v151, 1.0, v151
	v_rcp_f32_e32 v148, v148
	v_rcp_f32_e32 v149, v149
	v_rcp_f32_e32 v150, v150
	v_rcp_f32_e32 v151, v151
	v_mul_f32_e32 v156, v156, v148
	v_mul_f32_e32 v157, v157, v149
	v_mul_f32_e32 v158, v158, v150
	v_mul_f32_e32 v159, v159, v151
	v_mul_f32_e32 v156, v156, v237
	v_mul_f32_e32 v157, v157, v238
	v_mul_f32_e32 v158, v158, v239
	v_mul_f32_e32 v159, v159, v240
	v_cvt_pk_bf16_f32 v40, v156, v157
	v_cvt_pk_bf16_f32 v41, v158, v159
	v_bfi_b32 v18, v146, v72, v40
	v_bfi_b32 v19, v146, v73, v41
	ds_swizzle_b32 v16, v18 offset:0x401f
	ds_swizzle_b32 v17, v19 offset:0x401f
	v_add_u32_e32 v42, 0xc6000, v250
	s_waitcnt lgkmcnt(0)
	v_bfi_b32 v148, v146, v16, v72
	v_bfi_b32 v149, v146, v17, v73
	v_bfi_b32 v150, v146, v40, v16
	v_bfi_b32 v151, v146, v41, v17
	global_store_dwordx4 v42, v[148:151], s[14:15] nt
	s_nop 1
	v_cndmask_b32_e32 v148, v24, v32, vcc
	v_cndmask_b32_e32 v149, v25, v33, vcc
	v_cndmask_b32_e32 v150, v26, v34, vcc
	v_cndmask_b32_e32 v151, v27, v35, vcc
	v_cndmask_b32_e64 v152, v24, v12, s[98:99]
	v_cndmask_b32_e64 v153, v25, v13, s[98:99]
	v_cndmask_b32_e64 v154, v26, v14, s[98:99]
	v_cndmask_b32_e64 v155, v27, v15, s[98:99]
	v_fma_f32 v156, v120, v24, v104
	v_fma_f32 v157, v121, v25, v105
	v_fma_f32 v158, v122, v26, v106
	v_fma_f32 v159, v123, v27, v107
	v_fmac_f32_dpp v156, v148, v124 row_ror:1 row_mask:0xf bank_mask:0xf
	v_fmac_f32_dpp v157, v149, v125 row_ror:1 row_mask:0xf bank_mask:0xf
	v_fmac_f32_dpp v158, v150, v126 row_ror:1 row_mask:0xf bank_mask:0xf
	v_fmac_f32_dpp v159, v151, v127 row_ror:1 row_mask:0xf bank_mask:0xf
	v_fmac_f32_dpp v156, v152, v116 row_ror:15 row_mask:0xf bank_mask:0xf
	v_fmac_f32_dpp v157, v153, v117 row_ror:15 row_mask:0xf bank_mask:0xf
	v_fmac_f32_dpp v158, v154, v118 row_ror:15 row_mask:0xf bank_mask:0xf
	v_fmac_f32_dpp v159, v155, v119 row_ror:15 row_mask:0xf bank_mask:0xf
	v_cndmask_b32_e32 v148, v4, v8, vcc
	v_cndmask_b32_e32 v149, v5, v9, vcc
	v_cndmask_b32_e32 v150, v6, v10, vcc
	v_cndmask_b32_e32 v151, v7, v11, vcc
	v_cndmask_b32_e64 v152, v4, v0, s[98:99]
	v_cndmask_b32_e64 v153, v5, v1, s[98:99]
	v_cndmask_b32_e64 v154, v6, v2, s[98:99]
	v_cndmask_b32_e64 v155, v7, v3, s[98:99]
	v_fma_f32 v237, v100, v4, v80
	v_fma_f32 v238, v101, v5, v81
	v_fma_f32 v239, v102, v6, v82
	v_fma_f32 v240, v103, v7, v83
	v_fmac_f32_dpp v237, v148, v112 row_ror:1 row_mask:0xf bank_mask:0xf
	v_fmac_f32_dpp v238, v149, v113 row_ror:1 row_mask:0xf bank_mask:0xf
	v_fmac_f32_dpp v239, v150, v114 row_ror:1 row_mask:0xf bank_mask:0xf
	v_fmac_f32_dpp v240, v151, v115 row_ror:1 row_mask:0xf bank_mask:0xf
	v_fmac_f32_dpp v237, v152, v92 row_ror:15 row_mask:0xf bank_mask:0xf
	v_fmac_f32_dpp v238, v153, v93 row_ror:15 row_mask:0xf bank_mask:0xf
	v_fmac_f32_dpp v239, v154, v94 row_ror:15 row_mask:0xf bank_mask:0xf
	v_fmac_f32_dpp v240, v155, v95 row_ror:15 row_mask:0xf bank_mask:0xf
	v_mul_f32_e32 v148, 0xbfb8aa3b, v156
	v_mul_f32_e32 v149, 0xbfb8aa3b, v157
	v_mul_f32_e32 v150, 0xbfb8aa3b, v158
	v_mul_f32_e32 v151, 0xbfb8aa3b, v159
	v_exp_f32_e32 v148, v148
	v_exp_f32_e32 v149, v149
	v_exp_f32_e32 v150, v150
	v_exp_f32_e32 v151, v151
	v_add_f32_e32 v148, 1.0, v148
	v_add_f32_e32 v149, 1.0, v149
	v_add_f32_e32 v150, 1.0, v150
	v_add_f32_e32 v151, 1.0, v151
	v_rcp_f32_e32 v148, v148
	v_rcp_f32_e32 v149, v149
	v_rcp_f32_e32 v150, v150
	v_rcp_f32_e32 v151, v151
	v_mul_f32_e32 v156, v156, v148
	v_mul_f32_e32 v157, v157, v149
	v_mul_f32_e32 v158, v158, v150
	v_mul_f32_e32 v159, v159, v151
	v_mul_f32_e32 v156, v156, v237
	v_mul_f32_e32 v157, v157, v238
	v_mul_f32_e32 v158, v158, v239
	v_mul_f32_e32 v159, v159, v240
	v_cvt_pk_bf16_f32 v40, v156, v157
	v_cvt_pk_bf16_f32 v41, v158, v159
	v_bfi_b32 v18, v146, v74, v40
	v_bfi_b32 v19, v146, v75, v41
	ds_swizzle_b32 v16, v18 offset:0x401f
	ds_swizzle_b32 v17, v19 offset:0x401f
	v_add_u32_e32 v42, 0xdc000, v250
	s_waitcnt lgkmcnt(0)
	v_bfi_b32 v148, v146, v16, v74
	v_bfi_b32 v149, v146, v17, v75
	v_bfi_b32 v150, v146, v40, v16
	v_bfi_b32 v151, v146, v41, v17
	global_store_dwordx4 v42, v[148:151], s[14:15] nt
	s_nop 1
	s_waitcnt lgkmcnt(0)
	v_cndmask_b32_e32 v148, v12, v24, vcc
	v_cndmask_b32_e32 v149, v13, v25, vcc
	v_cndmask_b32_e32 v150, v14, v26, vcc
	v_cndmask_b32_e32 v151, v15, v27, vcc
	v_cndmask_b32_e64 v152, v12, v160, s[98:99]
	v_cndmask_b32_e64 v153, v13, v161, s[98:99]
	v_cndmask_b32_e64 v154, v14, v162, s[98:99]
	v_cndmask_b32_e64 v155, v15, v163, s[98:99]
	v_fma_f32 v156, v120, v12, v104
	v_fma_f32 v157, v121, v13, v105
	v_fma_f32 v158, v122, v14, v106
	v_fma_f32 v159, v123, v15, v107
	v_fmac_f32_dpp v156, v148, v124 row_ror:1 row_mask:0xf bank_mask:0xf
	v_fmac_f32_dpp v157, v149, v125 row_ror:1 row_mask:0xf bank_mask:0xf
	v_fmac_f32_dpp v158, v150, v126 row_ror:1 row_mask:0xf bank_mask:0xf
	v_fmac_f32_dpp v159, v151, v127 row_ror:1 row_mask:0xf bank_mask:0xf
	v_fmac_f32_dpp v156, v152, v116 row_ror:15 row_mask:0xf bank_mask:0xf
	v_fmac_f32_dpp v157, v153, v117 row_ror:15 row_mask:0xf bank_mask:0xf
	v_fmac_f32_dpp v158, v154, v118 row_ror:15 row_mask:0xf bank_mask:0xf
	v_fmac_f32_dpp v159, v155, v119 row_ror:15 row_mask:0xf bank_mask:0xf
	v_cndmask_b32_e32 v148, v0, v4, vcc
	v_cndmask_b32_e32 v149, v1, v5, vcc
	v_cndmask_b32_e32 v150, v2, v6, vcc
	v_cndmask_b32_e32 v151, v3, v7, vcc
	v_cndmask_b32_e64 v152, v0, v164, s[98:99]
	v_cndmask_b32_e64 v153, v1, v165, s[98:99]
	v_cndmask_b32_e64 v154, v2, v166, s[98:99]
	v_cndmask_b32_e64 v155, v3, v167, s[98:99]
	v_fma_f32 v237, v100, v0, v80
	v_fma_f32 v238, v101, v1, v81
	v_fma_f32 v239, v102, v2, v82
	v_fma_f32 v240, v103, v3, v83
	v_fmac_f32_dpp v237, v148, v112 row_ror:1 row_mask:0xf bank_mask:0xf
	v_fmac_f32_dpp v238, v149, v113 row_ror:1 row_mask:0xf bank_mask:0xf
	v_fmac_f32_dpp v239, v150, v114 row_ror:1 row_mask:0xf bank_mask:0xf
	v_fmac_f32_dpp v240, v151, v115 row_ror:1 row_mask:0xf bank_mask:0xf
	v_fmac_f32_dpp v237, v152, v92 row_ror:15 row_mask:0xf bank_mask:0xf
	v_fmac_f32_dpp v238, v153, v93 row_ror:15 row_mask:0xf bank_mask:0xf
	v_fmac_f32_dpp v239, v154, v94 row_ror:15 row_mask:0xf bank_mask:0xf
	v_fmac_f32_dpp v240, v155, v95 row_ror:15 row_mask:0xf bank_mask:0xf
	v_mul_f32_e32 v148, 0xbfb8aa3b, v156
	v_mul_f32_e32 v149, 0xbfb8aa3b, v157
	v_mul_f32_e32 v150, 0xbfb8aa3b, v158
	v_mul_f32_e32 v151, 0xbfb8aa3b, v159
	v_exp_f32_e32 v148, v148
	v_exp_f32_e32 v149, v149
	v_exp_f32_e32 v150, v150
	v_exp_f32_e32 v151, v151
	v_add_f32_e32 v148, 1.0, v148
	v_add_f32_e32 v149, 1.0, v149
	v_add_f32_e32 v150, 1.0, v150
	v_add_f32_e32 v151, 1.0, v151
	v_rcp_f32_e32 v148, v148
	v_rcp_f32_e32 v149, v149
	v_rcp_f32_e32 v150, v150
	v_rcp_f32_e32 v151, v151
	v_mul_f32_e32 v156, v156, v148
	v_mul_f32_e32 v157, v157, v149
	v_mul_f32_e32 v158, v158, v150
	v_mul_f32_e32 v159, v159, v151
	v_mul_f32_e32 v156, v156, v237
	v_mul_f32_e32 v157, v157, v238
	v_mul_f32_e32 v158, v158, v239
	v_mul_f32_e32 v159, v159, v240
	v_cvt_pk_bf16_f32 v40, v156, v157
	v_cvt_pk_bf16_f32 v41, v158, v159
	v_bfi_b32 v18, v146, v48, v40
	v_bfi_b32 v19, v146, v49, v41
	ds_swizzle_b32 v16, v18 offset:0x401f
	ds_swizzle_b32 v17, v19 offset:0x401f
	v_add_u32_e32 v42, 0xf2000, v250
	v_lshrrev_b32_e32 v152, 6, v251
	s_nop 1
	v_readfirstlane_b32 s100, v152
	s_waitcnt lgkmcnt(0)
	v_bfi_b32 v148, v146, v16, v48
	v_bfi_b32 v149, v146, v17, v49
	v_bfi_b32 v150, v146, v40, v16
	v_bfi_b32 v151, v146, v41, v17
	s_cmp_eq_u32 s100, 1
	s_cselect_b64 s[100:101], vcc, 0
	s_andn2_b64 exec, exec, s[100:101]
	global_store_dwordx4 v42, v[148:151], s[14:15] nt
	s_mov_b64 exec, -1
	s_nop 1
	s_branch .LBB0_1215

.LBB0_1284:
	ds_read_b128 v[148:151], v145
	ds_read_b128 v[152:155], v145 offset:1024
	ds_read_b128 v[156:159], v145 offset:2048
	ds_read_b128 v[160:163], v145 offset:3072
	s_add_u32 s14, s12, 0x100
	s_addc_u32 s15, s13, 0
	s_cmp_eq_u32 s44, 40
	s_cselect_b32 s19, s9, s15
	s_cselect_b32 s18, s8, s14
	s_cselect_b32 s17, s1, s43
	s_cselect_b32 s16, s0, s42
	s_mov_b32 m0, s35
	v_lshl_add_u64 v[168:169], s[12:13], 0, v[136:137]
	ds_read_b128 v[164:167], v146
	ds_read_b128 v[172:175], v146 offset:1024
	ds_read_b128 v[176:179], v146 offset:2048
	ds_read_b128 v[180:183], v146 offset:3072
	ds_read_b128 v[184:187], v146 offset:4096
	ds_read_b128 v[188:191], v146 offset:5120
	ds_read_b128 v[192:195], v146 offset:6144
	ds_read_b128 v[196:199], v146 offset:7168
	global_load_lds_dwordx4 v[168:169], off
	v_lshl_add_u64 v[168:169], s[12:13], 0, v[134:135]
	s_mov_b32 m0, s36
	s_nop 0
	global_load_lds_dwordx4 v[168:169], off
	s_waitcnt lgkmcnt(8)
	s_barrier
	s_waitcnt lgkmcnt(0)
	s_setprio 1
	s_waitcnt lgkmcnt(0)
	v_mfma_f32_16x16x32_bf16 v[124:127], v[148:151], v[164:167], v[124:127]
	v_mfma_f32_16x16x32_bf16 v[120:123], v[156:159], v[164:167], v[120:123]
	v_mfma_f32_16x16x32_bf16 v[116:119], v[148:151], v[176:179], v[116:119]
	v_mfma_f32_16x16x32_bf16 v[108:111], v[156:159], v[176:179], v[108:111]
	v_mfma_f32_16x16x32_bf16 v[100:103], v[148:151], v[184:187], v[100:103]
	v_mfma_f32_16x16x32_bf16 v[92:95], v[156:159], v[184:187], v[92:95]
	v_mfma_f32_16x16x32_bf16 v[84:87], v[148:151], v[192:195], v[84:87]
	v_mfma_f32_16x16x32_bf16 v[76:79], v[156:159], v[192:195], v[76:79]
	v_mfma_f32_16x16x32_bf16 v[124:127], v[152:155], v[172:175], v[124:127]
	v_mfma_f32_16x16x32_bf16 v[120:123], v[160:163], v[172:175], v[120:123]
	v_mfma_f32_16x16x32_bf16 v[116:119], v[152:155], v[180:183], v[116:119]
	v_mfma_f32_16x16x32_bf16 v[108:111], v[160:163], v[180:183], v[108:111]
	v_mfma_f32_16x16x32_bf16 v[100:103], v[152:155], v[188:191], v[100:103]
	v_mfma_f32_16x16x32_bf16 v[92:95], v[160:163], v[188:191], v[92:95]
	v_mfma_f32_16x16x32_bf16 v[84:87], v[152:155], v[196:199], v[84:87]
	v_mfma_f32_16x16x32_bf16 v[76:79], v[160:163], v[196:199], v[76:79]
	s_setprio 0
	s_barrier
	s_add_i32 s12, s33, s25
	v_lshl_add_u64 v[168:169], s[16:17], 0, v[130:131]
	s_mov_b32 m0, s12
	ds_read_b128 v[200:203], v147
	ds_read_b128 v[204:207], v147 offset:1024
	ds_read_b128 v[208:211], v147 offset:2048
	ds_read_b128 v[212:215], v147 offset:3072
	global_load_lds_dwordx4 v[168:169], off
	v_lshl_add_u64 v[216:217], s[16:17], 0, v[128:129]
	s_add_i32 m0, s12, 0x2000
	s_nop 0
	global_load_lds_dwordx4 v[216:217], off
	s_barrier
	s_waitcnt lgkmcnt(0)
	s_setprio 1
	s_waitcnt lgkmcnt(0)
	v_mfma_f32_16x16x32_bf16 v[112:115], v[200:203], v[164:167], v[112:115]
	v_mfma_f32_16x16x32_bf16 v[104:107], v[208:211], v[164:167], v[104:107]
	v_mfma_f32_16x16x32_bf16 v[96:99], v[200:203], v[176:179], v[96:99]
	v_mfma_f32_16x16x32_bf16 v[88:91], v[208:211], v[176:179], v[88:91]
	v_mfma_f32_16x16x32_bf16 v[80:83], v[200:203], v[184:187], v[80:83]
	v_mfma_f32_16x16x32_bf16 v[72:75], v[208:211], v[184:187], v[72:75]
	v_mfma_f32_16x16x32_bf16 v[68:71], v[200:203], v[192:195], v[68:71]
	v_mfma_f32_16x16x32_bf16 v[64:67], v[208:211], v[192:195], v[64:67]
	v_mfma_f32_16x16x32_bf16 v[112:115], v[204:207], v[172:175], v[112:115]
	v_mfma_f32_16x16x32_bf16 v[104:107], v[212:215], v[172:175], v[104:107]
	v_mfma_f32_16x16x32_bf16 v[96:99], v[204:207], v[180:183], v[96:99]
	v_mfma_f32_16x16x32_bf16 v[88:91], v[212:215], v[180:183], v[88:91]
	v_mfma_f32_16x16x32_bf16 v[80:83], v[204:207], v[188:191], v[80:83]
	v_mfma_f32_16x16x32_bf16 v[72:75], v[212:215], v[188:191], v[72:75]
	v_mfma_f32_16x16x32_bf16 v[68:71], v[204:207], v[196:199], v[68:71]
	v_mfma_f32_16x16x32_bf16 v[64:67], v[212:215], v[196:199], v[64:67]
	s_setprio 0
	s_mov_b32 m0, s26
	v_lshl_add_u64 v[218:219], s[18:19], 0, v[130:131]
	s_barrier
	ds_read_b128 v[164:167], v146 offset:16384
	ds_read_b128 v[172:175], v146 offset:17408
	ds_read_b128 v[176:179], v146 offset:18432
	ds_read_b128 v[180:183], v146 offset:19456
	ds_read_b128 v[184:187], v146 offset:20480
	ds_read_b128 v[188:191], v146 offset:21504
	ds_read_b128 v[192:195], v146 offset:22528
	ds_read_b128 v[196:199], v146 offset:23552
	global_load_lds_dwordx4 v[218:219], off
	v_lshl_add_u64 v[220:221], s[18:19], 0, v[128:129]
	s_mov_b32 m0, s27
	s_nop 0
	global_load_lds_dwordx4 v[220:221], off
	s_barrier
	s_waitcnt lgkmcnt(0)
	s_setprio 1
	s_waitcnt lgkmcnt(0)
	v_mfma_f32_16x16x32_bf16 v[60:63], v[148:151], v[164:167], v[60:63]
	v_mfma_f32_16x16x32_bf16 v[56:59], v[156:159], v[164:167], v[56:59]
	v_mfma_f32_16x16x32_bf16 v[52:55], v[148:151], v[176:179], v[52:55]
	v_mfma_f32_16x16x32_bf16 v[44:47], v[156:159], v[176:179], v[44:47]
	v_mfma_f32_16x16x32_bf16 v[36:39], v[148:151], v[184:187], v[36:39]
	v_mfma_f32_16x16x32_bf16 v[28:31], v[156:159], v[184:187], v[28:31]
	v_mfma_f32_16x16x32_bf16 v[20:23], v[148:151], v[192:195], v[20:23]
	v_mfma_f32_16x16x32_bf16 v[12:15], v[156:159], v[192:195], v[12:15]
	v_mfma_f32_16x16x32_bf16 v[60:63], v[152:155], v[172:175], v[60:63]
	v_mfma_f32_16x16x32_bf16 v[56:59], v[160:163], v[172:175], v[56:59]
	v_mfma_f32_16x16x32_bf16 v[52:55], v[152:155], v[180:183], v[52:55]
	v_mfma_f32_16x16x32_bf16 v[44:47], v[160:163], v[180:183], v[44:47]
	v_mfma_f32_16x16x32_bf16 v[36:39], v[152:155], v[188:191], v[36:39]
	v_mfma_f32_16x16x32_bf16 v[28:31], v[160:163], v[188:191], v[28:31]
	v_mfma_f32_16x16x32_bf16 v[20:23], v[152:155], v[196:199], v[20:23]
	v_mfma_f32_16x16x32_bf16 v[12:15], v[160:163], v[196:199], v[12:15]
	s_setprio 0
	s_barrier
	s_add_u32 s12, s16, 0xb0000
	s_addc_u32 s13, s17, 0
	s_add_i32 s45, s34, s25
	v_lshl_add_u64 v[148:149], s[12:13], 0, v[130:131]
	s_mov_b32 m0, s45
	s_nop 0
	global_load_lds_dwordx4 v[148:149], off
	v_lshl_add_u64 v[148:149], s[12:13], 0, v[128:129]
	s_add_i32 m0, s45, 0x2000
	s_nop 0
	global_load_lds_dwordx4 v[148:149], off
	s_waitcnt vmcnt(6)
	s_barrier
	s_setprio 1
	v_mfma_f32_16x16x32_bf16 v[48:51], v[200:203], v[164:167], v[48:51]
	v_mfma_f32_16x16x32_bf16 v[40:43], v[208:211], v[164:167], v[40:43]
	v_mfma_f32_16x16x32_bf16 v[32:35], v[200:203], v[176:179], v[32:35]
	v_mfma_f32_16x16x32_bf16 v[24:27], v[208:211], v[176:179], v[24:27]
	v_mfma_f32_16x16x32_bf16 v[16:19], v[200:203], v[184:187], v[16:19]
	v_mfma_f32_16x16x32_bf16 v[8:11], v[208:211], v[184:187], v[8:11]
	v_mfma_f32_16x16x32_bf16 v[4:7], v[200:203], v[192:195], v[4:7]
	v_mfma_f32_16x16x32_bf16 v[0:3], v[208:211], v[192:195], v[0:3]
	v_mfma_f32_16x16x32_bf16 v[48:51], v[204:207], v[172:175], v[48:51]
	v_mfma_f32_16x16x32_bf16 v[40:43], v[212:215], v[172:175], v[40:43]
	v_mfma_f32_16x16x32_bf16 v[32:35], v[204:207], v[180:183], v[32:35]
	v_mfma_f32_16x16x32_bf16 v[24:27], v[212:215], v[180:183], v[24:27]
	v_mfma_f32_16x16x32_bf16 v[16:19], v[204:207], v[188:191], v[16:19]
	v_mfma_f32_16x16x32_bf16 v[8:11], v[212:215], v[188:191], v[8:11]
	v_mfma_f32_16x16x32_bf16 v[4:7], v[204:207], v[196:199], v[4:7]
	v_mfma_f32_16x16x32_bf16 v[0:3], v[212:215], v[196:199], v[0:3]
	s_setprio 0
	s_add_i32 s45, 0, 0x18000
	v_add_u32_e32 v160, s45, v144
	s_barrier
	ds_read_b128 v[148:151], v160
	ds_read_b128 v[152:155], v160 offset:1024
	ds_read_b128 v[156:159], v160 offset:2048
	ds_read_b128 v[160:163], v160 offset:3072
	s_add_u32 s12, s18, 0xb0000
	s_addc_u32 s13, s19, 0
	s_mov_b32 m0, s28
	v_lshl_add_u64 v[200:201], s[12:13], 0, v[130:131]
	ds_read_b128 v[164:167], v146 offset:32768
	ds_read_b128 v[172:175], v146 offset:33792
	ds_read_b128 v[176:179], v146 offset:34816
	ds_read_b128 v[180:183], v146 offset:35840
	ds_read_b128 v[184:187], v146 offset:36864
	ds_read_b128 v[188:191], v146 offset:37888
	ds_read_b128 v[192:195], v146 offset:38912
	ds_read_b128 v[196:199], v146 offset:39936
	global_load_lds_dwordx4 v[200:201], off
	v_lshl_add_u64 v[200:201], s[12:13], 0, v[128:129]
	s_mov_b32 m0, s29
	s_nop 0
	global_load_lds_dwordx4 v[200:201], off
	s_waitcnt lgkmcnt(8)
	s_barrier
	s_waitcnt lgkmcnt(0)
	s_setprio 1
	s_waitcnt lgkmcnt(0)
	v_mfma_f32_16x16x32_bf16 v[124:127], v[148:151], v[164:167], v[124:127]
	v_mfma_f32_16x16x32_bf16 v[120:123], v[156:159], v[164:167], v[120:123]
	v_mfma_f32_16x16x32_bf16 v[116:119], v[148:151], v[176:179], v[116:119]
	v_mfma_f32_16x16x32_bf16 v[108:111], v[156:159], v[176:179], v[108:111]
	v_mfma_f32_16x16x32_bf16 v[100:103], v[148:151], v[184:187], v[100:103]
	v_mfma_f32_16x16x32_bf16 v[92:95], v[156:159], v[184:187], v[92:95]
	v_mfma_f32_16x16x32_bf16 v[84:87], v[148:151], v[192:195], v[84:87]
	v_mfma_f32_16x16x32_bf16 v[76:79], v[156:159], v[192:195], v[76:79]
	v_mfma_f32_16x16x32_bf16 v[124:127], v[152:155], v[172:175], v[124:127]
	v_mfma_f32_16x16x32_bf16 v[120:123], v[160:163], v[172:175], v[120:123]
	v_mfma_f32_16x16x32_bf16 v[116:119], v[152:155], v[180:183], v[116:119]
	v_mfma_f32_16x16x32_bf16 v[108:111], v[160:163], v[180:183], v[108:111]
	v_mfma_f32_16x16x32_bf16 v[100:103], v[152:155], v[188:191], v[100:103]
	v_mfma_f32_16x16x32_bf16 v[92:95], v[160:163], v[188:191], v[92:95]
	v_mfma_f32_16x16x32_bf16 v[84:87], v[152:155], v[196:199], v[84:87]
	v_mfma_f32_16x16x32_bf16 v[76:79], v[160:163], v[196:199], v[76:79]
	s_setprio 0
	s_barrier
	s_add_i32 s18, 0, 0x1c000
	s_add_i32 s12, s45, s25
	v_add_u32_e32 v171, s18, v144
	v_lshl_add_u64 v[168:169], v[168:169], 0, s[10:11]
	s_mov_b32 m0, s12
	ds_read_b128 v[200:203], v171
	ds_read_b128 v[204:207], v171 offset:1024
	ds_read_b128 v[208:211], v171 offset:2048
	ds_read_b128 v[212:215], v171 offset:3072
	global_load_lds_dwordx4 v[168:169], off
	v_lshl_add_u64 v[168:169], v[216:217], 0, s[10:11]
	s_add_i32 m0, s12, 0x2000
	s_nop 0
	global_load_lds_dwordx4 v[168:169], off
	s_barrier
	s_waitcnt lgkmcnt(0)
	s_setprio 1
	s_waitcnt lgkmcnt(0)
	v_mfma_f32_16x16x32_bf16 v[112:115], v[200:203], v[164:167], v[112:115]
	v_mfma_f32_16x16x32_bf16 v[104:107], v[208:211], v[164:167], v[104:107]
	v_mfma_f32_16x16x32_bf16 v[96:99], v[200:203], v[176:179], v[96:99]
	v_mfma_f32_16x16x32_bf16 v[88:91], v[208:211], v[176:179], v[88:91]
	v_mfma_f32_16x16x32_bf16 v[80:83], v[200:203], v[184:187], v[80:83]
	v_mfma_f32_16x16x32_bf16 v[72:75], v[208:211], v[184:187], v[72:75]
	v_mfma_f32_16x16x32_bf16 v[68:71], v[200:203], v[192:195], v[68:71]
	v_mfma_f32_16x16x32_bf16 v[64:67], v[208:211], v[192:195], v[64:67]
	v_mfma_f32_16x16x32_bf16 v[112:115], v[204:207], v[172:175], v[112:115]
	v_mfma_f32_16x16x32_bf16 v[104:107], v[212:215], v[172:175], v[104:107]
	v_mfma_f32_16x16x32_bf16 v[96:99], v[204:207], v[180:183], v[96:99]
	v_mfma_f32_16x16x32_bf16 v[88:91], v[212:215], v[180:183], v[88:91]
	v_mfma_f32_16x16x32_bf16 v[80:83], v[204:207], v[188:191], v[80:83]
	v_mfma_f32_16x16x32_bf16 v[72:75], v[212:215], v[188:191], v[72:75]
	v_mfma_f32_16x16x32_bf16 v[68:71], v[204:207], v[196:199], v[68:71]
	v_mfma_f32_16x16x32_bf16 v[64:67], v[212:215], v[196:199], v[64:67]
	s_setprio 0
	s_mov_b32 m0, s30
	v_lshl_add_u64 v[168:169], v[218:219], 0, s[10:11]
	s_barrier
	ds_read_b128 v[164:167], v146 offset:49152
	ds_read_b128 v[172:175], v146 offset:50176
	ds_read_b128 v[176:179], v146 offset:51200
	ds_read_b128 v[180:183], v146 offset:52224
	ds_read_b128 v[184:187], v146 offset:53248
	ds_read_b128 v[188:191], v146 offset:54272
	ds_read_b128 v[192:195], v146 offset:55296
	ds_read_b128 v[196:199], v146 offset:56320
	global_load_lds_dwordx4 v[168:169], off
	v_lshl_add_u64 v[168:169], v[220:221], 0, s[10:11]
	s_mov_b32 m0, s31
	s_nop 0
	global_load_lds_dwordx4 v[168:169], off
	s_barrier
	s_waitcnt lgkmcnt(0)
	s_setprio 1
	s_waitcnt lgkmcnt(0)
	v_mfma_f32_16x16x32_bf16 v[60:63], v[148:151], v[164:167], v[60:63]
	v_mfma_f32_16x16x32_bf16 v[56:59], v[156:159], v[164:167], v[56:59]
	v_mfma_f32_16x16x32_bf16 v[52:55], v[148:151], v[176:179], v[52:55]
	v_mfma_f32_16x16x32_bf16 v[44:47], v[156:159], v[176:179], v[44:47]
	v_mfma_f32_16x16x32_bf16 v[36:39], v[148:151], v[184:187], v[36:39]
	v_mfma_f32_16x16x32_bf16 v[28:31], v[156:159], v[184:187], v[28:31]
	v_mfma_f32_16x16x32_bf16 v[20:23], v[148:151], v[192:195], v[20:23]
	v_mfma_f32_16x16x32_bf16 v[12:15], v[156:159], v[192:195], v[12:15]
	v_mfma_f32_16x16x32_bf16 v[60:63], v[152:155], v[172:175], v[60:63]
	v_mfma_f32_16x16x32_bf16 v[56:59], v[160:163], v[172:175], v[56:59]
	v_mfma_f32_16x16x32_bf16 v[52:55], v[152:155], v[180:183], v[52:55]
	v_mfma_f32_16x16x32_bf16 v[44:47], v[160:163], v[180:183], v[44:47]
	v_mfma_f32_16x16x32_bf16 v[36:39], v[152:155], v[188:191], v[36:39]
	v_mfma_f32_16x16x32_bf16 v[28:31], v[160:163], v[188:191], v[28:31]
	v_mfma_f32_16x16x32_bf16 v[20:23], v[152:155], v[196:199], v[20:23]
	v_mfma_f32_16x16x32_bf16 v[12:15], v[160:163], v[196:199], v[12:15]
	s_setprio 0
	s_barrier
	s_add_u32 s12, s16, 0xb0080
	s_addc_u32 s13, s17, 0
	s_add_i32 s16, s18, s25
	v_lshl_add_u64 v[148:149], s[12:13], 0, v[130:131]
	s_mov_b32 m0, s16
	s_nop 0
	global_load_lds_dwordx4 v[148:149], off
	v_lshl_add_u64 v[148:149], s[12:13], 0, v[128:129]
	s_add_i32 m0, s16, 0x2000
	s_nop 0
	global_load_lds_dwordx4 v[148:149], off
	s_waitcnt vmcnt(6)
	s_barrier
	s_setprio 1
	v_mfma_f32_16x16x32_bf16 v[48:51], v[200:203], v[164:167], v[48:51]
	v_mfma_f32_16x16x32_bf16 v[40:43], v[208:211], v[164:167], v[40:43]
	v_mfma_f32_16x16x32_bf16 v[32:35], v[200:203], v[176:179], v[32:35]
	v_mfma_f32_16x16x32_bf16 v[24:27], v[208:211], v[176:179], v[24:27]
	v_mfma_f32_16x16x32_bf16 v[16:19], v[200:203], v[184:187], v[16:19]
	v_mfma_f32_16x16x32_bf16 v[8:11], v[208:211], v[184:187], v[8:11]
	v_mfma_f32_16x16x32_bf16 v[4:7], v[200:203], v[192:195], v[4:7]
	v_mfma_f32_16x16x32_bf16 v[0:3], v[208:211], v[192:195], v[0:3]
	v_mfma_f32_16x16x32_bf16 v[48:51], v[204:207], v[172:175], v[48:51]
	v_mfma_f32_16x16x32_bf16 v[40:43], v[212:215], v[172:175], v[40:43]
	v_mfma_f32_16x16x32_bf16 v[32:35], v[204:207], v[180:183], v[32:35]
	v_mfma_f32_16x16x32_bf16 v[24:27], v[212:215], v[180:183], v[24:27]
	v_mfma_f32_16x16x32_bf16 v[16:19], v[204:207], v[188:191], v[16:19]
	v_mfma_f32_16x16x32_bf16 v[8:11], v[212:215], v[188:191], v[8:11]
	v_mfma_f32_16x16x32_bf16 v[4:7], v[204:207], v[196:199], v[4:7]
	v_mfma_f32_16x16x32_bf16 v[0:3], v[212:215], v[196:199], v[0:3]
	s_setprio 0
	s_add_i32 s44, s44, 2
	s_add_u32 s42, s42, 0x100
	s_addc_u32 s43, s43, 0
	s_cmp_gt_u32 s44, 41
	s_mov_b64 s[12:13], s[14:15]
	s_barrier
	s_cbranch_scc0 .LBB0_1284
	v_lshl_add_u32 v148, s41, 8, v143
	s_lshl_b32 s12, s40, 8
	v_ashrrev_i32_e32 v149, 31, v148
	s_ashr_i32 s13, s12, 31
	v_lshlrev_b64 v[150:151], 11, v[148:149]
	v_lshl_add_u64 v[150:151], s[4:5], 0, v[150:151]
	s_lshl_b64 s[12:13], s[12:13], 1
	v_lshl_add_u64 v[150:151], v[150:151], 0, s[12:13]
	v_lshl_add_u64 v[150:151], v[150:151], 0, s[2:3]
	v_lshl_add_u64 v[150:151], v[150:151], 0, v[132:133]
	v_mbcnt_lo_u32_b32 v237, -1, 0
	v_mbcnt_hi_u32_b32 v237, -1, v237
	v_bfe_i32 v237, v237, 4, 1
	v_and_b32_e32 v244, 24, v237
	v_add_co_u32_e32 v248, vcc, v244, v150
	s_nop 1
	v_addc_co_u32_e32 v249, vcc, 0, v151, vcc
	v_cvt_pk_bf16_f32 v124, v124, v125
	v_cvt_pk_bf16_f32 v125, v126, v127
	v_cvt_pk_bf16_f32 v120, v120, v121
	v_cvt_pk_bf16_f32 v121, v122, v123
	v_bfi_b32 v244, v237, v124, v120
	v_bfi_b32 v245, v237, v125, v121
	ds_swizzle_b32 v250, v244 offset:0x401f
	ds_swizzle_b32 v251, v245 offset:0x401f
	v_cvt_pk_bf16_f32 v112, v112, v113
	v_cvt_pk_bf16_f32 v113, v114, v115
	v_cvt_pk_bf16_f32 v104, v104, v105
	v_cvt_pk_bf16_f32 v105, v106, v107
	v_bfi_b32 v246, v237, v112, v104
	v_bfi_b32 v247, v237, v113, v105
	ds_swizzle_b32 v252, v246 offset:0x401f
	ds_swizzle_b32 v253, v247 offset:0x401f
	s_waitcnt lgkmcnt(0)
	v_bfi_b32 v240, v237, v250, v124
	v_bfi_b32 v241, v237, v251, v125
	v_bfi_b32 v242, v237, v120, v250
	v_bfi_b32 v243, v237, v121, v251
	global_store_dwordx4 v[248:249], v[240:243], off nt
	s_nop 1
	v_bfi_b32 v240, v237, v252, v112
	v_bfi_b32 v241, v237, v253, v113
	v_bfi_b32 v242, v237, v104, v252
	v_bfi_b32 v243, v237, v105, v253
	global_store_dwordx4 v[248:249], v[240:243], off offset:256 nt
	s_nop 1
	v_add_co_u32_e32 v238, vcc, 0x8000, v248
	s_nop 1
	v_addc_co_u32_e32 v239, vcc, 0, v249, vcc
	v_cvt_pk_bf16_f32 v116, v116, v117
	v_cvt_pk_bf16_f32 v117, v118, v119
	v_cvt_pk_bf16_f32 v108, v108, v109
	v_cvt_pk_bf16_f32 v109, v110, v111
	v_bfi_b32 v244, v237, v116, v108
	v_bfi_b32 v245, v237, v117, v109
	ds_swizzle_b32 v250, v244 offset:0x401f
	ds_swizzle_b32 v251, v245 offset:0x401f
	v_cvt_pk_bf16_f32 v96, v96, v97
	v_cvt_pk_bf16_f32 v97, v98, v99
	v_cvt_pk_bf16_f32 v88, v88, v89
	v_cvt_pk_bf16_f32 v89, v90, v91
	v_bfi_b32 v246, v237, v96, v88
	v_bfi_b32 v247, v237, v97, v89
	ds_swizzle_b32 v252, v246 offset:0x401f
	ds_swizzle_b32 v253, v247 offset:0x401f
	s_waitcnt lgkmcnt(0)
	v_bfi_b32 v240, v237, v250, v116
	v_bfi_b32 v241, v237, v251, v117
	v_bfi_b32 v242, v237, v108, v250
	v_bfi_b32 v243, v237, v109, v251
	global_store_dwordx4 v[238:239], v[240:243], off nt
	s_nop 1
	v_bfi_b32 v240, v237, v252, v96
	v_bfi_b32 v241, v237, v253, v97
	v_bfi_b32 v242, v237, v88, v252
	v_bfi_b32 v243, v237, v89, v253
	global_store_dwordx4 v[238:239], v[240:243], off offset:256 nt
	s_nop 1
	v_add_co_u32_e32 v238, vcc, 0x10000, v248
	s_nop 1
	v_addc_co_u32_e32 v239, vcc, 0, v249, vcc
	v_cvt_pk_bf16_f32 v100, v100, v101
	v_cvt_pk_bf16_f32 v101, v102, v103
	v_cvt_pk_bf16_f32 v92, v92, v93
	v_cvt_pk_bf16_f32 v93, v94, v95
	v_bfi_b32 v244, v237, v100, v92
	v_bfi_b32 v245, v237, v101, v93
	ds_swizzle_b32 v250, v244 offset:0x401f
	ds_swizzle_b32 v251, v245 offset:0x401f
	v_cvt_pk_bf16_f32 v80, v80, v81
	v_cvt_pk_bf16_f32 v81, v82, v83
	v_cvt_pk_bf16_f32 v72, v72, v73
	v_cvt_pk_bf16_f32 v73, v74, v75
	v_bfi_b32 v246, v237, v80, v72
	v_bfi_b32 v247, v237, v81, v73
	ds_swizzle_b32 v252, v246 offset:0x401f
	ds_swizzle_b32 v253, v247 offset:0x401f
	s_waitcnt lgkmcnt(0)
	v_bfi_b32 v240, v237, v250, v100
	v_bfi_b32 v241, v237, v251, v101
	v_bfi_b32 v242, v237, v92, v250
	v_bfi_b32 v243, v237, v93, v251
	global_store_dwordx4 v[238:239], v[240:243], off nt
	s_nop 1
	v_bfi_b32 v240, v237, v252, v80
	v_bfi_b32 v241, v237, v253, v81
	v_bfi_b32 v242, v237, v72, v252
	v_bfi_b32 v243, v237, v73, v253
	global_store_dwordx4 v[238:239], v[240:243], off offset:256 nt
	s_nop 1
	v_add_co_u32_e32 v238, vcc, 0x18000, v248
	s_nop 1
	v_addc_co_u32_e32 v239, vcc, 0, v249, vcc
	v_cvt_pk_bf16_f32 v84, v84, v85
	v_cvt_pk_bf16_f32 v85, v86, v87
	v_cvt_pk_bf16_f32 v76, v76, v77
	v_cvt_pk_bf16_f32 v77, v78, v79
	v_bfi_b32 v244, v237, v84, v76
	v_bfi_b32 v245, v237, v85, v77
	ds_swizzle_b32 v250, v244 offset:0x401f
	ds_swizzle_b32 v251, v245 offset:0x401f
	v_cvt_pk_bf16_f32 v68, v68, v69
	v_cvt_pk_bf16_f32 v69, v70, v71
	v_cvt_pk_bf16_f32 v64, v64, v65
	v_cvt_pk_bf16_f32 v65, v66, v67
	v_bfi_b32 v246, v237, v68, v64
	v_bfi_b32 v247, v237, v69, v65
	ds_swizzle_b32 v252, v246 offset:0x401f
	ds_swizzle_b32 v253, v247 offset:0x401f
	s_waitcnt lgkmcnt(0)
	v_bfi_b32 v240, v237, v250, v84
	v_bfi_b32 v241, v237, v251, v85
	v_bfi_b32 v242, v237, v76, v250
	v_bfi_b32 v243, v237, v77, v251
	global_store_dwordx4 v[238:239], v[240:243], off nt
	s_nop 1
	v_bfi_b32 v240, v237, v252, v68
	v_bfi_b32 v241, v237, v253, v69
	v_bfi_b32 v242, v237, v64, v252
	v_bfi_b32 v243, v237, v65, v253
	global_store_dwordx4 v[238:239], v[240:243], off offset:256 nt
	s_nop 1
	v_add_co_u32_e32 v238, vcc, 0x40000, v248
	s_nop 1
	v_addc_co_u32_e32 v239, vcc, 0, v249, vcc
	v_cvt_pk_bf16_f32 v60, v60, v61
	v_cvt_pk_bf16_f32 v61, v62, v63
	v_cvt_pk_bf16_f32 v56, v56, v57
	v_cvt_pk_bf16_f32 v57, v58, v59
	v_bfi_b32 v244, v237, v60, v56
	v_bfi_b32 v245, v237, v61, v57
	ds_swizzle_b32 v250, v244 offset:0x401f
	ds_swizzle_b32 v251, v245 offset:0x401f
	v_cvt_pk_bf16_f32 v48, v48, v49
	v_cvt_pk_bf16_f32 v49, v50, v51
	v_cvt_pk_bf16_f32 v40, v40, v41
	v_cvt_pk_bf16_f32 v41, v42, v43
	v_bfi_b32 v246, v237, v48, v40
	v_bfi_b32 v247, v237, v49, v41
	ds_swizzle_b32 v252, v246 offset:0x401f
	ds_swizzle_b32 v253, v247 offset:0x401f
	s_waitcnt lgkmcnt(0)
	v_bfi_b32 v240, v237, v250, v60
	v_bfi_b32 v241, v237, v251, v61
	v_bfi_b32 v242, v237, v56, v250
	v_bfi_b32 v243, v237, v57, v251
	global_store_dwordx4 v[238:239], v[240:243], off nt
	s_nop 1
	v_bfi_b32 v240, v237, v252, v48
	v_bfi_b32 v241, v237, v253, v49
	v_bfi_b32 v242, v237, v40, v252
	v_bfi_b32 v243, v237, v41, v253
	global_store_dwordx4 v[238:239], v[240:243], off offset:256 nt
	s_nop 1
	v_add_co_u32_e32 v238, vcc, 0x48000, v248
	s_nop 1
	v_addc_co_u32_e32 v239, vcc, 0, v249, vcc
	v_cvt_pk_bf16_f32 v52, v52, v53
	v_cvt_pk_bf16_f32 v53, v54, v55
	v_cvt_pk_bf16_f32 v44, v44, v45
	v_cvt_pk_bf16_f32 v45, v46, v47
	v_bfi_b32 v244, v237, v52, v44
	v_bfi_b32 v245, v237, v53, v45
	ds_swizzle_b32 v250, v244 offset:0x401f
	ds_swizzle_b32 v251, v245 offset:0x401f
	v_cvt_pk_bf16_f32 v32, v32, v33
	v_cvt_pk_bf16_f32 v33, v34, v35
	v_cvt_pk_bf16_f32 v24, v24, v25
	v_cvt_pk_bf16_f32 v25, v26, v27
	v_bfi_b32 v246, v237, v32, v24
	v_bfi_b32 v247, v237, v33, v25
	ds_swizzle_b32 v252, v246 offset:0x401f
	ds_swizzle_b32 v253, v247 offset:0x401f
	s_waitcnt lgkmcnt(0)
	v_bfi_b32 v240, v237, v250, v52
	v_bfi_b32 v241, v237, v251, v53
	v_bfi_b32 v242, v237, v44, v250
	v_bfi_b32 v243, v237, v45, v251
	global_store_dwordx4 v[238:239], v[240:243], off nt
	s_nop 1
	v_bfi_b32 v240, v237, v252, v32
	v_bfi_b32 v241, v237, v253, v33
	v_bfi_b32 v242, v237, v24, v252
	v_bfi_b32 v243, v237, v25, v253
	global_store_dwordx4 v[238:239], v[240:243], off offset:256 nt
	s_nop 1
	v_add_co_u32_e32 v238, vcc, 0x50000, v248
	s_nop 1
	v_addc_co_u32_e32 v239, vcc, 0, v249, vcc
	v_cvt_pk_bf16_f32 v36, v36, v37
	v_cvt_pk_bf16_f32 v37, v38, v39
	v_cvt_pk_bf16_f32 v28, v28, v29
	v_cvt_pk_bf16_f32 v29, v30, v31
	v_bfi_b32 v244, v237, v36, v28
	v_bfi_b32 v245, v237, v37, v29
	ds_swizzle_b32 v250, v244 offset:0x401f
	ds_swizzle_b32 v251, v245 offset:0x401f
	v_cvt_pk_bf16_f32 v16, v16, v17
	v_cvt_pk_bf16_f32 v17, v18, v19
	v_cvt_pk_bf16_f32 v8, v8, v9
	v_cvt_pk_bf16_f32 v9, v10, v11
	v_bfi_b32 v246, v237, v16, v8
	v_bfi_b32 v247, v237, v17, v9
	ds_swizzle_b32 v252, v246 offset:0x401f
	ds_swizzle_b32 v253, v247 offset:0x401f
	s_waitcnt lgkmcnt(0)
	v_bfi_b32 v240, v237, v250, v36
	v_bfi_b32 v241, v237, v251, v37
	v_bfi_b32 v242, v237, v28, v250
	v_bfi_b32 v243, v237, v29, v251
	global_store_dwordx4 v[238:239], v[240:243], off nt
	s_nop 1
	v_bfi_b32 v240, v237, v252, v16
	v_bfi_b32 v241, v237, v253, v17
	v_bfi_b32 v242, v237, v8, v252
	v_bfi_b32 v243, v237, v9, v253
	global_store_dwordx4 v[238:239], v[240:243], off offset:256 nt
	s_nop 1
	v_add_co_u32_e32 v238, vcc, 0x58000, v248
	s_nop 1
	v_addc_co_u32_e32 v239, vcc, 0, v249, vcc
	v_cvt_pk_bf16_f32 v20, v20, v21
	v_cvt_pk_bf16_f32 v21, v22, v23
	v_cvt_pk_bf16_f32 v12, v12, v13
	v_cvt_pk_bf16_f32 v13, v14, v15
	v_bfi_b32 v244, v237, v20, v12
	v_bfi_b32 v245, v237, v21, v13
	ds_swizzle_b32 v250, v244 offset:0x401f
	ds_swizzle_b32 v251, v245 offset:0x401f
	v_cvt_pk_bf16_f32 v4, v4, v5
	v_cvt_pk_bf16_f32 v5, v6, v7
	v_cvt_pk_bf16_f32 v0, v0, v1
	v_cvt_pk_bf16_f32 v1, v2, v3
	v_bfi_b32 v246, v237, v4, v0
	v_bfi_b32 v247, v237, v5, v1
	ds_swizzle_b32 v252, v246 offset:0x401f
	ds_swizzle_b32 v253, v247 offset:0x401f
	s_waitcnt lgkmcnt(0)
	v_bfi_b32 v240, v237, v250, v20
	v_bfi_b32 v241, v237, v251, v21
	v_bfi_b32 v242, v237, v12, v250
	v_bfi_b32 v243, v237, v13, v251
	global_store_dwordx4 v[238:239], v[240:243], off nt
	s_nop 1
	v_bfi_b32 v240, v237, v252, v4
	v_bfi_b32 v241, v237, v253, v5
	v_bfi_b32 v242, v237, v0, v252
	v_bfi_b32 v243, v237, v1, v253
	global_store_dwordx4 v[238:239], v[240:243], off offset:256 nt
	s_nop 1
	s_and_b64 vcc, exec, s[6:7]
	s_mov_b32 s40, s38
	s_mov_b32 s41, s39
	s_mov_b64 s[14:15], s[0:1]
	s_mov_b64 s[12:13], s[8:9]
	s_cbranch_vccz .LBB0_1277
	s_waitcnt vmcnt(0)
	s_cmpk_gt_u32 s20, 0xff
	s_cbranch_scc1 .LBB0_1288
	s_barrier

.LBB0_2046:
	ds_read_b128 v[152:155], v149
	ds_read_b128 v[156:159], v149 offset:1024
	ds_read_b128 v[160:163], v149 offset:2048
	ds_read_b128 v[164:167], v149 offset:3072
	s_add_u32 s8, s16, 0x100
	s_addc_u32 s9, s17, 0
	s_cmp_eq_u32 s45, 12
	s_cselect_b32 s21, s13, s9
	s_cselect_b32 s20, s12, s8
	s_cselect_b32 s19, s11, s44
	s_cselect_b32 s18, s42, s43
	v_lshl_add_u64 v[168:169], s[16:17], 0, v[140:141]
	s_add_i32 m0, s28, 0xc000
	ds_read_b128 v[172:175], v150
	ds_read_b128 v[176:179], v150 offset:1024
	ds_read_b128 v[180:183], v150 offset:2048
	ds_read_b128 v[184:187], v150 offset:3072
	ds_read_b128 v[188:191], v150 offset:4096
	ds_read_b128 v[192:195], v150 offset:5120
	ds_read_b128 v[196:199], v150 offset:6144
	ds_read_b128 v[200:203], v150 offset:7168
	global_load_lds_dwordx4 v[168:169], off
	v_lshl_add_u64 v[168:169], s[16:17], 0, v[138:139]
	s_add_i32 m0, s28, 0xe000
	s_nop 0
	global_load_lds_dwordx4 v[168:169], off
	s_waitcnt lgkmcnt(8)
	s_barrier
	s_waitcnt lgkmcnt(0)
	s_setprio 1
	s_waitcnt lgkmcnt(0)
	v_mfma_f32_16x16x32_bf16 v[124:127], v[152:155], v[172:175], v[124:127]
	v_mfma_f32_16x16x32_bf16 v[120:123], v[160:163], v[172:175], v[120:123]
	v_mfma_f32_16x16x32_bf16 v[116:119], v[152:155], v[180:183], v[116:119]
	v_mfma_f32_16x16x32_bf16 v[108:111], v[160:163], v[180:183], v[108:111]
	v_mfma_f32_16x16x32_bf16 v[100:103], v[152:155], v[188:191], v[100:103]
	v_mfma_f32_16x16x32_bf16 v[92:95], v[160:163], v[188:191], v[92:95]
	v_mfma_f32_16x16x32_bf16 v[84:87], v[152:155], v[196:199], v[84:87]
	v_mfma_f32_16x16x32_bf16 v[76:79], v[160:163], v[196:199], v[76:79]
	v_mfma_f32_16x16x32_bf16 v[124:127], v[156:159], v[176:179], v[124:127]
	v_mfma_f32_16x16x32_bf16 v[120:123], v[164:167], v[176:179], v[120:123]
	v_mfma_f32_16x16x32_bf16 v[116:119], v[156:159], v[184:187], v[116:119]
	v_mfma_f32_16x16x32_bf16 v[108:111], v[164:167], v[184:187], v[108:111]
	v_mfma_f32_16x16x32_bf16 v[100:103], v[156:159], v[192:195], v[100:103]
	v_mfma_f32_16x16x32_bf16 v[92:95], v[164:167], v[192:195], v[92:95]
	v_mfma_f32_16x16x32_bf16 v[84:87], v[156:159], v[200:203], v[84:87]
	v_mfma_f32_16x16x32_bf16 v[76:79], v[164:167], v[200:203], v[76:79]
	s_setprio 0
	s_barrier
	s_add_i32 s16, s36, s27
	v_lshl_add_u64 v[168:169], s[18:19], 0, v[132:133]
	s_mov_b32 m0, s16
	ds_read_b128 v[204:207], v151
	ds_read_b128 v[208:211], v151 offset:1024
	ds_read_b128 v[212:215], v151 offset:2048
	ds_read_b128 v[216:219], v151 offset:3072
	global_load_lds_dwordx4 v[168:169], off
	v_lshl_add_u64 v[220:221], s[18:19], 0, v[128:129]
	s_add_i32 m0, s16, 0x2000
	s_nop 0
	global_load_lds_dwordx4 v[220:221], off
	s_barrier
	s_waitcnt lgkmcnt(0)
	s_setprio 1
	s_waitcnt lgkmcnt(0)
	v_mfma_f32_16x16x32_bf16 v[112:115], v[204:207], v[172:175], v[112:115]
	v_mfma_f32_16x16x32_bf16 v[104:107], v[212:215], v[172:175], v[104:107]
	v_mfma_f32_16x16x32_bf16 v[96:99], v[204:207], v[180:183], v[96:99]
	v_mfma_f32_16x16x32_bf16 v[88:91], v[212:215], v[180:183], v[88:91]
	v_mfma_f32_16x16x32_bf16 v[80:83], v[204:207], v[188:191], v[80:83]
	v_mfma_f32_16x16x32_bf16 v[72:75], v[212:215], v[188:191], v[72:75]
	v_mfma_f32_16x16x32_bf16 v[68:71], v[204:207], v[196:199], v[68:71]
	v_mfma_f32_16x16x32_bf16 v[64:67], v[212:215], v[196:199], v[64:67]
	v_mfma_f32_16x16x32_bf16 v[112:115], v[208:211], v[176:179], v[112:115]
	v_mfma_f32_16x16x32_bf16 v[104:107], v[216:219], v[176:179], v[104:107]
	v_mfma_f32_16x16x32_bf16 v[96:99], v[208:211], v[184:187], v[96:99]
	v_mfma_f32_16x16x32_bf16 v[88:91], v[216:219], v[184:187], v[88:91]
	v_mfma_f32_16x16x32_bf16 v[80:83], v[208:211], v[192:195], v[80:83]
	v_mfma_f32_16x16x32_bf16 v[72:75], v[216:219], v[192:195], v[72:75]
	v_mfma_f32_16x16x32_bf16 v[68:71], v[208:211], v[200:203], v[68:71]
	v_mfma_f32_16x16x32_bf16 v[64:67], v[216:219], v[200:203], v[64:67]
	s_setprio 0
	s_mov_b32 m0, s28
	v_lshl_add_u64 v[222:223], s[20:21], 0, v[134:135]
	s_barrier
	ds_read_b128 v[172:175], v150 offset:16384
	ds_read_b128 v[176:179], v150 offset:17408
	ds_read_b128 v[180:183], v150 offset:18432
	ds_read_b128 v[184:187], v150 offset:19456
	ds_read_b128 v[188:191], v150 offset:20480
	ds_read_b128 v[192:195], v150 offset:21504
	ds_read_b128 v[196:199], v150 offset:22528
	ds_read_b128 v[200:203], v150 offset:23552
	global_load_lds_dwordx4 v[222:223], off
	v_lshl_add_u64 v[224:225], s[20:21], 0, v[130:131]
	s_mov_b32 m0, s29
	s_nop 0
	global_load_lds_dwordx4 v[224:225], off
	s_barrier
	s_waitcnt lgkmcnt(0)
	s_setprio 1
	s_waitcnt lgkmcnt(0)
	v_mfma_f32_16x16x32_bf16 v[60:63], v[152:155], v[172:175], v[60:63]
	v_mfma_f32_16x16x32_bf16 v[56:59], v[160:163], v[172:175], v[56:59]
	v_mfma_f32_16x16x32_bf16 v[52:55], v[152:155], v[180:183], v[52:55]
	v_mfma_f32_16x16x32_bf16 v[44:47], v[160:163], v[180:183], v[44:47]
	v_mfma_f32_16x16x32_bf16 v[36:39], v[152:155], v[188:191], v[36:39]
	v_mfma_f32_16x16x32_bf16 v[28:31], v[160:163], v[188:191], v[28:31]
	v_mfma_f32_16x16x32_bf16 v[20:23], v[152:155], v[196:199], v[20:23]
	v_mfma_f32_16x16x32_bf16 v[12:15], v[160:163], v[196:199], v[12:15]
	v_mfma_f32_16x16x32_bf16 v[60:63], v[156:159], v[176:179], v[60:63]
	v_mfma_f32_16x16x32_bf16 v[56:59], v[164:167], v[176:179], v[56:59]
	v_mfma_f32_16x16x32_bf16 v[52:55], v[156:159], v[184:187], v[52:55]
	v_mfma_f32_16x16x32_bf16 v[44:47], v[164:167], v[184:187], v[44:47]
	v_mfma_f32_16x16x32_bf16 v[36:39], v[156:159], v[192:195], v[36:39]
	v_mfma_f32_16x16x32_bf16 v[28:31], v[164:167], v[192:195], v[28:31]
	v_mfma_f32_16x16x32_bf16 v[20:23], v[156:159], v[200:203], v[20:23]
	v_mfma_f32_16x16x32_bf16 v[12:15], v[164:167], v[200:203], v[12:15]
	s_setprio 0
	s_barrier
	s_add_u32 s16, s18, 0x40000
	s_addc_u32 s17, s19, 0
	s_add_i32 s46, s37, s27
	v_lshl_add_u64 v[152:153], s[16:17], 0, v[132:133]
	s_mov_b32 m0, s46
	s_nop 0
	global_load_lds_dwordx4 v[152:153], off
	v_lshl_add_u64 v[152:153], s[16:17], 0, v[128:129]
	s_add_i32 m0, s46, 0x2000
	s_nop 0
	global_load_lds_dwordx4 v[152:153], off
	s_waitcnt vmcnt(6)
	s_barrier
	s_setprio 1
	v_mfma_f32_16x16x32_bf16 v[48:51], v[204:207], v[172:175], v[48:51]
	v_mfma_f32_16x16x32_bf16 v[40:43], v[212:215], v[172:175], v[40:43]
	v_mfma_f32_16x16x32_bf16 v[32:35], v[204:207], v[180:183], v[32:35]
	v_mfma_f32_16x16x32_bf16 v[24:27], v[212:215], v[180:183], v[24:27]
	v_mfma_f32_16x16x32_bf16 v[16:19], v[204:207], v[188:191], v[16:19]
	v_mfma_f32_16x16x32_bf16 v[8:11], v[212:215], v[188:191], v[8:11]
	v_mfma_f32_16x16x32_bf16 v[4:7], v[204:207], v[196:199], v[4:7]
	v_mfma_f32_16x16x32_bf16 v[0:3], v[212:215], v[196:199], v[0:3]
	v_mfma_f32_16x16x32_bf16 v[48:51], v[208:211], v[176:179], v[48:51]
	v_mfma_f32_16x16x32_bf16 v[40:43], v[216:219], v[176:179], v[40:43]
	v_mfma_f32_16x16x32_bf16 v[32:35], v[208:211], v[184:187], v[32:35]
	v_mfma_f32_16x16x32_bf16 v[24:27], v[216:219], v[184:187], v[24:27]
	v_mfma_f32_16x16x32_bf16 v[16:19], v[208:211], v[192:195], v[16:19]
	v_mfma_f32_16x16x32_bf16 v[8:11], v[216:219], v[192:195], v[8:11]
	v_mfma_f32_16x16x32_bf16 v[4:7], v[208:211], v[200:203], v[4:7]
	v_mfma_f32_16x16x32_bf16 v[0:3], v[216:219], v[200:203], v[0:3]
	s_setprio 0
	s_add_i32 s46, 0, 0x18000
	v_add_u32_e32 v164, s46, v148
	s_barrier
	ds_read_b128 v[152:155], v164
	ds_read_b128 v[156:159], v164 offset:1024
	ds_read_b128 v[160:163], v164 offset:2048
	ds_read_b128 v[164:167], v164 offset:3072
	s_add_u32 s16, s20, 0xea000
	s_addc_u32 s17, s21, 0
	s_mov_b32 m0, s30
	v_lshl_add_u64 v[204:205], s[16:17], 0, v[134:135]
	ds_read_b128 v[172:175], v150 offset:32768
	ds_read_b128 v[176:179], v150 offset:33792
	ds_read_b128 v[180:183], v150 offset:34816
	ds_read_b128 v[184:187], v150 offset:35840
	ds_read_b128 v[188:191], v150 offset:36864
	ds_read_b128 v[192:195], v150 offset:37888
	ds_read_b128 v[196:199], v150 offset:38912
	ds_read_b128 v[200:203], v150 offset:39936
	global_load_lds_dwordx4 v[204:205], off
	v_lshl_add_u64 v[204:205], s[16:17], 0, v[130:131]
	s_mov_b32 m0, s31
	s_nop 0
	global_load_lds_dwordx4 v[204:205], off
	s_waitcnt lgkmcnt(8)
	s_barrier
	s_waitcnt lgkmcnt(0)
	s_setprio 1
	s_waitcnt lgkmcnt(0)
	v_mfma_f32_16x16x32_bf16 v[124:127], v[152:155], v[172:175], v[124:127]
	v_mfma_f32_16x16x32_bf16 v[120:123], v[160:163], v[172:175], v[120:123]
	v_mfma_f32_16x16x32_bf16 v[116:119], v[152:155], v[180:183], v[116:119]
	v_mfma_f32_16x16x32_bf16 v[108:111], v[160:163], v[180:183], v[108:111]
	v_mfma_f32_16x16x32_bf16 v[100:103], v[152:155], v[188:191], v[100:103]
	v_mfma_f32_16x16x32_bf16 v[92:95], v[160:163], v[188:191], v[92:95]
	v_mfma_f32_16x16x32_bf16 v[84:87], v[152:155], v[196:199], v[84:87]
	v_mfma_f32_16x16x32_bf16 v[76:79], v[160:163], v[196:199], v[76:79]
	v_mfma_f32_16x16x32_bf16 v[124:127], v[156:159], v[176:179], v[124:127]
	v_mfma_f32_16x16x32_bf16 v[120:123], v[164:167], v[176:179], v[120:123]
	v_mfma_f32_16x16x32_bf16 v[116:119], v[156:159], v[184:187], v[116:119]
	v_mfma_f32_16x16x32_bf16 v[108:111], v[164:167], v[184:187], v[108:111]
	v_mfma_f32_16x16x32_bf16 v[100:103], v[156:159], v[192:195], v[100:103]
	v_mfma_f32_16x16x32_bf16 v[92:95], v[164:167], v[192:195], v[92:95]
	v_mfma_f32_16x16x32_bf16 v[84:87], v[156:159], v[200:203], v[84:87]
	v_mfma_f32_16x16x32_bf16 v[76:79], v[164:167], v[200:203], v[76:79]
	s_setprio 0
	s_barrier
	s_add_i32 s20, 0, 0x1c000
	s_add_i32 s16, s46, s27
	v_add_u32_e32 v171, s20, v148
	v_lshl_add_u64 v[168:169], v[168:169], 0, s[4:5]
	s_mov_b32 m0, s16
	ds_read_b128 v[204:207], v171
	ds_read_b128 v[208:211], v171 offset:1024
	ds_read_b128 v[212:215], v171 offset:2048
	ds_read_b128 v[216:219], v171 offset:3072
	global_load_lds_dwordx4 v[168:169], off
	v_lshl_add_u64 v[168:169], v[220:221], 0, s[4:5]
	s_add_i32 m0, s16, 0x2000
	s_nop 0
	global_load_lds_dwordx4 v[168:169], off
	s_barrier
	s_waitcnt lgkmcnt(0)
	s_setprio 1
	s_waitcnt lgkmcnt(0)
	v_mfma_f32_16x16x32_bf16 v[112:115], v[204:207], v[172:175], v[112:115]
	v_mfma_f32_16x16x32_bf16 v[104:107], v[212:215], v[172:175], v[104:107]
	v_mfma_f32_16x16x32_bf16 v[96:99], v[204:207], v[180:183], v[96:99]
	v_mfma_f32_16x16x32_bf16 v[88:91], v[212:215], v[180:183], v[88:91]
	v_mfma_f32_16x16x32_bf16 v[80:83], v[204:207], v[188:191], v[80:83]
	v_mfma_f32_16x16x32_bf16 v[72:75], v[212:215], v[188:191], v[72:75]
	v_mfma_f32_16x16x32_bf16 v[68:71], v[204:207], v[196:199], v[68:71]
	v_mfma_f32_16x16x32_bf16 v[64:67], v[212:215], v[196:199], v[64:67]
	v_mfma_f32_16x16x32_bf16 v[112:115], v[208:211], v[176:179], v[112:115]
	v_mfma_f32_16x16x32_bf16 v[104:107], v[216:219], v[176:179], v[104:107]
	v_mfma_f32_16x16x32_bf16 v[96:99], v[208:211], v[184:187], v[96:99]
	v_mfma_f32_16x16x32_bf16 v[88:91], v[216:219], v[184:187], v[88:91]
	v_mfma_f32_16x16x32_bf16 v[80:83], v[208:211], v[192:195], v[80:83]
	v_mfma_f32_16x16x32_bf16 v[72:75], v[216:219], v[192:195], v[72:75]
	v_mfma_f32_16x16x32_bf16 v[68:71], v[208:211], v[200:203], v[68:71]
	v_mfma_f32_16x16x32_bf16 v[64:67], v[216:219], v[200:203], v[64:67]
	s_setprio 0
	s_mov_b32 m0, s33
	v_lshl_add_u64 v[168:169], v[222:223], 0, s[4:5]
	s_barrier
	ds_read_b128 v[172:175], v150 offset:49152
	ds_read_b128 v[176:179], v150 offset:50176
	ds_read_b128 v[180:183], v150 offset:51200
	ds_read_b128 v[184:187], v150 offset:52224
	ds_read_b128 v[188:191], v150 offset:53248
	ds_read_b128 v[192:195], v150 offset:54272
	ds_read_b128 v[196:199], v150 offset:55296
	ds_read_b128 v[200:203], v150 offset:56320
	global_load_lds_dwordx4 v[168:169], off
	v_lshl_add_u64 v[168:169], v[224:225], 0, s[4:5]
	s_mov_b32 m0, s34
	s_nop 0
	global_load_lds_dwordx4 v[168:169], off
	s_barrier
	s_waitcnt lgkmcnt(0)
	s_setprio 1
	s_waitcnt lgkmcnt(0)
	v_mfma_f32_16x16x32_bf16 v[60:63], v[152:155], v[172:175], v[60:63]
	v_mfma_f32_16x16x32_bf16 v[56:59], v[160:163], v[172:175], v[56:59]
	v_mfma_f32_16x16x32_bf16 v[52:55], v[152:155], v[180:183], v[52:55]
	v_mfma_f32_16x16x32_bf16 v[44:47], v[160:163], v[180:183], v[44:47]
	v_mfma_f32_16x16x32_bf16 v[36:39], v[152:155], v[188:191], v[36:39]
	v_mfma_f32_16x16x32_bf16 v[28:31], v[160:163], v[188:191], v[28:31]
	v_mfma_f32_16x16x32_bf16 v[20:23], v[152:155], v[196:199], v[20:23]
	v_mfma_f32_16x16x32_bf16 v[12:15], v[160:163], v[196:199], v[12:15]
	v_mfma_f32_16x16x32_bf16 v[60:63], v[156:159], v[176:179], v[60:63]
	v_mfma_f32_16x16x32_bf16 v[56:59], v[164:167], v[176:179], v[56:59]
	v_mfma_f32_16x16x32_bf16 v[52:55], v[156:159], v[184:187], v[52:55]
	v_mfma_f32_16x16x32_bf16 v[44:47], v[164:167], v[184:187], v[44:47]
	v_mfma_f32_16x16x32_bf16 v[36:39], v[156:159], v[192:195], v[36:39]
	v_mfma_f32_16x16x32_bf16 v[28:31], v[164:167], v[192:195], v[28:31]
	v_mfma_f32_16x16x32_bf16 v[20:23], v[156:159], v[200:203], v[20:23]
	v_mfma_f32_16x16x32_bf16 v[12:15], v[164:167], v[200:203], v[12:15]
	s_setprio 0
	s_barrier
	s_add_u32 s16, s18, 0x40080
	s_addc_u32 s17, s19, 0
	s_add_i32 s18, s20, s27
	v_lshl_add_u64 v[152:153], s[16:17], 0, v[132:133]
	s_mov_b32 m0, s18
	s_nop 0
	global_load_lds_dwordx4 v[152:153], off
	v_lshl_add_u64 v[152:153], s[16:17], 0, v[128:129]
	s_add_i32 m0, s18, 0x2000
	s_nop 0
	global_load_lds_dwordx4 v[152:153], off
	s_waitcnt vmcnt(6)
	s_barrier
	s_setprio 1
	v_mfma_f32_16x16x32_bf16 v[48:51], v[204:207], v[172:175], v[48:51]
	v_mfma_f32_16x16x32_bf16 v[40:43], v[212:215], v[172:175], v[40:43]
	v_mfma_f32_16x16x32_bf16 v[32:35], v[204:207], v[180:183], v[32:35]
	v_mfma_f32_16x16x32_bf16 v[24:27], v[212:215], v[180:183], v[24:27]
	v_mfma_f32_16x16x32_bf16 v[16:19], v[204:207], v[188:191], v[16:19]
	v_mfma_f32_16x16x32_bf16 v[8:11], v[212:215], v[188:191], v[8:11]
	v_mfma_f32_16x16x32_bf16 v[4:7], v[204:207], v[196:199], v[4:7]
	v_mfma_f32_16x16x32_bf16 v[0:3], v[212:215], v[196:199], v[0:3]
	v_mfma_f32_16x16x32_bf16 v[48:51], v[208:211], v[176:179], v[48:51]
	v_mfma_f32_16x16x32_bf16 v[40:43], v[216:219], v[176:179], v[40:43]
	v_mfma_f32_16x16x32_bf16 v[32:35], v[208:211], v[184:187], v[32:35]
	v_mfma_f32_16x16x32_bf16 v[24:27], v[216:219], v[184:187], v[24:27]
	v_mfma_f32_16x16x32_bf16 v[16:19], v[208:211], v[192:195], v[16:19]
	v_mfma_f32_16x16x32_bf16 v[8:11], v[216:219], v[192:195], v[8:11]
	v_mfma_f32_16x16x32_bf16 v[4:7], v[208:211], v[200:203], v[4:7]
	v_mfma_f32_16x16x32_bf16 v[0:3], v[216:219], v[200:203], v[0:3]
	s_setprio 0
	s_add_i32 s45, s45, 2
	s_add_u32 s43, s43, 0x100
	s_addc_u32 s44, s44, 0
	s_cmp_gt_u32 s45, 13
	s_mov_b64 s[16:17], s[8:9]
	s_barrier
	s_cbranch_scc0 .LBB0_2046
	v_lshl_add_u32 v152, s41, 8, v147
	s_lshl_b32 s8, s40, 8
	v_ashrrev_i32_e32 v153, 31, v152
	s_ashr_i32 s9, s8, 31
	v_lshlrev_b64 v[154:155], 11, v[152:153]
	v_lshl_add_u64 v[154:155], s[0:1], 0, v[154:155]
	s_lshl_b64 s[8:9], s[8:9], 1
	v_lshl_add_u64 v[154:155], v[154:155], 0, s[8:9]
	v_lshl_add_u64 v[154:155], v[154:155], 0, s[2:3]
	v_lshl_add_u64 v[154:155], v[154:155], 0, v[136:137]
	v_mbcnt_lo_u32_b32 v237, -1, 0
	v_mbcnt_hi_u32_b32 v237, -1, v237
	v_bfe_i32 v237, v237, 4, 1
	v_and_b32_e32 v244, 24, v237
	v_add_co_u32_e32 v248, vcc, v244, v154
	s_nop 1
	v_addc_co_u32_e32 v249, vcc, 0, v155, vcc
	v_cvt_pk_bf16_f32 v124, v124, v125
	v_cvt_pk_bf16_f32 v125, v126, v127
	v_cvt_pk_bf16_f32 v120, v120, v121
	v_cvt_pk_bf16_f32 v121, v122, v123
	v_bfi_b32 v244, v237, v124, v120
	v_bfi_b32 v245, v237, v125, v121
	ds_swizzle_b32 v250, v244 offset:0x401f
	ds_swizzle_b32 v251, v245 offset:0x401f
	v_cvt_pk_bf16_f32 v112, v112, v113
	v_cvt_pk_bf16_f32 v113, v114, v115
	v_cvt_pk_bf16_f32 v104, v104, v105
	v_cvt_pk_bf16_f32 v105, v106, v107
	v_bfi_b32 v246, v237, v112, v104
	v_bfi_b32 v247, v237, v113, v105
	ds_swizzle_b32 v252, v246 offset:0x401f
	ds_swizzle_b32 v253, v247 offset:0x401f
	s_waitcnt lgkmcnt(0)
	v_bfi_b32 v240, v237, v250, v124
	v_bfi_b32 v241, v237, v251, v125
	v_bfi_b32 v242, v237, v120, v250
	v_bfi_b32 v243, v237, v121, v251
	global_store_dwordx4 v[248:249], v[240:243], off nt
	s_nop 1
	v_bfi_b32 v240, v237, v252, v112
	v_bfi_b32 v241, v237, v253, v113
	v_bfi_b32 v242, v237, v104, v252
	v_bfi_b32 v243, v237, v105, v253
	global_store_dwordx4 v[248:249], v[240:243], off offset:256 nt
	s_nop 1
	v_add_co_u32_e32 v238, vcc, 0x8000, v248
	s_nop 1
	v_addc_co_u32_e32 v239, vcc, 0, v249, vcc
	v_cvt_pk_bf16_f32 v116, v116, v117
	v_cvt_pk_bf16_f32 v117, v118, v119
	v_cvt_pk_bf16_f32 v108, v108, v109
	v_cvt_pk_bf16_f32 v109, v110, v111
	v_bfi_b32 v244, v237, v116, v108
	v_bfi_b32 v245, v237, v117, v109
	ds_swizzle_b32 v250, v244 offset:0x401f
	ds_swizzle_b32 v251, v245 offset:0x401f
	v_cvt_pk_bf16_f32 v96, v96, v97
	v_cvt_pk_bf16_f32 v97, v98, v99
	v_cvt_pk_bf16_f32 v88, v88, v89
	v_cvt_pk_bf16_f32 v89, v90, v91
	v_bfi_b32 v246, v237, v96, v88
	v_bfi_b32 v247, v237, v97, v89
	ds_swizzle_b32 v252, v246 offset:0x401f
	ds_swizzle_b32 v253, v247 offset:0x401f
	s_waitcnt lgkmcnt(0)
	v_bfi_b32 v240, v237, v250, v116
	v_bfi_b32 v241, v237, v251, v117
	v_bfi_b32 v242, v237, v108, v250
	v_bfi_b32 v243, v237, v109, v251
	global_store_dwordx4 v[238:239], v[240:243], off nt
	s_nop 1
	v_bfi_b32 v240, v237, v252, v96
	v_bfi_b32 v241, v237, v253, v97
	v_bfi_b32 v242, v237, v88, v252
	v_bfi_b32 v243, v237, v89, v253
	global_store_dwordx4 v[238:239], v[240:243], off offset:256 nt
	s_nop 1
	v_add_co_u32_e32 v238, vcc, 0x10000, v248
	s_nop 1
	v_addc_co_u32_e32 v239, vcc, 0, v249, vcc
	v_cvt_pk_bf16_f32 v100, v100, v101
	v_cvt_pk_bf16_f32 v101, v102, v103
	v_cvt_pk_bf16_f32 v92, v92, v93
	v_cvt_pk_bf16_f32 v93, v94, v95
	v_bfi_b32 v244, v237, v100, v92
	v_bfi_b32 v245, v237, v101, v93
	ds_swizzle_b32 v250, v244 offset:0x401f
	ds_swizzle_b32 v251, v245 offset:0x401f
	v_cvt_pk_bf16_f32 v80, v80, v81
	v_cvt_pk_bf16_f32 v81, v82, v83
	v_cvt_pk_bf16_f32 v72, v72, v73
	v_cvt_pk_bf16_f32 v73, v74, v75
	v_bfi_b32 v246, v237, v80, v72
	v_bfi_b32 v247, v237, v81, v73
	ds_swizzle_b32 v252, v246 offset:0x401f
	ds_swizzle_b32 v253, v247 offset:0x401f
	s_waitcnt lgkmcnt(0)
	v_bfi_b32 v240, v237, v250, v100
	v_bfi_b32 v241, v237, v251, v101
	v_bfi_b32 v242, v237, v92, v250
	v_bfi_b32 v243, v237, v93, v251
	global_store_dwordx4 v[238:239], v[240:243], off nt
	s_nop 1
	v_bfi_b32 v240, v237, v252, v80
	v_bfi_b32 v241, v237, v253, v81
	v_bfi_b32 v242, v237, v72, v252
	v_bfi_b32 v243, v237, v73, v253
	global_store_dwordx4 v[238:239], v[240:243], off offset:256 nt
	s_nop 1
	v_add_co_u32_e32 v238, vcc, 0x18000, v248
	s_nop 1
	v_addc_co_u32_e32 v239, vcc, 0, v249, vcc
	v_cvt_pk_bf16_f32 v84, v84, v85
	v_cvt_pk_bf16_f32 v85, v86, v87
	v_cvt_pk_bf16_f32 v76, v76, v77
	v_cvt_pk_bf16_f32 v77, v78, v79
	v_bfi_b32 v244, v237, v84, v76
	v_bfi_b32 v245, v237, v85, v77
	ds_swizzle_b32 v250, v244 offset:0x401f
	ds_swizzle_b32 v251, v245 offset:0x401f
	v_cvt_pk_bf16_f32 v68, v68, v69
	v_cvt_pk_bf16_f32 v69, v70, v71
	v_cvt_pk_bf16_f32 v64, v64, v65
	v_cvt_pk_bf16_f32 v65, v66, v67
	v_bfi_b32 v246, v237, v68, v64
	v_bfi_b32 v247, v237, v69, v65
	ds_swizzle_b32 v252, v246 offset:0x401f
	ds_swizzle_b32 v253, v247 offset:0x401f
	s_waitcnt lgkmcnt(0)
	v_bfi_b32 v240, v237, v250, v84
	v_bfi_b32 v241, v237, v251, v85
	v_bfi_b32 v242, v237, v76, v250
	v_bfi_b32 v243, v237, v77, v251
	global_store_dwordx4 v[238:239], v[240:243], off nt
	s_nop 1
	v_bfi_b32 v240, v237, v252, v68
	v_bfi_b32 v241, v237, v253, v69
	v_bfi_b32 v242, v237, v64, v252
	v_bfi_b32 v243, v237, v65, v253
	global_store_dwordx4 v[238:239], v[240:243], off offset:256 nt
	s_nop 1
	v_add_co_u32_e32 v238, vcc, 0x40000, v248
	s_nop 1
	v_addc_co_u32_e32 v239, vcc, 0, v249, vcc
	v_cvt_pk_bf16_f32 v60, v60, v61
	v_cvt_pk_bf16_f32 v61, v62, v63
	v_cvt_pk_bf16_f32 v56, v56, v57
	v_cvt_pk_bf16_f32 v57, v58, v59
	v_bfi_b32 v244, v237, v60, v56
	v_bfi_b32 v245, v237, v61, v57
	ds_swizzle_b32 v250, v244 offset:0x401f
	ds_swizzle_b32 v251, v245 offset:0x401f
	v_cvt_pk_bf16_f32 v48, v48, v49
	v_cvt_pk_bf16_f32 v49, v50, v51
	v_cvt_pk_bf16_f32 v40, v40, v41
	v_cvt_pk_bf16_f32 v41, v42, v43
	v_bfi_b32 v246, v237, v48, v40
	v_bfi_b32 v247, v237, v49, v41
	ds_swizzle_b32 v252, v246 offset:0x401f
	ds_swizzle_b32 v253, v247 offset:0x401f
	s_waitcnt lgkmcnt(0)
	v_bfi_b32 v240, v237, v250, v60
	v_bfi_b32 v241, v237, v251, v61
	v_bfi_b32 v242, v237, v56, v250
	v_bfi_b32 v243, v237, v57, v251
	global_store_dwordx4 v[238:239], v[240:243], off nt
	s_nop 1
	v_bfi_b32 v240, v237, v252, v48
	v_bfi_b32 v241, v237, v253, v49
	v_bfi_b32 v242, v237, v40, v252
	v_bfi_b32 v243, v237, v41, v253
	global_store_dwordx4 v[238:239], v[240:243], off offset:256 nt
	s_nop 1
	v_add_co_u32_e32 v238, vcc, 0x48000, v248
	s_nop 1
	v_addc_co_u32_e32 v239, vcc, 0, v249, vcc
	v_cvt_pk_bf16_f32 v52, v52, v53
	v_cvt_pk_bf16_f32 v53, v54, v55
	v_cvt_pk_bf16_f32 v44, v44, v45
	v_cvt_pk_bf16_f32 v45, v46, v47
	v_bfi_b32 v244, v237, v52, v44
	v_bfi_b32 v245, v237, v53, v45
	ds_swizzle_b32 v250, v244 offset:0x401f
	ds_swizzle_b32 v251, v245 offset:0x401f
	v_cvt_pk_bf16_f32 v32, v32, v33
	v_cvt_pk_bf16_f32 v33, v34, v35
	v_cvt_pk_bf16_f32 v24, v24, v25
	v_cvt_pk_bf16_f32 v25, v26, v27
	v_bfi_b32 v246, v237, v32, v24
	v_bfi_b32 v247, v237, v33, v25
	ds_swizzle_b32 v252, v246 offset:0x401f
	ds_swizzle_b32 v253, v247 offset:0x401f
	s_waitcnt lgkmcnt(0)
	v_bfi_b32 v240, v237, v250, v52
	v_bfi_b32 v241, v237, v251, v53
	v_bfi_b32 v242, v237, v44, v250
	v_bfi_b32 v243, v237, v45, v251
	global_store_dwordx4 v[238:239], v[240:243], off nt
	s_nop 1
	v_bfi_b32 v240, v237, v252, v32
	v_bfi_b32 v241, v237, v253, v33
	v_bfi_b32 v242, v237, v24, v252
	v_bfi_b32 v243, v237, v25, v253
	global_store_dwordx4 v[238:239], v[240:243], off offset:256 nt
	s_nop 1
	v_add_co_u32_e32 v238, vcc, 0x50000, v248
	s_nop 1
	v_addc_co_u32_e32 v239, vcc, 0, v249, vcc
	v_cvt_pk_bf16_f32 v36, v36, v37
	v_cvt_pk_bf16_f32 v37, v38, v39
	v_cvt_pk_bf16_f32 v28, v28, v29
	v_cvt_pk_bf16_f32 v29, v30, v31
	v_bfi_b32 v244, v237, v36, v28
	v_bfi_b32 v245, v237, v37, v29
	ds_swizzle_b32 v250, v244 offset:0x401f
	ds_swizzle_b32 v251, v245 offset:0x401f
	v_cvt_pk_bf16_f32 v16, v16, v17
	v_cvt_pk_bf16_f32 v17, v18, v19
	v_cvt_pk_bf16_f32 v8, v8, v9
	v_cvt_pk_bf16_f32 v9, v10, v11
	v_bfi_b32 v246, v237, v16, v8
	v_bfi_b32 v247, v237, v17, v9
	ds_swizzle_b32 v252, v246 offset:0x401f
	ds_swizzle_b32 v253, v247 offset:0x401f
	s_waitcnt lgkmcnt(0)
	v_bfi_b32 v240, v237, v250, v36
	v_bfi_b32 v241, v237, v251, v37
	v_bfi_b32 v242, v237, v28, v250
	v_bfi_b32 v243, v237, v29, v251
	global_store_dwordx4 v[238:239], v[240:243], off nt
	s_nop 1
	v_bfi_b32 v240, v237, v252, v16
	v_bfi_b32 v241, v237, v253, v17
	v_bfi_b32 v242, v237, v8, v252
	v_bfi_b32 v243, v237, v9, v253
	global_store_dwordx4 v[238:239], v[240:243], off offset:256 nt
	s_nop 1
	v_add_co_u32_e32 v238, vcc, 0x58000, v248
	s_nop 1
	v_addc_co_u32_e32 v239, vcc, 0, v249, vcc
	v_cvt_pk_bf16_f32 v20, v20, v21
	v_cvt_pk_bf16_f32 v21, v22, v23
	v_cvt_pk_bf16_f32 v12, v12, v13
	v_cvt_pk_bf16_f32 v13, v14, v15
	v_bfi_b32 v244, v237, v20, v12
	v_bfi_b32 v245, v237, v21, v13
	ds_swizzle_b32 v250, v244 offset:0x401f
	ds_swizzle_b32 v251, v245 offset:0x401f
	v_cvt_pk_bf16_f32 v4, v4, v5
	v_cvt_pk_bf16_f32 v5, v6, v7
	v_cvt_pk_bf16_f32 v0, v0, v1
	v_cvt_pk_bf16_f32 v1, v2, v3
	v_bfi_b32 v246, v237, v4, v0
	v_bfi_b32 v247, v237, v5, v1
	ds_swizzle_b32 v252, v246 offset:0x401f
	ds_swizzle_b32 v253, v247 offset:0x401f
	s_waitcnt lgkmcnt(0)
	v_bfi_b32 v240, v237, v250, v20
	v_bfi_b32 v241, v237, v251, v21
	v_bfi_b32 v242, v237, v12, v250
	v_bfi_b32 v243, v237, v13, v251
	global_store_dwordx4 v[238:239], v[240:243], off nt
	s_nop 1
	v_bfi_b32 v240, v237, v252, v4
	v_bfi_b32 v241, v237, v253, v5
	v_bfi_b32 v242, v237, v0, v252
	v_bfi_b32 v243, v237, v1, v253
	global_store_dwordx4 v[238:239], v[240:243], off offset:256 nt
	s_nop 1
	s_and_b64 vcc, exec, s[6:7]
	s_mov_b32 s40, s10
	s_mov_b32 s41, s39
	s_mov_b64 s[18:19], s[14:15]
	s_mov_b64 s[16:17], s[12:13]
	s_cbranch_vccz .LBB0_2041
	s_waitcnt vmcnt(0)
	s_cmpk_gt_u32 s22, 0xff
	s_cbranch_scc1 .LBB0_2050
	s_barrier

.Lupf_u1_entry:
	v_mbcnt_lo_u32_b32 v253, -1, 0
	v_mbcnt_hi_u32_b32 v253, -1, v253
	v_and_b32_e32 v254, 15, v253
	v_lshrrev_b32_e32 v255, 4, v253
	s_lshr_b32 s100, s33, 6
	s_lshr_b32 s101, s100, 2
	s_and_b32 s100, s100, 3
	s_lshl_b32 vcc_lo, s101, 6
	v_add_u32_e32 v251, vcc_lo, v254
	s_add_i32 vcc_hi, s98, -1
	v_add_u32_e32 v250, vcc_hi, v251
	v_mul_u32_u24_e32 v250, 0x1600, v250
	s_lshl_b32 vcc_lo, s40, 7
	s_lshl_b32 vcc_hi, s100, 5
	s_add_i32 vcc_lo, vcc_lo, vcc_hi
	v_lshl_add_u32 v253, v255, 2, vcc_lo
	v_and_b32_e32 v252, 1, v255
	v_lshlrev_b32_e32 v252, 1, v252
	v_lshrrev_b32_e32 v245, 1, v255
	v_or_b32_e32 v252, v252, v245
	v_lshl_add_u32 v252, v252, 3, vcc_lo
	v_lshl_add_u32 v250, v252, 1, v250
	v_lshlrev_b32_e32 v146, 2, v253
	v_add_u32_e32 v147, 0x5800, v146
	v_add_u32_e32 v168, 0xb000, v146
	v_add_u32_e32 v169, 0x2c00, v146
	v_add_u32_e32 v245, 0x8400, v146
	v_add_u32_e32 v252, 0xdc00, v146
	global_load_dwordx4 v[172:175], v146, s[14:15] offset:0
	global_load_dwordx4 v[176:179], v147, s[14:15] offset:0
	global_load_dwordx4 v[180:183], v168, s[14:15] offset:0
	global_load_dwordx4 v[188:191], v169, s[14:15] offset:0
	global_load_dwordx4 v[192:195], v245, s[14:15] offset:0
	global_load_dwordx4 v[196:199], v252, s[14:15] offset:0
	global_load_dwordx4 v[184:187], v146, s[16:17] offset:0
	global_load_dwordx4 v[200:203], v169, s[16:17] offset:0
	s_lshl_b32 s101, s101, 11
	s_lshl_b32 s100, s100, 7
	s_add_i32 s101, s101, s100
	s_add_i32 s101, s101, 0x20000
	v_lshl_add_u32 v249, v255, 4, s101
	v_add_u32_e32 v253, 0x400, v249
	v_cmp_eq_u32_e64 s[98:99], 0, v254
	v_cmp_eq_u32_e32 vcc, 15, v254
	s_nop 4
	s_mov_b64 exec, s[98:99]
	ds_write_b128 v253, v[124:127] offset:0
	ds_write_b128 v253, v[108:111] offset:64
	ds_write_b128 v253, v[112:115] offset:512
	ds_write_b128 v253, v[84:87] offset:576
	ds_write_b128 v253, v[72:75] offset:4096
	ds_write_b128 v253, v[44:47] offset:4160
	ds_write_b128 v253, v[48:51] offset:4608
	ds_write_b128 v253, v[20:23] offset:4672
	s_mov_b64 exec, vcc
	ds_write_b128 v253, v[104:107] offset:1024
	ds_write_b128 v253, v[76:79] offset:1088
	ds_write_b128 v253, v[80:83] offset:1536
	ds_write_b128 v253, v[52:55] offset:1600
	ds_write_b128 v253, v[40:43] offset:5120
	ds_write_b128 v253, v[12:15] offset:5184
	ds_write_b128 v253, v[16:19] offset:5632
	ds_write_b128 v253, v[0:3] offset:5696
	s_mov_b64 exec, -1
	s_waitcnt lgkmcnt(0)
	s_barrier
	ds_read_b128 v[204:207], v249 offset:0
	ds_read_b128 v[208:211], v249 offset:512
	ds_read_b128 v[160:163], v249 offset:3072
	ds_read_b128 v[164:167], v249 offset:3584
	s_waitcnt vmcnt(0) lgkmcnt(0)
	v_cndmask_b32_e32 v148, v124, v204, vcc
	v_cndmask_b32_e32 v149, v125, v205, vcc
	v_cndmask_b32_e32 v150, v126, v206, vcc
	v_cndmask_b32_e32 v151, v127, v207, vcc
	v_cndmask_b32_e64 v152, v124, v120, s[98:99]
	v_cndmask_b32_e64 v153, v125, v121, s[98:99]
	v_cndmask_b32_e64 v154, v126, v122, s[98:99]
	v_cndmask_b32_e64 v155, v127, v123, s[98:99]
	v_fma_f32 v156, v176, v124, v184
	v_fma_f32 v157, v177, v125, v185
	v_fma_f32 v158, v178, v126, v186
	v_fma_f32 v159, v179, v127, v187
	v_fmac_f32_dpp v156, v148, v172 row_ror:1 row_mask:0xf bank_mask:0xf
	v_fmac_f32_dpp v157, v149, v173 row_ror:1 row_mask:0xf bank_mask:0xf
	v_fmac_f32_dpp v158, v150, v174 row_ror:1 row_mask:0xf bank_mask:0xf
	v_fmac_f32_dpp v159, v151, v175 row_ror:1 row_mask:0xf bank_mask:0xf
	v_fmac_f32_dpp v156, v152, v180 row_ror:15 row_mask:0xf bank_mask:0xf
	v_fmac_f32_dpp v157, v153, v181 row_ror:15 row_mask:0xf bank_mask:0xf
	v_fmac_f32_dpp v158, v154, v182 row_ror:15 row_mask:0xf bank_mask:0xf
	v_fmac_f32_dpp v159, v155, v183 row_ror:15 row_mask:0xf bank_mask:0xf
	v_cndmask_b32_e32 v148, v112, v208, vcc
	v_cndmask_b32_e32 v149, v113, v209, vcc
	v_cndmask_b32_e32 v150, v114, v210, vcc
	v_cndmask_b32_e32 v151, v115, v211, vcc
	v_cndmask_b32_e64 v152, v112, v100, s[98:99]
	v_cndmask_b32_e64 v153, v113, v101, s[98:99]
	v_cndmask_b32_e64 v154, v114, v102, s[98:99]
	v_cndmask_b32_e64 v155, v115, v103, s[98:99]
	v_fma_f32 v237, v192, v112, v200
	v_fma_f32 v238, v193, v113, v201
	v_fma_f32 v239, v194, v114, v202
	v_fma_f32 v240, v195, v115, v203
	v_fmac_f32_dpp v237, v148, v188 row_ror:1 row_mask:0xf bank_mask:0xf
	v_fmac_f32_dpp v238, v149, v189 row_ror:1 row_mask:0xf bank_mask:0xf
	v_fmac_f32_dpp v239, v150, v190 row_ror:1 row_mask:0xf bank_mask:0xf
	v_fmac_f32_dpp v240, v151, v191 row_ror:1 row_mask:0xf bank_mask:0xf
	v_fmac_f32_dpp v237, v152, v196 row_ror:15 row_mask:0xf bank_mask:0xf
	v_fmac_f32_dpp v238, v153, v197 row_ror:15 row_mask:0xf bank_mask:0xf
	v_fmac_f32_dpp v239, v154, v198 row_ror:15 row_mask:0xf bank_mask:0xf
	v_fmac_f32_dpp v240, v155, v199 row_ror:15 row_mask:0xf bank_mask:0xf
	v_mul_f32_e32 v148, 0xbfb8aa3b, v156
	v_mul_f32_e32 v149, 0xbfb8aa3b, v157
	v_mul_f32_e32 v150, 0xbfb8aa3b, v158
	v_mul_f32_e32 v151, 0xbfb8aa3b, v159
	v_exp_f32_e32 v148, v148
	v_exp_f32_e32 v149, v149
	v_exp_f32_e32 v150, v150
	v_exp_f32_e32 v151, v151
	v_add_f32_e32 v148, 1.0, v148
	v_add_f32_e32 v149, 1.0, v149
	v_add_f32_e32 v150, 1.0, v150
	v_add_f32_e32 v151, 1.0, v151
	v_rcp_f32_e32 v148, v148
	v_rcp_f32_e32 v149, v149
	v_rcp_f32_e32 v150, v150
	v_rcp_f32_e32 v151, v151
	v_mul_f32_e32 v156, v156, v148
	v_mul_f32_e32 v157, v157, v149
	v_mul_f32_e32 v158, v158, v150
	v_mul_f32_e32 v159, v159, v151
	v_mul_f32_e32 v156, v156, v237
	v_mul_f32_e32 v157, v157, v238
	v_mul_f32_e32 v158, v158, v239
	v_mul_f32_e32 v159, v159, v240
	v_cvt_pk_bf16_f32 v241, v156, v157
	v_cvt_pk_bf16_f32 v242, v158, v159
	ds_read_b128 v[204:207], v249 offset:4096
	ds_read_b128 v[208:211], v249 offset:4608
	v_cndmask_b32_e32 v148, v120, v124, vcc
	v_cndmask_b32_e32 v149, v121, v125, vcc
	v_cndmask_b32_e32 v150, v122, v126, vcc
	v_cndmask_b32_e32 v151, v123, v127, vcc
	v_cndmask_b32_e64 v152, v120, v116, s[98:99]
	v_cndmask_b32_e64 v153, v121, v117, s[98:99]
	v_cndmask_b32_e64 v154, v122, v118, s[98:99]
	v_cndmask_b32_e64 v155, v123, v119, s[98:99]
	v_fma_f32 v156, v176, v120, v184
	v_fma_f32 v157, v177, v121, v185
	v_fma_f32 v158, v178, v122, v186
	v_fma_f32 v159, v179, v123, v187
	v_fmac_f32_dpp v156, v148, v172 row_ror:1 row_mask:0xf bank_mask:0xf
	v_fmac_f32_dpp v157, v149, v173 row_ror:1 row_mask:0xf bank_mask:0xf
	v_fmac_f32_dpp v158, v150, v174 row_ror:1 row_mask:0xf bank_mask:0xf
	v_fmac_f32_dpp v159, v151, v175 row_ror:1 row_mask:0xf bank_mask:0xf
	v_fmac_f32_dpp v156, v152, v180 row_ror:15 row_mask:0xf bank_mask:0xf
	v_fmac_f32_dpp v157, v153, v181 row_ror:15 row_mask:0xf bank_mask:0xf
	v_fmac_f32_dpp v158, v154, v182 row_ror:15 row_mask:0xf bank_mask:0xf
	v_fmac_f32_dpp v159, v155, v183 row_ror:15 row_mask:0xf bank_mask:0xf
	v_cndmask_b32_e32 v148, v100, v112, vcc
	v_cndmask_b32_e32 v149, v101, v113, vcc
	v_cndmask_b32_e32 v150, v102, v114, vcc
	v_cndmask_b32_e32 v151, v103, v115, vcc
	v_cndmask_b32_e64 v152, v100, v92, s[98:99]
	v_cndmask_b32_e64 v153, v101, v93, s[98:99]
	v_cndmask_b32_e64 v154, v102, v94, s[98:99]
	v_cndmask_b32_e64 v155, v103, v95, s[98:99]
	v_fma_f32 v237, v192, v100, v200
	v_fma_f32 v238, v193, v101, v201
	v_fma_f32 v239, v194, v102, v202
	v_fma_f32 v240, v195, v103, v203
	v_fmac_f32_dpp v237, v148, v188 row_ror:1 row_mask:0xf bank_mask:0xf
	v_fmac_f32_dpp v238, v149, v189 row_ror:1 row_mask:0xf bank_mask:0xf
	v_fmac_f32_dpp v239, v150, v190 row_ror:1 row_mask:0xf bank_mask:0xf
	v_fmac_f32_dpp v240, v151, v191 row_ror:1 row_mask:0xf bank_mask:0xf
	v_fmac_f32_dpp v237, v152, v196 row_ror:15 row_mask:0xf bank_mask:0xf
	v_fmac_f32_dpp v238, v153, v197 row_ror:15 row_mask:0xf bank_mask:0xf
	v_fmac_f32_dpp v239, v154, v198 row_ror:15 row_mask:0xf bank_mask:0xf
	v_fmac_f32_dpp v240, v155, v199 row_ror:15 row_mask:0xf bank_mask:0xf
	v_mul_f32_e32 v148, 0xbfb8aa3b, v156
	v_mul_f32_e32 v149, 0xbfb8aa3b, v157
	v_mul_f32_e32 v150, 0xbfb8aa3b, v158
	v_mul_f32_e32 v151, 0xbfb8aa3b, v159
	v_exp_f32_e32 v148, v148
	v_exp_f32_e32 v149, v149
	v_exp_f32_e32 v150, v150
	v_exp_f32_e32 v151, v151
	v_add_f32_e32 v148, 1.0, v148
	v_add_f32_e32 v149, 1.0, v149
	v_add_f32_e32 v150, 1.0, v150
	v_add_f32_e32 v151, 1.0, v151
	v_rcp_f32_e32 v148, v148
	v_rcp_f32_e32 v149, v149
	v_rcp_f32_e32 v150, v150
	v_rcp_f32_e32 v151, v151
	v_mul_f32_e32 v156, v156, v148
	v_mul_f32_e32 v157, v157, v149
	v_mul_f32_e32 v158, v158, v150
	v_mul_f32_e32 v159, v159, v151
	v_mul_f32_e32 v156, v156, v237
	v_mul_f32_e32 v157, v157, v238
	v_mul_f32_e32 v158, v158, v239
	v_mul_f32_e32 v159, v159, v240
	v_cvt_pk_bf16_f32 v243, v156, v157
	v_cvt_pk_bf16_f32 v244, v158, v159
	v_cndmask_b32_e32 v148, v116, v120, vcc
	v_cndmask_b32_e32 v149, v117, v121, vcc
	v_cndmask_b32_e32 v150, v118, v122, vcc
	v_cndmask_b32_e32 v151, v119, v123, vcc
	v_cndmask_b32_e64 v152, v116, v104, s[98:99]
	v_cndmask_b32_e64 v153, v117, v105, s[98:99]
	v_cndmask_b32_e64 v154, v118, v106, s[98:99]
	v_cndmask_b32_e64 v155, v119, v107, s[98:99]
	v_fma_f32 v156, v176, v116, v184
	v_fma_f32 v157, v177, v117, v185
	v_fma_f32 v158, v178, v118, v186
	v_fma_f32 v159, v179, v119, v187
	v_fmac_f32_dpp v156, v148, v172 row_ror:1 row_mask:0xf bank_mask:0xf
	v_fmac_f32_dpp v157, v149, v173 row_ror:1 row_mask:0xf bank_mask:0xf
	v_fmac_f32_dpp v158, v150, v174 row_ror:1 row_mask:0xf bank_mask:0xf
	v_fmac_f32_dpp v159, v151, v175 row_ror:1 row_mask:0xf bank_mask:0xf
	v_fmac_f32_dpp v156, v152, v180 row_ror:15 row_mask:0xf bank_mask:0xf
	v_fmac_f32_dpp v157, v153, v181 row_ror:15 row_mask:0xf bank_mask:0xf
	v_fmac_f32_dpp v158, v154, v182 row_ror:15 row_mask:0xf bank_mask:0xf
	v_fmac_f32_dpp v159, v155, v183 row_ror:15 row_mask:0xf bank_mask:0xf
	v_cndmask_b32_e32 v148, v92, v100, vcc
	v_cndmask_b32_e32 v149, v93, v101, vcc
	v_cndmask_b32_e32 v150, v94, v102, vcc
	v_cndmask_b32_e32 v151, v95, v103, vcc
	v_cndmask_b32_e64 v152, v92, v80, s[98:99]
	v_cndmask_b32_e64 v153, v93, v81, s[98:99]
	v_cndmask_b32_e64 v154, v94, v82, s[98:99]
	v_cndmask_b32_e64 v155, v95, v83, s[98:99]
	v_fma_f32 v237, v192, v92, v200
	v_fma_f32 v238, v193, v93, v201
	v_fma_f32 v239, v194, v94, v202
	v_fma_f32 v240, v195, v95, v203
	v_fmac_f32_dpp v237, v148, v188 row_ror:1 row_mask:0xf bank_mask:0xf
	v_fmac_f32_dpp v238, v149, v189 row_ror:1 row_mask:0xf bank_mask:0xf
	v_fmac_f32_dpp v239, v150, v190 row_ror:1 row_mask:0xf bank_mask:0xf
	v_fmac_f32_dpp v240, v151, v191 row_ror:1 row_mask:0xf bank_mask:0xf
	v_fmac_f32_dpp v237, v152, v196 row_ror:15 row_mask:0xf bank_mask:0xf
	v_fmac_f32_dpp v238, v153, v197 row_ror:15 row_mask:0xf bank_mask:0xf
	v_fmac_f32_dpp v239, v154, v198 row_ror:15 row_mask:0xf bank_mask:0xf
	v_fmac_f32_dpp v240, v155, v199 row_ror:15 row_mask:0xf bank_mask:0xf
	v_mul_f32_e32 v148, 0xbfb8aa3b, v156
	v_mul_f32_e32 v149, 0xbfb8aa3b, v157
	v_mul_f32_e32 v150, 0xbfb8aa3b, v158
	v_mul_f32_e32 v151, 0xbfb8aa3b, v159
	v_exp_f32_e32 v148, v148
	v_exp_f32_e32 v149, v149
	v_exp_f32_e32 v150, v150
	v_exp_f32_e32 v151, v151
	v_add_f32_e32 v148, 1.0, v148
	v_add_f32_e32 v149, 1.0, v149
	v_add_f32_e32 v150, 1.0, v150
	v_add_f32_e32 v151, 1.0, v151
	v_rcp_f32_e32 v148, v148
	v_rcp_f32_e32 v149, v149
	v_rcp_f32_e32 v150, v150
	v_rcp_f32_e32 v151, v151
	v_mul_f32_e32 v156, v156, v148
	v_mul_f32_e32 v157, v157, v149
	v_mul_f32_e32 v158, v158, v150
	v_mul_f32_e32 v159, v159, v151
	v_mul_f32_e32 v156, v156, v237
	v_mul_f32_e32 v157, v157, v238
	v_mul_f32_e32 v158, v158, v239
	v_mul_f32_e32 v159, v159, v240
	v_cvt_pk_bf16_f32 v253, v156, v157
	v_cvt_pk_bf16_f32 v254, v158, v159
	v_cndmask_b32_e32 v148, v104, v116, vcc
	v_cndmask_b32_e32 v149, v105, v117, vcc
	v_cndmask_b32_e32 v150, v106, v118, vcc
	v_cndmask_b32_e32 v151, v107, v119, vcc
	v_cndmask_b32_e64 v152, v104, v160, s[98:99]
	v_cndmask_b32_e64 v153, v105, v161, s[98:99]
	v_cndmask_b32_e64 v154, v106, v162, s[98:99]
	v_cndmask_b32_e64 v155, v107, v163, s[98:99]
	v_fma_f32 v156, v176, v104, v184
	v_fma_f32 v157, v177, v105, v185
	v_fma_f32 v158, v178, v106, v186
	v_fma_f32 v159, v179, v107, v187
	v_fmac_f32_dpp v156, v148, v172 row_ror:1 row_mask:0xf bank_mask:0xf
	v_fmac_f32_dpp v157, v149, v173 row_ror:1 row_mask:0xf bank_mask:0xf
	v_fmac_f32_dpp v158, v150, v174 row_ror:1 row_mask:0xf bank_mask:0xf
	v_fmac_f32_dpp v159, v151, v175 row_ror:1 row_mask:0xf bank_mask:0xf
	v_fmac_f32_dpp v156, v152, v180 row_ror:15 row_mask:0xf bank_mask:0xf
	v_fmac_f32_dpp v157, v153, v181 row_ror:15 row_mask:0xf bank_mask:0xf
	v_fmac_f32_dpp v158, v154, v182 row_ror:15 row_mask:0xf bank_mask:0xf
	v_fmac_f32_dpp v159, v155, v183 row_ror:15 row_mask:0xf bank_mask:0xf
	v_cndmask_b32_e32 v148, v80, v92, vcc
	v_cndmask_b32_e32 v149, v81, v93, vcc
	v_cndmask_b32_e32 v150, v82, v94, vcc
	v_cndmask_b32_e32 v151, v83, v95, vcc
	v_cndmask_b32_e64 v152, v80, v164, s[98:99]
	v_cndmask_b32_e64 v153, v81, v165, s[98:99]
	v_cndmask_b32_e64 v154, v82, v166, s[98:99]
	v_cndmask_b32_e64 v155, v83, v167, s[98:99]
	v_fma_f32 v237, v192, v80, v200
	v_fma_f32 v238, v193, v81, v201
	v_fma_f32 v239, v194, v82, v202
	v_fma_f32 v240, v195, v83, v203
	v_fmac_f32_dpp v237, v148, v188 row_ror:1 row_mask:0xf bank_mask:0xf
	v_fmac_f32_dpp v238, v149, v189 row_ror:1 row_mask:0xf bank_mask:0xf
	v_fmac_f32_dpp v239, v150, v190 row_ror:1 row_mask:0xf bank_mask:0xf
	v_fmac_f32_dpp v240, v151, v191 row_ror:1 row_mask:0xf bank_mask:0xf
	v_fmac_f32_dpp v237, v152, v196 row_ror:15 row_mask:0xf bank_mask:0xf
	v_fmac_f32_dpp v238, v153, v197 row_ror:15 row_mask:0xf bank_mask:0xf
	v_fmac_f32_dpp v239, v154, v198 row_ror:15 row_mask:0xf bank_mask:0xf
	v_fmac_f32_dpp v240, v155, v199 row_ror:15 row_mask:0xf bank_mask:0xf
	v_mul_f32_e32 v148, 0xbfb8aa3b, v156
	v_mul_f32_e32 v149, 0xbfb8aa3b, v157
	v_mul_f32_e32 v150, 0xbfb8aa3b, v158
	v_mul_f32_e32 v151, 0xbfb8aa3b, v159
	v_exp_f32_e32 v148, v148
	v_exp_f32_e32 v149, v149
	v_exp_f32_e32 v150, v150
	v_exp_f32_e32 v151, v151
	v_add_f32_e32 v148, 1.0, v148
	v_add_f32_e32 v149, 1.0, v149
	v_add_f32_e32 v150, 1.0, v150
	v_add_f32_e32 v151, 1.0, v151
	v_rcp_f32_e32 v148, v148
	v_rcp_f32_e32 v149, v149
	v_rcp_f32_e32 v150, v150
	v_rcp_f32_e32 v151, v151
	v_mul_f32_e32 v156, v156, v148
	v_mul_f32_e32 v157, v157, v149
	v_mul_f32_e32 v158, v158, v150
	v_mul_f32_e32 v159, v159, v151
	v_mul_f32_e32 v156, v156, v237
	v_mul_f32_e32 v157, v157, v238
	v_mul_f32_e32 v158, v158, v239
	v_mul_f32_e32 v159, v159, v240
	v_cvt_pk_bf16_f32 v255, v156, v157
	v_cvt_pk_bf16_f32 v246, v158, v159
	global_load_dwordx4 v[124:127], v146, s[14:15] offset:64
	global_load_dwordx4 v[120:123], v147, s[14:15] offset:64
	global_load_dwordx4 v[116:119], v168, s[14:15] offset:64
	global_load_dwordx4 v[112:115], v169, s[14:15] offset:64
	global_load_dwordx4 v[100:103], v245, s[14:15] offset:64
	global_load_dwordx4 v[92:95], v252, s[14:15] offset:64
	global_load_dwordx4 v[104:107], v146, s[16:17] offset:64
	global_load_dwordx4 v[80:83], v169, s[16:17] offset:64
	ds_read_b128 v[160:163], v249 offset:7168
	ds_read_b128 v[164:167], v249 offset:7680
	s_waitcnt lgkmcnt(2)
	v_cndmask_b32_e32 v148, v72, v204, vcc
	v_cndmask_b32_e32 v149, v73, v205, vcc
	v_cndmask_b32_e32 v150, v74, v206, vcc
	v_cndmask_b32_e32 v151, v75, v207, vcc
	v_cndmask_b32_e64 v152, v72, v64, s[98:99]
	v_cndmask_b32_e64 v153, v73, v65, s[98:99]
	v_cndmask_b32_e64 v154, v74, v66, s[98:99]
	v_cndmask_b32_e64 v155, v75, v67, s[98:99]
	v_fma_f32 v156, v176, v72, v184
	v_fma_f32 v157, v177, v73, v185
	v_fma_f32 v158, v178, v74, v186
	v_fma_f32 v159, v179, v75, v187
	v_fmac_f32_dpp v156, v148, v172 row_ror:1 row_mask:0xf bank_mask:0xf
	v_fmac_f32_dpp v157, v149, v173 row_ror:1 row_mask:0xf bank_mask:0xf
	v_fmac_f32_dpp v158, v150, v174 row_ror:1 row_mask:0xf bank_mask:0xf
	v_fmac_f32_dpp v159, v151, v175 row_ror:1 row_mask:0xf bank_mask:0xf
	v_fmac_f32_dpp v156, v152, v180 row_ror:15 row_mask:0xf bank_mask:0xf
	v_fmac_f32_dpp v157, v153, v181 row_ror:15 row_mask:0xf bank_mask:0xf
	v_fmac_f32_dpp v158, v154, v182 row_ror:15 row_mask:0xf bank_mask:0xf
	v_fmac_f32_dpp v159, v155, v183 row_ror:15 row_mask:0xf bank_mask:0xf
	v_cndmask_b32_e32 v148, v48, v208, vcc
	v_cndmask_b32_e32 v149, v49, v209, vcc
	v_cndmask_b32_e32 v150, v50, v210, vcc
	v_cndmask_b32_e32 v151, v51, v211, vcc
	v_cndmask_b32_e64 v152, v48, v36, s[98:99]
	v_cndmask_b32_e64 v153, v49, v37, s[98:99]
	v_cndmask_b32_e64 v154, v50, v38, s[98:99]
	v_cndmask_b32_e64 v155, v51, v39, s[98:99]
	v_fma_f32 v237, v192, v48, v200
	v_fma_f32 v238, v193, v49, v201
	v_fma_f32 v239, v194, v50, v202
	v_fma_f32 v240, v195, v51, v203
	v_fmac_f32_dpp v237, v148, v188 row_ror:1 row_mask:0xf bank_mask:0xf
	v_fmac_f32_dpp v238, v149, v189 row_ror:1 row_mask:0xf bank_mask:0xf
	v_fmac_f32_dpp v239, v150, v190 row_ror:1 row_mask:0xf bank_mask:0xf
	v_fmac_f32_dpp v240, v151, v191 row_ror:1 row_mask:0xf bank_mask:0xf
	v_fmac_f32_dpp v237, v152, v196 row_ror:15 row_mask:0xf bank_mask:0xf
	v_fmac_f32_dpp v238, v153, v197 row_ror:15 row_mask:0xf bank_mask:0xf
	v_fmac_f32_dpp v239, v154, v198 row_ror:15 row_mask:0xf bank_mask:0xf
	v_fmac_f32_dpp v240, v155, v199 row_ror:15 row_mask:0xf bank_mask:0xf
	v_mul_f32_e32 v148, 0xbfb8aa3b, v156
	v_mul_f32_e32 v149, 0xbfb8aa3b, v157
	v_mul_f32_e32 v150, 0xbfb8aa3b, v158
	v_mul_f32_e32 v151, 0xbfb8aa3b, v159
	v_exp_f32_e32 v148, v148
	v_exp_f32_e32 v149, v149
	v_exp_f32_e32 v150, v150
	v_exp_f32_e32 v151, v151
	v_add_f32_e32 v148, 1.0, v148
	v_add_f32_e32 v149, 1.0, v149
	v_add_f32_e32 v150, 1.0, v150
	v_add_f32_e32 v151, 1.0, v151
	v_rcp_f32_e32 v148, v148
	v_rcp_f32_e32 v149, v149
	v_rcp_f32_e32 v150, v150
	v_rcp_f32_e32 v151, v151
	v_mul_f32_e32 v156, v156, v148
	v_mul_f32_e32 v157, v157, v149
	v_mul_f32_e32 v158, v158, v150
	v_mul_f32_e32 v159, v159, v151
	v_mul_f32_e32 v156, v156, v237
	v_mul_f32_e32 v157, v157, v238
	v_mul_f32_e32 v158, v158, v239
	v_mul_f32_e32 v159, v159, v240
	v_cvt_pk_bf16_f32 v247, v156, v157
	v_cvt_pk_bf16_f32 v248, v158, v159
	ds_read_b128 v[204:207], v249 offset:64
	ds_read_b128 v[208:211], v249 offset:576
	v_cndmask_b32_e32 v148, v64, v72, vcc
	v_cndmask_b32_e32 v149, v65, v73, vcc
	v_cndmask_b32_e32 v150, v66, v74, vcc
	v_cndmask_b32_e32 v151, v67, v75, vcc
	v_cndmask_b32_e64 v152, v64, v56, s[98:99]
	v_cndmask_b32_e64 v153, v65, v57, s[98:99]
	v_cndmask_b32_e64 v154, v66, v58, s[98:99]
	v_cndmask_b32_e64 v155, v67, v59, s[98:99]
	v_fma_f32 v156, v176, v64, v184
	v_fma_f32 v157, v177, v65, v185
	v_fma_f32 v158, v178, v66, v186
	v_fma_f32 v159, v179, v67, v187
	v_fmac_f32_dpp v156, v148, v172 row_ror:1 row_mask:0xf bank_mask:0xf
	v_fmac_f32_dpp v157, v149, v173 row_ror:1 row_mask:0xf bank_mask:0xf
	v_fmac_f32_dpp v158, v150, v174 row_ror:1 row_mask:0xf bank_mask:0xf
	v_fmac_f32_dpp v159, v151, v175 row_ror:1 row_mask:0xf bank_mask:0xf
	v_fmac_f32_dpp v156, v152, v180 row_ror:15 row_mask:0xf bank_mask:0xf
	v_fmac_f32_dpp v157, v153, v181 row_ror:15 row_mask:0xf bank_mask:0xf
	v_fmac_f32_dpp v158, v154, v182 row_ror:15 row_mask:0xf bank_mask:0xf
	v_fmac_f32_dpp v159, v155, v183 row_ror:15 row_mask:0xf bank_mask:0xf
	v_cndmask_b32_e32 v148, v36, v48, vcc
	v_cndmask_b32_e32 v149, v37, v49, vcc
	v_cndmask_b32_e32 v150, v38, v50, vcc
	v_cndmask_b32_e32 v151, v39, v51, vcc
	v_cndmask_b32_e64 v152, v36, v28, s[98:99]
	v_cndmask_b32_e64 v153, v37, v29, s[98:99]
	v_cndmask_b32_e64 v154, v38, v30, s[98:99]
	v_cndmask_b32_e64 v155, v39, v31, s[98:99]
	v_fma_f32 v237, v192, v36, v200
	v_fma_f32 v238, v193, v37, v201
	v_fma_f32 v239, v194, v38, v202
	v_fma_f32 v240, v195, v39, v203
	v_fmac_f32_dpp v237, v148, v188 row_ror:1 row_mask:0xf bank_mask:0xf
	v_fmac_f32_dpp v238, v149, v189 row_ror:1 row_mask:0xf bank_mask:0xf
	v_fmac_f32_dpp v239, v150, v190 row_ror:1 row_mask:0xf bank_mask:0xf
	v_fmac_f32_dpp v240, v151, v191 row_ror:1 row_mask:0xf bank_mask:0xf
	v_fmac_f32_dpp v237, v152, v196 row_ror:15 row_mask:0xf bank_mask:0xf
	v_fmac_f32_dpp v238, v153, v197 row_ror:15 row_mask:0xf bank_mask:0xf
	v_fmac_f32_dpp v239, v154, v198 row_ror:15 row_mask:0xf bank_mask:0xf
	v_fmac_f32_dpp v240, v155, v199 row_ror:15 row_mask:0xf bank_mask:0xf
	v_mul_f32_e32 v148, 0xbfb8aa3b, v156
	v_mul_f32_e32 v149, 0xbfb8aa3b, v157
	v_mul_f32_e32 v150, 0xbfb8aa3b, v158
	v_mul_f32_e32 v151, 0xbfb8aa3b, v159
	v_exp_f32_e32 v148, v148
	v_exp_f32_e32 v149, v149
	v_exp_f32_e32 v150, v150
	v_exp_f32_e32 v151, v151
	v_add_f32_e32 v148, 1.0, v148
	v_add_f32_e32 v149, 1.0, v149
	v_add_f32_e32 v150, 1.0, v150
	v_add_f32_e32 v151, 1.0, v151
	v_rcp_f32_e32 v148, v148
	v_rcp_f32_e32 v149, v149
	v_rcp_f32_e32 v150, v150
	v_rcp_f32_e32 v151, v151
	v_mul_f32_e32 v156, v156, v148
	v_mul_f32_e32 v157, v157, v149
	v_mul_f32_e32 v158, v158, v150
	v_mul_f32_e32 v159, v159, v151
	v_mul_f32_e32 v156, v156, v237
	v_mul_f32_e32 v157, v157, v238
	v_mul_f32_e32 v158, v158, v239
	v_mul_f32_e32 v159, v159, v240
	v_cvt_pk_bf16_f32 v72, v156, v157
	v_cvt_pk_bf16_f32 v73, v158, v159
	v_cndmask_b32_e32 v148, v56, v64, vcc
	v_cndmask_b32_e32 v149, v57, v65, vcc
	v_cndmask_b32_e32 v150, v58, v66, vcc
	v_cndmask_b32_e32 v151, v59, v67, vcc
	v_cndmask_b32_e64 v152, v56, v40, s[98:99]
	v_cndmask_b32_e64 v153, v57, v41, s[98:99]
	v_cndmask_b32_e64 v154, v58, v42, s[98:99]
	v_cndmask_b32_e64 v155, v59, v43, s[98:99]
	v_fma_f32 v156, v176, v56, v184
	v_fma_f32 v157, v177, v57, v185
	v_fma_f32 v158, v178, v58, v186
	v_fma_f32 v159, v179, v59, v187
	v_fmac_f32_dpp v156, v148, v172 row_ror:1 row_mask:0xf bank_mask:0xf
	v_fmac_f32_dpp v157, v149, v173 row_ror:1 row_mask:0xf bank_mask:0xf
	v_fmac_f32_dpp v158, v150, v174 row_ror:1 row_mask:0xf bank_mask:0xf
	v_fmac_f32_dpp v159, v151, v175 row_ror:1 row_mask:0xf bank_mask:0xf
	v_fmac_f32_dpp v156, v152, v180 row_ror:15 row_mask:0xf bank_mask:0xf
	v_fmac_f32_dpp v157, v153, v181 row_ror:15 row_mask:0xf bank_mask:0xf
	v_fmac_f32_dpp v158, v154, v182 row_ror:15 row_mask:0xf bank_mask:0xf
	v_fmac_f32_dpp v159, v155, v183 row_ror:15 row_mask:0xf bank_mask:0xf
	v_cndmask_b32_e32 v148, v28, v36, vcc
	v_cndmask_b32_e32 v149, v29, v37, vcc
	v_cndmask_b32_e32 v150, v30, v38, vcc
	v_cndmask_b32_e32 v151, v31, v39, vcc
	v_cndmask_b32_e64 v152, v28, v16, s[98:99]
	v_cndmask_b32_e64 v153, v29, v17, s[98:99]
	v_cndmask_b32_e64 v154, v30, v18, s[98:99]
	v_cndmask_b32_e64 v155, v31, v19, s[98:99]
	v_fma_f32 v237, v192, v28, v200
	v_fma_f32 v238, v193, v29, v201
	v_fma_f32 v239, v194, v30, v202
	v_fma_f32 v240, v195, v31, v203
	v_fmac_f32_dpp v237, v148, v188 row_ror:1 row_mask:0xf bank_mask:0xf
	v_fmac_f32_dpp v238, v149, v189 row_ror:1 row_mask:0xf bank_mask:0xf
	v_fmac_f32_dpp v239, v150, v190 row_ror:1 row_mask:0xf bank_mask:0xf
	v_fmac_f32_dpp v240, v151, v191 row_ror:1 row_mask:0xf bank_mask:0xf
	v_fmac_f32_dpp v237, v152, v196 row_ror:15 row_mask:0xf bank_mask:0xf
	v_fmac_f32_dpp v238, v153, v197 row_ror:15 row_mask:0xf bank_mask:0xf
	v_fmac_f32_dpp v239, v154, v198 row_ror:15 row_mask:0xf bank_mask:0xf
	v_fmac_f32_dpp v240, v155, v199 row_ror:15 row_mask:0xf bank_mask:0xf
	v_mul_f32_e32 v148, 0xbfb8aa3b, v156
	v_mul_f32_e32 v149, 0xbfb8aa3b, v157
	v_mul_f32_e32 v150, 0xbfb8aa3b, v158
	v_mul_f32_e32 v151, 0xbfb8aa3b, v159
	v_exp_f32_e32 v148, v148
	v_exp_f32_e32 v149, v149
	v_exp_f32_e32 v150, v150
	v_exp_f32_e32 v151, v151
	v_add_f32_e32 v148, 1.0, v148
	v_add_f32_e32 v149, 1.0, v149
	v_add_f32_e32 v150, 1.0, v150
	v_add_f32_e32 v151, 1.0, v151
	v_rcp_f32_e32 v148, v148
	v_rcp_f32_e32 v149, v149
	v_rcp_f32_e32 v150, v150
	v_rcp_f32_e32 v151, v151
	v_mul_f32_e32 v156, v156, v148
	v_mul_f32_e32 v157, v157, v149
	v_mul_f32_e32 v158, v158, v150
	v_mul_f32_e32 v159, v159, v151
	v_mul_f32_e32 v156, v156, v237
	v_mul_f32_e32 v157, v157, v238
	v_mul_f32_e32 v158, v158, v239
	v_mul_f32_e32 v159, v159, v240
	v_cvt_pk_bf16_f32 v74, v156, v157
	v_cvt_pk_bf16_f32 v75, v158, v159
	s_waitcnt lgkmcnt(2)
	v_cndmask_b32_e32 v148, v40, v56, vcc
	v_cndmask_b32_e32 v149, v41, v57, vcc
	v_cndmask_b32_e32 v150, v42, v58, vcc
	v_cndmask_b32_e32 v151, v43, v59, vcc
	v_cndmask_b32_e64 v152, v40, v160, s[98:99]
	v_cndmask_b32_e64 v153, v41, v161, s[98:99]
	v_cndmask_b32_e64 v154, v42, v162, s[98:99]
	v_cndmask_b32_e64 v155, v43, v163, s[98:99]
	v_fma_f32 v156, v176, v40, v184
	v_fma_f32 v157, v177, v41, v185
	v_fma_f32 v158, v178, v42, v186
	v_fma_f32 v159, v179, v43, v187
	v_fmac_f32_dpp v156, v148, v172 row_ror:1 row_mask:0xf bank_mask:0xf
	v_fmac_f32_dpp v157, v149, v173 row_ror:1 row_mask:0xf bank_mask:0xf
	v_fmac_f32_dpp v158, v150, v174 row_ror:1 row_mask:0xf bank_mask:0xf
	v_fmac_f32_dpp v159, v151, v175 row_ror:1 row_mask:0xf bank_mask:0xf
	v_fmac_f32_dpp v156, v152, v180 row_ror:15 row_mask:0xf bank_mask:0xf
	v_fmac_f32_dpp v157, v153, v181 row_ror:15 row_mask:0xf bank_mask:0xf
	v_fmac_f32_dpp v158, v154, v182 row_ror:15 row_mask:0xf bank_mask:0xf
	v_fmac_f32_dpp v159, v155, v183 row_ror:15 row_mask:0xf bank_mask:0xf
	v_cndmask_b32_e32 v148, v16, v28, vcc
	v_cndmask_b32_e32 v149, v17, v29, vcc
	v_cndmask_b32_e32 v150, v18, v30, vcc
	v_cndmask_b32_e32 v151, v19, v31, vcc
	v_cndmask_b32_e64 v152, v16, v164, s[98:99]
	v_cndmask_b32_e64 v153, v17, v165, s[98:99]
	v_cndmask_b32_e64 v154, v18, v166, s[98:99]
	v_cndmask_b32_e64 v155, v19, v167, s[98:99]
	v_fma_f32 v237, v192, v16, v200
	v_fma_f32 v238, v193, v17, v201
	v_fma_f32 v239, v194, v18, v202
	v_fma_f32 v240, v195, v19, v203
	v_fmac_f32_dpp v237, v148, v188 row_ror:1 row_mask:0xf bank_mask:0xf
	v_fmac_f32_dpp v238, v149, v189 row_ror:1 row_mask:0xf bank_mask:0xf
	v_fmac_f32_dpp v239, v150, v190 row_ror:1 row_mask:0xf bank_mask:0xf
	v_fmac_f32_dpp v240, v151, v191 row_ror:1 row_mask:0xf bank_mask:0xf
	v_fmac_f32_dpp v237, v152, v196 row_ror:15 row_mask:0xf bank_mask:0xf
	v_fmac_f32_dpp v238, v153, v197 row_ror:15 row_mask:0xf bank_mask:0xf
	v_fmac_f32_dpp v239, v154, v198 row_ror:15 row_mask:0xf bank_mask:0xf
	v_fmac_f32_dpp v240, v155, v199 row_ror:15 row_mask:0xf bank_mask:0xf
	v_mul_f32_e32 v148, 0xbfb8aa3b, v156
	v_mul_f32_e32 v149, 0xbfb8aa3b, v157
	v_mul_f32_e32 v150, 0xbfb8aa3b, v158
	v_mul_f32_e32 v151, 0xbfb8aa3b, v159
	v_exp_f32_e32 v148, v148
	v_exp_f32_e32 v149, v149
	v_exp_f32_e32 v150, v150
	v_exp_f32_e32 v151, v151
	v_add_f32_e32 v148, 1.0, v148
	v_add_f32_e32 v149, 1.0, v149
	v_add_f32_e32 v150, 1.0, v150
	v_add_f32_e32 v151, 1.0, v151
	v_rcp_f32_e32 v148, v148
	v_rcp_f32_e32 v149, v149
	v_rcp_f32_e32 v150, v150
	v_rcp_f32_e32 v151, v151
	v_mul_f32_e32 v156, v156, v148
	v_mul_f32_e32 v157, v157, v149
	v_mul_f32_e32 v158, v158, v150
	v_mul_f32_e32 v159, v159, v151
	v_mul_f32_e32 v156, v156, v237
	v_mul_f32_e32 v157, v157, v238
	v_mul_f32_e32 v158, v158, v239
	v_mul_f32_e32 v159, v159, v240
	v_cvt_pk_bf16_f32 v48, v156, v157
	v_cvt_pk_bf16_f32 v49, v158, v159
	ds_read_b128 v[160:163], v249 offset:3136
	ds_read_b128 v[164:167], v249 offset:3648
	s_waitcnt vmcnt(0) lgkmcnt(0)
	v_mbcnt_lo_u32_b32 v146, -1, 0
	v_mbcnt_hi_u32_b32 v146, -1, v146
	v_bfe_i32 v146, v146, 4, 1
	v_cndmask_b32_e32 v148, v108, v204, vcc
	v_cndmask_b32_e32 v149, v109, v205, vcc
	v_cndmask_b32_e32 v150, v110, v206, vcc
	v_cndmask_b32_e32 v151, v111, v207, vcc
	v_cndmask_b32_e64 v152, v108, v96, s[98:99]
	v_cndmask_b32_e64 v153, v109, v97, s[98:99]
	v_cndmask_b32_e64 v154, v110, v98, s[98:99]
	v_cndmask_b32_e64 v155, v111, v99, s[98:99]
	v_fma_f32 v156, v120, v108, v104
	v_fma_f32 v157, v121, v109, v105
	v_fma_f32 v158, v122, v110, v106
	v_fma_f32 v159, v123, v111, v107
	v_fmac_f32_dpp v156, v148, v124 row_ror:1 row_mask:0xf bank_mask:0xf
	v_fmac_f32_dpp v157, v149, v125 row_ror:1 row_mask:0xf bank_mask:0xf
	v_fmac_f32_dpp v158, v150, v126 row_ror:1 row_mask:0xf bank_mask:0xf
	v_fmac_f32_dpp v159, v151, v127 row_ror:1 row_mask:0xf bank_mask:0xf
	v_fmac_f32_dpp v156, v152, v116 row_ror:15 row_mask:0xf bank_mask:0xf
	v_fmac_f32_dpp v157, v153, v117 row_ror:15 row_mask:0xf bank_mask:0xf
	v_fmac_f32_dpp v158, v154, v118 row_ror:15 row_mask:0xf bank_mask:0xf
	v_fmac_f32_dpp v159, v155, v119 row_ror:15 row_mask:0xf bank_mask:0xf
	v_cndmask_b32_e32 v148, v84, v208, vcc
	v_cndmask_b32_e32 v149, v85, v209, vcc
	v_cndmask_b32_e32 v150, v86, v210, vcc
	v_cndmask_b32_e32 v151, v87, v211, vcc
	v_cndmask_b32_e64 v152, v84, v68, s[98:99]
	v_cndmask_b32_e64 v153, v85, v69, s[98:99]
	v_cndmask_b32_e64 v154, v86, v70, s[98:99]
	v_cndmask_b32_e64 v155, v87, v71, s[98:99]
	v_fma_f32 v237, v100, v84, v80
	v_fma_f32 v238, v101, v85, v81
	v_fma_f32 v239, v102, v86, v82
	v_fma_f32 v240, v103, v87, v83
	v_fmac_f32_dpp v237, v148, v112 row_ror:1 row_mask:0xf bank_mask:0xf
	v_fmac_f32_dpp v238, v149, v113 row_ror:1 row_mask:0xf bank_mask:0xf
	v_fmac_f32_dpp v239, v150, v114 row_ror:1 row_mask:0xf bank_mask:0xf
	v_fmac_f32_dpp v240, v151, v115 row_ror:1 row_mask:0xf bank_mask:0xf
	v_fmac_f32_dpp v237, v152, v92 row_ror:15 row_mask:0xf bank_mask:0xf
	v_fmac_f32_dpp v238, v153, v93 row_ror:15 row_mask:0xf bank_mask:0xf
	v_fmac_f32_dpp v239, v154, v94 row_ror:15 row_mask:0xf bank_mask:0xf
	v_fmac_f32_dpp v240, v155, v95 row_ror:15 row_mask:0xf bank_mask:0xf
	v_mul_f32_e32 v148, 0xbfb8aa3b, v156
	v_mul_f32_e32 v149, 0xbfb8aa3b, v157
	v_mul_f32_e32 v150, 0xbfb8aa3b, v158
	v_mul_f32_e32 v151, 0xbfb8aa3b, v159
	v_exp_f32_e32 v148, v148
	v_exp_f32_e32 v149, v149
	v_exp_f32_e32 v150, v150
	v_exp_f32_e32 v151, v151
	v_add_f32_e32 v148, 1.0, v148
	v_add_f32_e32 v149, 1.0, v149
	v_add_f32_e32 v150, 1.0, v150
	v_add_f32_e32 v151, 1.0, v151
	v_rcp_f32_e32 v148, v148
	v_rcp_f32_e32 v149, v149
	v_rcp_f32_e32 v150, v150
	v_rcp_f32_e32 v151, v151
	v_mul_f32_e32 v156, v156, v148
	v_mul_f32_e32 v157, v157, v149
	v_mul_f32_e32 v158, v158, v150
	v_mul_f32_e32 v159, v159, v151
	v_mul_f32_e32 v156, v156, v237
	v_mul_f32_e32 v157, v157, v238
	v_mul_f32_e32 v158, v158, v239
	v_mul_f32_e32 v159, v159, v240
	v_cvt_pk_bf16_f32 v40, v156, v157
	v_cvt_pk_bf16_f32 v41, v158, v159
	v_bfi_b32 v18, v146, v241, v40
	v_bfi_b32 v19, v146, v242, v41
	ds_swizzle_b32 v16, v18 offset:0x401f
	ds_swizzle_b32 v17, v19 offset:0x401f
	v_mov_b32_e32 v42, v250
	v_lshrrev_b32_e32 v152, 6, v251
	s_nop 1
	v_readfirstlane_b32 s100, v152
	s_waitcnt lgkmcnt(0)
	v_bfi_b32 v148, v146, v16, v241
	v_bfi_b32 v149, v146, v17, v242
	v_bfi_b32 v150, v146, v40, v16
	v_bfi_b32 v151, v146, v41, v17
	s_cmp_eq_u32 s100, 0
	s_cselect_b64 s[100:101], s[98:99], 0
	s_andn2_b64 exec, exec, s[100:101]
	global_store_dwordx4 v42, v[148:151], s[12:13] nt
	s_mov_b64 exec, -1
	s_nop 1
	ds_read_b128 v[204:207], v249 offset:4160
	ds_read_b128 v[208:211], v249 offset:4672
	v_cndmask_b32_e32 v148, v96, v108, vcc
	v_cndmask_b32_e32 v149, v97, v109, vcc
	v_cndmask_b32_e32 v150, v98, v110, vcc
	v_cndmask_b32_e32 v151, v99, v111, vcc
	v_cndmask_b32_e64 v152, v96, v88, s[98:99]
	v_cndmask_b32_e64 v153, v97, v89, s[98:99]
	v_cndmask_b32_e64 v154, v98, v90, s[98:99]
	v_cndmask_b32_e64 v155, v99, v91, s[98:99]
	v_fma_f32 v156, v120, v96, v104
	v_fma_f32 v157, v121, v97, v105
	v_fma_f32 v158, v122, v98, v106
	v_fma_f32 v159, v123, v99, v107
	v_fmac_f32_dpp v156, v148, v124 row_ror:1 row_mask:0xf bank_mask:0xf
	v_fmac_f32_dpp v157, v149, v125 row_ror:1 row_mask:0xf bank_mask:0xf
	v_fmac_f32_dpp v158, v150, v126 row_ror:1 row_mask:0xf bank_mask:0xf
	v_fmac_f32_dpp v159, v151, v127 row_ror:1 row_mask:0xf bank_mask:0xf
	v_fmac_f32_dpp v156, v152, v116 row_ror:15 row_mask:0xf bank_mask:0xf
	v_fmac_f32_dpp v157, v153, v117 row_ror:15 row_mask:0xf bank_mask:0xf
	v_fmac_f32_dpp v158, v154, v118 row_ror:15 row_mask:0xf bank_mask:0xf
	v_fmac_f32_dpp v159, v155, v119 row_ror:15 row_mask:0xf bank_mask:0xf
	v_cndmask_b32_e32 v148, v68, v84, vcc
	v_cndmask_b32_e32 v149, v69, v85, vcc
	v_cndmask_b32_e32 v150, v70, v86, vcc
	v_cndmask_b32_e32 v151, v71, v87, vcc
	v_cndmask_b32_e64 v152, v68, v60, s[98:99]
	v_cndmask_b32_e64 v153, v69, v61, s[98:99]
	v_cndmask_b32_e64 v154, v70, v62, s[98:99]
	v_cndmask_b32_e64 v155, v71, v63, s[98:99]
	v_fma_f32 v237, v100, v68, v80
	v_fma_f32 v238, v101, v69, v81
	v_fma_f32 v239, v102, v70, v82
	v_fma_f32 v240, v103, v71, v83
	v_fmac_f32_dpp v237, v148, v112 row_ror:1 row_mask:0xf bank_mask:0xf
	v_fmac_f32_dpp v238, v149, v113 row_ror:1 row_mask:0xf bank_mask:0xf
	v_fmac_f32_dpp v239, v150, v114 row_ror:1 row_mask:0xf bank_mask:0xf
	v_fmac_f32_dpp v240, v151, v115 row_ror:1 row_mask:0xf bank_mask:0xf
	v_fmac_f32_dpp v237, v152, v92 row_ror:15 row_mask:0xf bank_mask:0xf
	v_fmac_f32_dpp v238, v153, v93 row_ror:15 row_mask:0xf bank_mask:0xf
	v_fmac_f32_dpp v239, v154, v94 row_ror:15 row_mask:0xf bank_mask:0xf
	v_fmac_f32_dpp v240, v155, v95 row_ror:15 row_mask:0xf bank_mask:0xf
	v_mul_f32_e32 v148, 0xbfb8aa3b, v156
	v_mul_f32_e32 v149, 0xbfb8aa3b, v157
	v_mul_f32_e32 v150, 0xbfb8aa3b, v158
	v_mul_f32_e32 v151, 0xbfb8aa3b, v159
	v_exp_f32_e32 v148, v148
	v_exp_f32_e32 v149, v149
	v_exp_f32_e32 v150, v150
	v_exp_f32_e32 v151, v151
	v_add_f32_e32 v148, 1.0, v148
	v_add_f32_e32 v149, 1.0, v149
	v_add_f32_e32 v150, 1.0, v150
	v_add_f32_e32 v151, 1.0, v151
	v_rcp_f32_e32 v148, v148
	v_rcp_f32_e32 v149, v149
	v_rcp_f32_e32 v150, v150
	v_rcp_f32_e32 v151, v151
	v_mul_f32_e32 v156, v156, v148
	v_mul_f32_e32 v157, v157, v149
	v_mul_f32_e32 v158, v158, v150
	v_mul_f32_e32 v159, v159, v151
	v_mul_f32_e32 v156, v156, v237
	v_mul_f32_e32 v157, v157, v238
	v_mul_f32_e32 v158, v158, v239
	v_mul_f32_e32 v159, v159, v240
	v_cvt_pk_bf16_f32 v40, v156, v157
	v_cvt_pk_bf16_f32 v41, v158, v159
	v_bfi_b32 v18, v146, v243, v40
	v_bfi_b32 v19, v146, v244, v41
	ds_swizzle_b32 v16, v18 offset:0x401f
	ds_swizzle_b32 v17, v19 offset:0x401f
	v_add_u32_e32 v42, 0x16000, v250
	s_waitcnt lgkmcnt(0)
	v_bfi_b32 v148, v146, v16, v243
	v_bfi_b32 v149, v146, v17, v244
	v_bfi_b32 v150, v146, v40, v16
	v_bfi_b32 v151, v146, v41, v17
	global_store_dwordx4 v42, v[148:151], s[12:13] nt
	s_nop 1
	v_cndmask_b32_e32 v148, v88, v96, vcc
	v_cndmask_b32_e32 v149, v89, v97, vcc
	v_cndmask_b32_e32 v150, v90, v98, vcc
	v_cndmask_b32_e32 v151, v91, v99, vcc
	v_cndmask_b32_e64 v152, v88, v76, s[98:99]
	v_cndmask_b32_e64 v153, v89, v77, s[98:99]
	v_cndmask_b32_e64 v154, v90, v78, s[98:99]
	v_cndmask_b32_e64 v155, v91, v79, s[98:99]
	v_fma_f32 v156, v120, v88, v104
	v_fma_f32 v157, v121, v89, v105
	v_fma_f32 v158, v122, v90, v106
	v_fma_f32 v159, v123, v91, v107
	v_fmac_f32_dpp v156, v148, v124 row_ror:1 row_mask:0xf bank_mask:0xf
	v_fmac_f32_dpp v157, v149, v125 row_ror:1 row_mask:0xf bank_mask:0xf
	v_fmac_f32_dpp v158, v150, v126 row_ror:1 row_mask:0xf bank_mask:0xf
	v_fmac_f32_dpp v159, v151, v127 row_ror:1 row_mask:0xf bank_mask:0xf
	v_fmac_f32_dpp v156, v152, v116 row_ror:15 row_mask:0xf bank_mask:0xf
	v_fmac_f32_dpp v157, v153, v117 row_ror:15 row_mask:0xf bank_mask:0xf
	v_fmac_f32_dpp v158, v154, v118 row_ror:15 row_mask:0xf bank_mask:0xf
	v_fmac_f32_dpp v159, v155, v119 row_ror:15 row_mask:0xf bank_mask:0xf
	v_cndmask_b32_e32 v148, v60, v68, vcc
	v_cndmask_b32_e32 v149, v61, v69, vcc
	v_cndmask_b32_e32 v150, v62, v70, vcc
	v_cndmask_b32_e32 v151, v63, v71, vcc
	v_cndmask_b32_e64 v152, v60, v52, s[98:99]
	v_cndmask_b32_e64 v153, v61, v53, s[98:99]
	v_cndmask_b32_e64 v154, v62, v54, s[98:99]
	v_cndmask_b32_e64 v155, v63, v55, s[98:99]
	v_fma_f32 v237, v100, v60, v80
	v_fma_f32 v238, v101, v61, v81
	v_fma_f32 v239, v102, v62, v82
	v_fma_f32 v240, v103, v63, v83
	v_fmac_f32_dpp v237, v148, v112 row_ror:1 row_mask:0xf bank_mask:0xf
	v_fmac_f32_dpp v238, v149, v113 row_ror:1 row_mask:0xf bank_mask:0xf
	v_fmac_f32_dpp v239, v150, v114 row_ror:1 row_mask:0xf bank_mask:0xf
	v_fmac_f32_dpp v240, v151, v115 row_ror:1 row_mask:0xf bank_mask:0xf
	v_fmac_f32_dpp v237, v152, v92 row_ror:15 row_mask:0xf bank_mask:0xf
	v_fmac_f32_dpp v238, v153, v93 row_ror:15 row_mask:0xf bank_mask:0xf
	v_fmac_f32_dpp v239, v154, v94 row_ror:15 row_mask:0xf bank_mask:0xf
	v_fmac_f32_dpp v240, v155, v95 row_ror:15 row_mask:0xf bank_mask:0xf
	v_mul_f32_e32 v148, 0xbfb8aa3b, v156
	v_mul_f32_e32 v149, 0xbfb8aa3b, v157
	v_mul_f32_e32 v150, 0xbfb8aa3b, v158
	v_mul_f32_e32 v151, 0xbfb8aa3b, v159
	v_exp_f32_e32 v148, v148
	v_exp_f32_e32 v149, v149
	v_exp_f32_e32 v150, v150
	v_exp_f32_e32 v151, v151
	v_add_f32_e32 v148, 1.0, v148
	v_add_f32_e32 v149, 1.0, v149
	v_add_f32_e32 v150, 1.0, v150
	v_add_f32_e32 v151, 1.0, v151
	v_rcp_f32_e32 v148, v148
	v_rcp_f32_e32 v149, v149
	v_rcp_f32_e32 v150, v150
	v_rcp_f32_e32 v151, v151
	v_mul_f32_e32 v156, v156, v148
	v_mul_f32_e32 v157, v157, v149
	v_mul_f32_e32 v158, v158, v150
	v_mul_f32_e32 v159, v159, v151
	v_mul_f32_e32 v156, v156, v237
	v_mul_f32_e32 v157, v157, v238
	v_mul_f32_e32 v158, v158, v239
	v_mul_f32_e32 v159, v159, v240
	v_cvt_pk_bf16_f32 v40, v156, v157
	v_cvt_pk_bf16_f32 v41, v158, v159
	v_bfi_b32 v18, v146, v253, v40
	v_bfi_b32 v19, v146, v254, v41
	ds_swizzle_b32 v16, v18 offset:0x401f
	ds_swizzle_b32 v17, v19 offset:0x401f
	v_add_u32_e32 v42, 0x2c000, v250
	s_waitcnt lgkmcnt(0)
	v_bfi_b32 v148, v146, v16, v253
	v_bfi_b32 v149, v146, v17, v254
	v_bfi_b32 v150, v146, v40, v16
	v_bfi_b32 v151, v146, v41, v17
	global_store_dwordx4 v42, v[148:151], s[12:13] nt
	s_nop 1
	v_cndmask_b32_e32 v148, v76, v88, vcc
	v_cndmask_b32_e32 v149, v77, v89, vcc
	v_cndmask_b32_e32 v150, v78, v90, vcc
	v_cndmask_b32_e32 v151, v79, v91, vcc
	v_cndmask_b32_e64 v152, v76, v160, s[98:99]
	v_cndmask_b32_e64 v153, v77, v161, s[98:99]
	v_cndmask_b32_e64 v154, v78, v162, s[98:99]
	v_cndmask_b32_e64 v155, v79, v163, s[98:99]
	v_fma_f32 v156, v120, v76, v104
	v_fma_f32 v157, v121, v77, v105
	v_fma_f32 v158, v122, v78, v106
	v_fma_f32 v159, v123, v79, v107
	v_fmac_f32_dpp v156, v148, v124 row_ror:1 row_mask:0xf bank_mask:0xf
	v_fmac_f32_dpp v157, v149, v125 row_ror:1 row_mask:0xf bank_mask:0xf
	v_fmac_f32_dpp v158, v150, v126 row_ror:1 row_mask:0xf bank_mask:0xf
	v_fmac_f32_dpp v159, v151, v127 row_ror:1 row_mask:0xf bank_mask:0xf
	v_fmac_f32_dpp v156, v152, v116 row_ror:15 row_mask:0xf bank_mask:0xf
	v_fmac_f32_dpp v157, v153, v117 row_ror:15 row_mask:0xf bank_mask:0xf
	v_fmac_f32_dpp v158, v154, v118 row_ror:15 row_mask:0xf bank_mask:0xf
	v_fmac_f32_dpp v159, v155, v119 row_ror:15 row_mask:0xf bank_mask:0xf
	v_cndmask_b32_e32 v148, v52, v60, vcc
	v_cndmask_b32_e32 v149, v53, v61, vcc
	v_cndmask_b32_e32 v150, v54, v62, vcc
	v_cndmask_b32_e32 v151, v55, v63, vcc
	v_cndmask_b32_e64 v152, v52, v164, s[98:99]
	v_cndmask_b32_e64 v153, v53, v165, s[98:99]
	v_cndmask_b32_e64 v154, v54, v166, s[98:99]
	v_cndmask_b32_e64 v155, v55, v167, s[98:99]
	v_fma_f32 v237, v100, v52, v80
	v_fma_f32 v238, v101, v53, v81
	v_fma_f32 v239, v102, v54, v82
	v_fma_f32 v240, v103, v55, v83
	v_fmac_f32_dpp v237, v148, v112 row_ror:1 row_mask:0xf bank_mask:0xf
	v_fmac_f32_dpp v238, v149, v113 row_ror:1 row_mask:0xf bank_mask:0xf
	v_fmac_f32_dpp v239, v150, v114 row_ror:1 row_mask:0xf bank_mask:0xf
	v_fmac_f32_dpp v240, v151, v115 row_ror:1 row_mask:0xf bank_mask:0xf
	v_fmac_f32_dpp v237, v152, v92 row_ror:15 row_mask:0xf bank_mask:0xf
	v_fmac_f32_dpp v238, v153, v93 row_ror:15 row_mask:0xf bank_mask:0xf
	v_fmac_f32_dpp v239, v154, v94 row_ror:15 row_mask:0xf bank_mask:0xf
	v_fmac_f32_dpp v240, v155, v95 row_ror:15 row_mask:0xf bank_mask:0xf
	v_mul_f32_e32 v148, 0xbfb8aa3b, v156
	v_mul_f32_e32 v149, 0xbfb8aa3b, v157
	v_mul_f32_e32 v150, 0xbfb8aa3b, v158
	v_mul_f32_e32 v151, 0xbfb8aa3b, v159
	v_exp_f32_e32 v148, v148
	v_exp_f32_e32 v149, v149
	v_exp_f32_e32 v150, v150
	v_exp_f32_e32 v151, v151
	v_add_f32_e32 v148, 1.0, v148
	v_add_f32_e32 v149, 1.0, v149
	v_add_f32_e32 v150, 1.0, v150
	v_add_f32_e32 v151, 1.0, v151
	v_rcp_f32_e32 v148, v148
	v_rcp_f32_e32 v149, v149
	v_rcp_f32_e32 v150, v150
	v_rcp_f32_e32 v151, v151
	v_mul_f32_e32 v156, v156, v148
	v_mul_f32_e32 v157, v157, v149
	v_mul_f32_e32 v158, v158, v150
	v_mul_f32_e32 v159, v159, v151
	v_mul_f32_e32 v156, v156, v237
	v_mul_f32_e32 v157, v157, v238
	v_mul_f32_e32 v158, v158, v239
	v_mul_f32_e32 v159, v159, v240
	v_cvt_pk_bf16_f32 v40, v156, v157
	v_cvt_pk_bf16_f32 v41, v158, v159
	v_bfi_b32 v18, v146, v255, v40
	v_bfi_b32 v19, v146, v246, v41
	ds_swizzle_b32 v16, v18 offset:0x401f
	ds_swizzle_b32 v17, v19 offset:0x401f
	v_add_u32_e32 v42, 0x42000, v250
	s_waitcnt lgkmcnt(0)
	v_bfi_b32 v148, v146, v16, v255
	v_bfi_b32 v149, v146, v17, v246
	v_bfi_b32 v150, v146, v40, v16
	v_bfi_b32 v151, v146, v41, v17
	global_store_dwordx4 v42, v[148:151], s[12:13] nt
	s_nop 1
	ds_read_b128 v[160:163], v249 offset:7232
	ds_read_b128 v[164:167], v249 offset:7744
	s_waitcnt lgkmcnt(2)
	v_cndmask_b32_e32 v148, v44, v204, vcc
	v_cndmask_b32_e32 v149, v45, v205, vcc
	v_cndmask_b32_e32 v150, v46, v206, vcc
	v_cndmask_b32_e32 v151, v47, v207, vcc
	v_cndmask_b32_e64 v152, v44, v32, s[98:99]
	v_cndmask_b32_e64 v153, v45, v33, s[98:99]
	v_cndmask_b32_e64 v154, v46, v34, s[98:99]
	v_cndmask_b32_e64 v155, v47, v35, s[98:99]
	v_fma_f32 v156, v120, v44, v104
	v_fma_f32 v157, v121, v45, v105
	v_fma_f32 v158, v122, v46, v106
	v_fma_f32 v159, v123, v47, v107
	v_fmac_f32_dpp v156, v148, v124 row_ror:1 row_mask:0xf bank_mask:0xf
	v_fmac_f32_dpp v157, v149, v125 row_ror:1 row_mask:0xf bank_mask:0xf
	v_fmac_f32_dpp v158, v150, v126 row_ror:1 row_mask:0xf bank_mask:0xf
	v_fmac_f32_dpp v159, v151, v127 row_ror:1 row_mask:0xf bank_mask:0xf
	v_fmac_f32_dpp v156, v152, v116 row_ror:15 row_mask:0xf bank_mask:0xf
	v_fmac_f32_dpp v157, v153, v117 row_ror:15 row_mask:0xf bank_mask:0xf
	v_fmac_f32_dpp v158, v154, v118 row_ror:15 row_mask:0xf bank_mask:0xf
	v_fmac_f32_dpp v159, v155, v119 row_ror:15 row_mask:0xf bank_mask:0xf
	v_cndmask_b32_e32 v148, v20, v208, vcc
	v_cndmask_b32_e32 v149, v21, v209, vcc
	v_cndmask_b32_e32 v150, v22, v210, vcc
	v_cndmask_b32_e32 v151, v23, v211, vcc
	v_cndmask_b32_e64 v152, v20, v8, s[98:99]
	v_cndmask_b32_e64 v153, v21, v9, s[98:99]
	v_cndmask_b32_e64 v154, v22, v10, s[98:99]
	v_cndmask_b32_e64 v155, v23, v11, s[98:99]
	v_fma_f32 v237, v100, v20, v80
	v_fma_f32 v238, v101, v21, v81
	v_fma_f32 v239, v102, v22, v82
	v_fma_f32 v240, v103, v23, v83
	v_fmac_f32_dpp v237, v148, v112 row_ror:1 row_mask:0xf bank_mask:0xf
	v_fmac_f32_dpp v238, v149, v113 row_ror:1 row_mask:0xf bank_mask:0xf
	v_fmac_f32_dpp v239, v150, v114 row_ror:1 row_mask:0xf bank_mask:0xf
	v_fmac_f32_dpp v240, v151, v115 row_ror:1 row_mask:0xf bank_mask:0xf
	v_fmac_f32_dpp v237, v152, v92 row_ror:15 row_mask:0xf bank_mask:0xf
	v_fmac_f32_dpp v238, v153, v93 row_ror:15 row_mask:0xf bank_mask:0xf
	v_fmac_f32_dpp v239, v154, v94 row_ror:15 row_mask:0xf bank_mask:0xf
	v_fmac_f32_dpp v240, v155, v95 row_ror:15 row_mask:0xf bank_mask:0xf
	v_mul_f32_e32 v148, 0xbfb8aa3b, v156
	v_mul_f32_e32 v149, 0xbfb8aa3b, v157
	v_mul_f32_e32 v150, 0xbfb8aa3b, v158
	v_mul_f32_e32 v151, 0xbfb8aa3b, v159
	v_exp_f32_e32 v148, v148
	v_exp_f32_e32 v149, v149
	v_exp_f32_e32 v150, v150
	v_exp_f32_e32 v151, v151
	v_add_f32_e32 v148, 1.0, v148
	v_add_f32_e32 v149, 1.0, v149
	v_add_f32_e32 v150, 1.0, v150
	v_add_f32_e32 v151, 1.0, v151
	v_rcp_f32_e32 v148, v148
	v_rcp_f32_e32 v149, v149
	v_rcp_f32_e32 v150, v150
	v_rcp_f32_e32 v151, v151
	v_mul_f32_e32 v156, v156, v148
	v_mul_f32_e32 v157, v157, v149
	v_mul_f32_e32 v158, v158, v150
	v_mul_f32_e32 v159, v159, v151
	v_mul_f32_e32 v156, v156, v237
	v_mul_f32_e32 v157, v157, v238
	v_mul_f32_e32 v158, v158, v239
	v_mul_f32_e32 v159, v159, v240
	v_cvt_pk_bf16_f32 v40, v156, v157
	v_cvt_pk_bf16_f32 v41, v158, v159
	v_bfi_b32 v18, v146, v247, v40
	v_bfi_b32 v19, v146, v248, v41
	ds_swizzle_b32 v16, v18 offset:0x401f
	ds_swizzle_b32 v17, v19 offset:0x401f
	v_add_u32_e32 v42, 0xb0000, v250
	s_waitcnt lgkmcnt(0)
	v_bfi_b32 v148, v146, v16, v247
	v_bfi_b32 v149, v146, v17, v248
	v_bfi_b32 v150, v146, v40, v16
	v_bfi_b32 v151, v146, v41, v17
	global_store_dwordx4 v42, v[148:151], s[12:13] nt
	s_nop 1
	v_cndmask_b32_e32 v148, v32, v44, vcc
	v_cndmask_b32_e32 v149, v33, v45, vcc
	v_cndmask_b32_e32 v150, v34, v46, vcc
	v_cndmask_b32_e32 v151, v35, v47, vcc
	v_cndmask_b32_e64 v152, v32, v24, s[98:99]
	v_cndmask_b32_e64 v153, v33, v25, s[98:99]
	v_cndmask_b32_e64 v154, v34, v26, s[98:99]
	v_cndmask_b32_e64 v155, v35, v27, s[98:99]
	v_fma_f32 v156, v120, v32, v104
	v_fma_f32 v157, v121, v33, v105
	v_fma_f32 v158, v122, v34, v106
	v_fma_f32 v159, v123, v35, v107
	v_fmac_f32_dpp v156, v148, v124 row_ror:1 row_mask:0xf bank_mask:0xf
	v_fmac_f32_dpp v157, v149, v125 row_ror:1 row_mask:0xf bank_mask:0xf
	v_fmac_f32_dpp v158, v150, v126 row_ror:1 row_mask:0xf bank_mask:0xf
	v_fmac_f32_dpp v159, v151, v127 row_ror:1 row_mask:0xf bank_mask:0xf
	v_fmac_f32_dpp v156, v152, v116 row_ror:15 row_mask:0xf bank_mask:0xf
	v_fmac_f32_dpp v157, v153, v117 row_ror:15 row_mask:0xf bank_mask:0xf
	v_fmac_f32_dpp v158, v154, v118 row_ror:15 row_mask:0xf bank_mask:0xf
	v_fmac_f32_dpp v159, v155, v119 row_ror:15 row_mask:0xf bank_mask:0xf
	v_cndmask_b32_e32 v148, v8, v20, vcc
	v_cndmask_b32_e32 v149, v9, v21, vcc
	v_cndmask_b32_e32 v150, v10, v22, vcc
	v_cndmask_b32_e32 v151, v11, v23, vcc
	v_cndmask_b32_e64 v152, v8, v4, s[98:99]
	v_cndmask_b32_e64 v153, v9, v5, s[98:99]
	v_cndmask_b32_e64 v154, v10, v6, s[98:99]
	v_cndmask_b32_e64 v155, v11, v7, s[98:99]
	v_fma_f32 v237, v100, v8, v80
	v_fma_f32 v238, v101, v9, v81
	v_fma_f32 v239, v102, v10, v82
	v_fma_f32 v240, v103, v11, v83
	v_fmac_f32_dpp v237, v148, v112 row_ror:1 row_mask:0xf bank_mask:0xf
	v_fmac_f32_dpp v238, v149, v113 row_ror:1 row_mask:0xf bank_mask:0xf
	v_fmac_f32_dpp v239, v150, v114 row_ror:1 row_mask:0xf bank_mask:0xf
	v_fmac_f32_dpp v240, v151, v115 row_ror:1 row_mask:0xf bank_mask:0xf
	v_fmac_f32_dpp v237, v152, v92 row_ror:15 row_mask:0xf bank_mask:0xf
	v_fmac_f32_dpp v238, v153, v93 row_ror:15 row_mask:0xf bank_mask:0xf
	v_fmac_f32_dpp v239, v154, v94 row_ror:15 row_mask:0xf bank_mask:0xf
	v_fmac_f32_dpp v240, v155, v95 row_ror:15 row_mask:0xf bank_mask:0xf
	v_mul_f32_e32 v148, 0xbfb8aa3b, v156
	v_mul_f32_e32 v149, 0xbfb8aa3b, v157
	v_mul_f32_e32 v150, 0xbfb8aa3b, v158
	v_mul_f32_e32 v151, 0xbfb8aa3b, v159
	v_exp_f32_e32 v148, v148
	v_exp_f32_e32 v149, v149
	v_exp_f32_e32 v150, v150
	v_exp_f32_e32 v151, v151
	v_add_f32_e32 v148, 1.0, v148
	v_add_f32_e32 v149, 1.0, v149
	v_add_f32_e32 v150, 1.0, v150
	v_add_f32_e32 v151, 1.0, v151
	v_rcp_f32_e32 v148, v148
	v_rcp_f32_e32 v149, v149
	v_rcp_f32_e32 v150, v150
	v_rcp_f32_e32 v151, v151
	v_mul_f32_e32 v156, v156, v148
	v_mul_f32_e32 v157, v157, v149
	v_mul_f32_e32 v158, v158, v150
	v_mul_f32_e32 v159, v159, v151
	v_mul_f32_e32 v156, v156, v237
	v_mul_f32_e32 v157, v157, v238
	v_mul_f32_e32 v158, v158, v239
	v_mul_f32_e32 v159, v159, v240
	v_cvt_pk_bf16_f32 v40, v156, v157
	v_cvt_pk_bf16_f32 v41, v158, v159
	v_bfi_b32 v18, v146, v72, v40
	v_bfi_b32 v19, v146, v73, v41
	ds_swizzle_b32 v16, v18 offset:0x401f
	ds_swizzle_b32 v17, v19 offset:0x401f
	v_add_u32_e32 v42, 0xc6000, v250
	s_waitcnt lgkmcnt(0)
	v_bfi_b32 v148, v146, v16, v72
	v_bfi_b32 v149, v146, v17, v73
	v_bfi_b32 v150, v146, v40, v16
	v_bfi_b32 v151, v146, v41, v17
	global_store_dwordx4 v42, v[148:151], s[12:13] nt
	s_nop 1
	v_cndmask_b32_e32 v148, v24, v32, vcc
	v_cndmask_b32_e32 v149, v25, v33, vcc
	v_cndmask_b32_e32 v150, v26, v34, vcc
	v_cndmask_b32_e32 v151, v27, v35, vcc
	v_cndmask_b32_e64 v152, v24, v12, s[98:99]
	v_cndmask_b32_e64 v153, v25, v13, s[98:99]
	v_cndmask_b32_e64 v154, v26, v14, s[98:99]
	v_cndmask_b32_e64 v155, v27, v15, s[98:99]
	v_fma_f32 v156, v120, v24, v104
	v_fma_f32 v157, v121, v25, v105
	v_fma_f32 v158, v122, v26, v106
	v_fma_f32 v159, v123, v27, v107
	v_fmac_f32_dpp v156, v148, v124 row_ror:1 row_mask:0xf bank_mask:0xf
	v_fmac_f32_dpp v157, v149, v125 row_ror:1 row_mask:0xf bank_mask:0xf
	v_fmac_f32_dpp v158, v150, v126 row_ror:1 row_mask:0xf bank_mask:0xf
	v_fmac_f32_dpp v159, v151, v127 row_ror:1 row_mask:0xf bank_mask:0xf
	v_fmac_f32_dpp v156, v152, v116 row_ror:15 row_mask:0xf bank_mask:0xf
	v_fmac_f32_dpp v157, v153, v117 row_ror:15 row_mask:0xf bank_mask:0xf
	v_fmac_f32_dpp v158, v154, v118 row_ror:15 row_mask:0xf bank_mask:0xf
	v_fmac_f32_dpp v159, v155, v119 row_ror:15 row_mask:0xf bank_mask:0xf
	v_cndmask_b32_e32 v148, v4, v8, vcc
	v_cndmask_b32_e32 v149, v5, v9, vcc
	v_cndmask_b32_e32 v150, v6, v10, vcc
	v_cndmask_b32_e32 v151, v7, v11, vcc
	v_cndmask_b32_e64 v152, v4, v0, s[98:99]
	v_cndmask_b32_e64 v153, v5, v1, s[98:99]
	v_cndmask_b32_e64 v154, v6, v2, s[98:99]
	v_cndmask_b32_e64 v155, v7, v3, s[98:99]
	v_fma_f32 v237, v100, v4, v80
	v_fma_f32 v238, v101, v5, v81
	v_fma_f32 v239, v102, v6, v82
	v_fma_f32 v240, v103, v7, v83
	v_fmac_f32_dpp v237, v148, v112 row_ror:1 row_mask:0xf bank_mask:0xf
	v_fmac_f32_dpp v238, v149, v113 row_ror:1 row_mask:0xf bank_mask:0xf
	v_fmac_f32_dpp v239, v150, v114 row_ror:1 row_mask:0xf bank_mask:0xf
	v_fmac_f32_dpp v240, v151, v115 row_ror:1 row_mask:0xf bank_mask:0xf
	v_fmac_f32_dpp v237, v152, v92 row_ror:15 row_mask:0xf bank_mask:0xf
	v_fmac_f32_dpp v238, v153, v93 row_ror:15 row_mask:0xf bank_mask:0xf
	v_fmac_f32_dpp v239, v154, v94 row_ror:15 row_mask:0xf bank_mask:0xf
	v_fmac_f32_dpp v240, v155, v95 row_ror:15 row_mask:0xf bank_mask:0xf
	v_mul_f32_e32 v148, 0xbfb8aa3b, v156
	v_mul_f32_e32 v149, 0xbfb8aa3b, v157
	v_mul_f32_e32 v150, 0xbfb8aa3b, v158
	v_mul_f32_e32 v151, 0xbfb8aa3b, v159
	v_exp_f32_e32 v148, v148
	v_exp_f32_e32 v149, v149
	v_exp_f32_e32 v150, v150
	v_exp_f32_e32 v151, v151
	v_add_f32_e32 v148, 1.0, v148
	v_add_f32_e32 v149, 1.0, v149
	v_add_f32_e32 v150, 1.0, v150
	v_add_f32_e32 v151, 1.0, v151
	v_rcp_f32_e32 v148, v148
	v_rcp_f32_e32 v149, v149
	v_rcp_f32_e32 v150, v150
	v_rcp_f32_e32 v151, v151
	v_mul_f32_e32 v156, v156, v148
	v_mul_f32_e32 v157, v157, v149
	v_mul_f32_e32 v158, v158, v150
	v_mul_f32_e32 v159, v159, v151
	v_mul_f32_e32 v156, v156, v237
	v_mul_f32_e32 v157, v157, v238
	v_mul_f32_e32 v158, v158, v239
	v_mul_f32_e32 v159, v159, v240
	v_cvt_pk_bf16_f32 v40, v156, v157
	v_cvt_pk_bf16_f32 v41, v158, v159
	v_bfi_b32 v18, v146, v74, v40
	v_bfi_b32 v19, v146, v75, v41
	ds_swizzle_b32 v16, v18 offset:0x401f
	ds_swizzle_b32 v17, v19 offset:0x401f
	v_add_u32_e32 v42, 0xdc000, v250
	s_waitcnt lgkmcnt(0)
	v_bfi_b32 v148, v146, v16, v74
	v_bfi_b32 v149, v146, v17, v75
	v_bfi_b32 v150, v146, v40, v16
	v_bfi_b32 v151, v146, v41, v17
	global_store_dwordx4 v42, v[148:151], s[12:13] nt
	s_nop 1
	s_waitcnt lgkmcnt(0)
	v_cndmask_b32_e32 v148, v12, v24, vcc
	v_cndmask_b32_e32 v149, v13, v25, vcc
	v_cndmask_b32_e32 v150, v14, v26, vcc
	v_cndmask_b32_e32 v151, v15, v27, vcc
	v_cndmask_b32_e64 v152, v12, v160, s[98:99]
	v_cndmask_b32_e64 v153, v13, v161, s[98:99]
	v_cndmask_b32_e64 v154, v14, v162, s[98:99]
	v_cndmask_b32_e64 v155, v15, v163, s[98:99]
	v_fma_f32 v156, v120, v12, v104
	v_fma_f32 v157, v121, v13, v105
	v_fma_f32 v158, v122, v14, v106
	v_fma_f32 v159, v123, v15, v107
	v_fmac_f32_dpp v156, v148, v124 row_ror:1 row_mask:0xf bank_mask:0xf
	v_fmac_f32_dpp v157, v149, v125 row_ror:1 row_mask:0xf bank_mask:0xf
	v_fmac_f32_dpp v158, v150, v126 row_ror:1 row_mask:0xf bank_mask:0xf
	v_fmac_f32_dpp v159, v151, v127 row_ror:1 row_mask:0xf bank_mask:0xf
	v_fmac_f32_dpp v156, v152, v116 row_ror:15 row_mask:0xf bank_mask:0xf
	v_fmac_f32_dpp v157, v153, v117 row_ror:15 row_mask:0xf bank_mask:0xf
	v_fmac_f32_dpp v158, v154, v118 row_ror:15 row_mask:0xf bank_mask:0xf
	v_fmac_f32_dpp v159, v155, v119 row_ror:15 row_mask:0xf bank_mask:0xf
	v_cndmask_b32_e32 v148, v0, v4, vcc
	v_cndmask_b32_e32 v149, v1, v5, vcc
	v_cndmask_b32_e32 v150, v2, v6, vcc
	v_cndmask_b32_e32 v151, v3, v7, vcc
	v_cndmask_b32_e64 v152, v0, v164, s[98:99]
	v_cndmask_b32_e64 v153, v1, v165, s[98:99]
	v_cndmask_b32_e64 v154, v2, v166, s[98:99]
	v_cndmask_b32_e64 v155, v3, v167, s[98:99]
	v_fma_f32 v237, v100, v0, v80
	v_fma_f32 v238, v101, v1, v81
	v_fma_f32 v239, v102, v2, v82
	v_fma_f32 v240, v103, v3, v83
	v_fmac_f32_dpp v237, v148, v112 row_ror:1 row_mask:0xf bank_mask:0xf
	v_fmac_f32_dpp v238, v149, v113 row_ror:1 row_mask:0xf bank_mask:0xf
	v_fmac_f32_dpp v239, v150, v114 row_ror:1 row_mask:0xf bank_mask:0xf
	v_fmac_f32_dpp v240, v151, v115 row_ror:1 row_mask:0xf bank_mask:0xf
	v_fmac_f32_dpp v237, v152, v92 row_ror:15 row_mask:0xf bank_mask:0xf
	v_fmac_f32_dpp v238, v153, v93 row_ror:15 row_mask:0xf bank_mask:0xf
	v_fmac_f32_dpp v239, v154, v94 row_ror:15 row_mask:0xf bank_mask:0xf
	v_fmac_f32_dpp v240, v155, v95 row_ror:15 row_mask:0xf bank_mask:0xf
	v_mul_f32_e32 v148, 0xbfb8aa3b, v156
	v_mul_f32_e32 v149, 0xbfb8aa3b, v157
	v_mul_f32_e32 v150, 0xbfb8aa3b, v158
	v_mul_f32_e32 v151, 0xbfb8aa3b, v159
	v_exp_f32_e32 v148, v148
	v_exp_f32_e32 v149, v149
	v_exp_f32_e32 v150, v150
	v_exp_f32_e32 v151, v151
	v_add_f32_e32 v148, 1.0, v148
	v_add_f32_e32 v149, 1.0, v149
	v_add_f32_e32 v150, 1.0, v150
	v_add_f32_e32 v151, 1.0, v151
	v_rcp_f32_e32 v148, v148
	v_rcp_f32_e32 v149, v149
	v_rcp_f32_e32 v150, v150
	v_rcp_f32_e32 v151, v151
	v_mul_f32_e32 v156, v156, v148
	v_mul_f32_e32 v157, v157, v149
	v_mul_f32_e32 v158, v158, v150
	v_mul_f32_e32 v159, v159, v151
	v_mul_f32_e32 v156, v156, v237
	v_mul_f32_e32 v157, v157, v238
	v_mul_f32_e32 v158, v158, v239
	v_mul_f32_e32 v159, v159, v240
	v_cvt_pk_bf16_f32 v40, v156, v157
	v_cvt_pk_bf16_f32 v41, v158, v159
	v_bfi_b32 v18, v146, v48, v40
	v_bfi_b32 v19, v146, v49, v41
	ds_swizzle_b32 v16, v18 offset:0x401f
	ds_swizzle_b32 v17, v19 offset:0x401f
	v_add_u32_e32 v42, 0xf2000, v250
	v_lshrrev_b32_e32 v152, 6, v251
	s_nop 1
	v_readfirstlane_b32 s100, v152
	s_waitcnt lgkmcnt(0)
	v_bfi_b32 v148, v146, v16, v48
	v_bfi_b32 v149, v146, v17, v49
	v_bfi_b32 v150, v146, v40, v16
	v_bfi_b32 v151, v146, v41, v17
	s_cmp_eq_u32 s100, 1
	s_cselect_b64 s[100:101], vcc, 0
	s_andn2_b64 exec, exec, s[100:101]
	global_store_dwordx4 v42, v[148:151], s[12:13] nt
	s_mov_b64 exec, -1
	s_nop 1
	s_branch .LBB0_2210

.LBB0_2279:
	ds_read_b128 v[148:151], v145
	ds_read_b128 v[152:155], v145 offset:1024
	ds_read_b128 v[156:159], v145 offset:2048
	ds_read_b128 v[160:163], v145 offset:3072
	s_add_u32 s14, s12, 0x100
	s_addc_u32 s15, s13, 0
	s_cmp_eq_u32 s43, 40
	s_cselect_b32 s19, s7, s15
	s_cselect_b32 s18, s6, s14
	s_cselect_b32 s17, s1, s42
	s_cselect_b32 s16, s0, s41
	s_mov_b32 m0, s36
	v_lshl_add_u64 v[168:169], s[12:13], 0, v[136:137]
	ds_read_b128 v[164:167], v146
	ds_read_b128 v[172:175], v146 offset:1024
	ds_read_b128 v[176:179], v146 offset:2048
	ds_read_b128 v[180:183], v146 offset:3072
	ds_read_b128 v[184:187], v146 offset:4096
	ds_read_b128 v[188:191], v146 offset:5120
	ds_read_b128 v[192:195], v146 offset:6144
	ds_read_b128 v[196:199], v146 offset:7168
	global_load_lds_dwordx4 v[168:169], off
	v_lshl_add_u64 v[168:169], s[12:13], 0, v[134:135]
	s_mov_b32 m0, s37
	s_nop 0
	global_load_lds_dwordx4 v[168:169], off
	s_waitcnt lgkmcnt(8)
	s_barrier
	s_waitcnt lgkmcnt(0)
	s_setprio 1
	s_waitcnt lgkmcnt(0)
	v_mfma_f32_16x16x32_bf16 v[124:127], v[148:151], v[164:167], v[124:127]
	v_mfma_f32_16x16x32_bf16 v[120:123], v[156:159], v[164:167], v[120:123]
	v_mfma_f32_16x16x32_bf16 v[116:119], v[148:151], v[176:179], v[116:119]
	v_mfma_f32_16x16x32_bf16 v[108:111], v[156:159], v[176:179], v[108:111]
	v_mfma_f32_16x16x32_bf16 v[100:103], v[148:151], v[184:187], v[100:103]
	v_mfma_f32_16x16x32_bf16 v[92:95], v[156:159], v[184:187], v[92:95]
	v_mfma_f32_16x16x32_bf16 v[84:87], v[148:151], v[192:195], v[84:87]
	v_mfma_f32_16x16x32_bf16 v[76:79], v[156:159], v[192:195], v[76:79]
	v_mfma_f32_16x16x32_bf16 v[124:127], v[152:155], v[172:175], v[124:127]
	v_mfma_f32_16x16x32_bf16 v[120:123], v[160:163], v[172:175], v[120:123]
	v_mfma_f32_16x16x32_bf16 v[116:119], v[152:155], v[180:183], v[116:119]
	v_mfma_f32_16x16x32_bf16 v[108:111], v[160:163], v[180:183], v[108:111]
	v_mfma_f32_16x16x32_bf16 v[100:103], v[152:155], v[188:191], v[100:103]
	v_mfma_f32_16x16x32_bf16 v[92:95], v[160:163], v[188:191], v[92:95]
	v_mfma_f32_16x16x32_bf16 v[84:87], v[152:155], v[196:199], v[84:87]
	v_mfma_f32_16x16x32_bf16 v[76:79], v[160:163], v[196:199], v[76:79]
	s_setprio 0
	s_barrier
	s_add_i32 s12, s34, s25
	v_lshl_add_u64 v[168:169], s[16:17], 0, v[130:131]
	s_mov_b32 m0, s12
	ds_read_b128 v[200:203], v147
	ds_read_b128 v[204:207], v147 offset:1024
	ds_read_b128 v[208:211], v147 offset:2048
	ds_read_b128 v[212:215], v147 offset:3072
	global_load_lds_dwordx4 v[168:169], off
	v_lshl_add_u64 v[216:217], s[16:17], 0, v[128:129]
	s_add_i32 m0, s12, 0x2000
	s_nop 0
	global_load_lds_dwordx4 v[216:217], off
	s_barrier
	s_waitcnt lgkmcnt(0)
	s_setprio 1
	s_waitcnt lgkmcnt(0)
	v_mfma_f32_16x16x32_bf16 v[112:115], v[200:203], v[164:167], v[112:115]
	v_mfma_f32_16x16x32_bf16 v[104:107], v[208:211], v[164:167], v[104:107]
	v_mfma_f32_16x16x32_bf16 v[96:99], v[200:203], v[176:179], v[96:99]
	v_mfma_f32_16x16x32_bf16 v[88:91], v[208:211], v[176:179], v[88:91]
	v_mfma_f32_16x16x32_bf16 v[80:83], v[200:203], v[184:187], v[80:83]
	v_mfma_f32_16x16x32_bf16 v[72:75], v[208:211], v[184:187], v[72:75]
	v_mfma_f32_16x16x32_bf16 v[68:71], v[200:203], v[192:195], v[68:71]
	v_mfma_f32_16x16x32_bf16 v[64:67], v[208:211], v[192:195], v[64:67]
	v_mfma_f32_16x16x32_bf16 v[112:115], v[204:207], v[172:175], v[112:115]
	v_mfma_f32_16x16x32_bf16 v[104:107], v[212:215], v[172:175], v[104:107]
	v_mfma_f32_16x16x32_bf16 v[96:99], v[204:207], v[180:183], v[96:99]
	v_mfma_f32_16x16x32_bf16 v[88:91], v[212:215], v[180:183], v[88:91]
	v_mfma_f32_16x16x32_bf16 v[80:83], v[204:207], v[188:191], v[80:83]
	v_mfma_f32_16x16x32_bf16 v[72:75], v[212:215], v[188:191], v[72:75]
	v_mfma_f32_16x16x32_bf16 v[68:71], v[204:207], v[196:199], v[68:71]
	v_mfma_f32_16x16x32_bf16 v[64:67], v[212:215], v[196:199], v[64:67]
	s_setprio 0
	s_mov_b32 m0, s26
	v_lshl_add_u64 v[218:219], s[18:19], 0, v[130:131]
	s_barrier
	ds_read_b128 v[164:167], v146 offset:16384
	ds_read_b128 v[172:175], v146 offset:17408
	ds_read_b128 v[176:179], v146 offset:18432
	ds_read_b128 v[180:183], v146 offset:19456
	ds_read_b128 v[184:187], v146 offset:20480
	ds_read_b128 v[188:191], v146 offset:21504
	ds_read_b128 v[192:195], v146 offset:22528
	ds_read_b128 v[196:199], v146 offset:23552
	global_load_lds_dwordx4 v[218:219], off
	v_lshl_add_u64 v[220:221], s[18:19], 0, v[128:129]
	s_mov_b32 m0, s27
	s_nop 0
	global_load_lds_dwordx4 v[220:221], off
	s_barrier
	s_waitcnt lgkmcnt(0)
	s_setprio 1
	s_waitcnt lgkmcnt(0)
	v_mfma_f32_16x16x32_bf16 v[60:63], v[148:151], v[164:167], v[60:63]
	v_mfma_f32_16x16x32_bf16 v[56:59], v[156:159], v[164:167], v[56:59]
	v_mfma_f32_16x16x32_bf16 v[52:55], v[148:151], v[176:179], v[52:55]
	v_mfma_f32_16x16x32_bf16 v[44:47], v[156:159], v[176:179], v[44:47]
	v_mfma_f32_16x16x32_bf16 v[36:39], v[148:151], v[184:187], v[36:39]
	v_mfma_f32_16x16x32_bf16 v[28:31], v[156:159], v[184:187], v[28:31]
	v_mfma_f32_16x16x32_bf16 v[20:23], v[148:151], v[192:195], v[20:23]
	v_mfma_f32_16x16x32_bf16 v[12:15], v[156:159], v[192:195], v[12:15]
	v_mfma_f32_16x16x32_bf16 v[60:63], v[152:155], v[172:175], v[60:63]
	v_mfma_f32_16x16x32_bf16 v[56:59], v[160:163], v[172:175], v[56:59]
	v_mfma_f32_16x16x32_bf16 v[52:55], v[152:155], v[180:183], v[52:55]
	v_mfma_f32_16x16x32_bf16 v[44:47], v[160:163], v[180:183], v[44:47]
	v_mfma_f32_16x16x32_bf16 v[36:39], v[152:155], v[188:191], v[36:39]
	v_mfma_f32_16x16x32_bf16 v[28:31], v[160:163], v[188:191], v[28:31]
	v_mfma_f32_16x16x32_bf16 v[20:23], v[152:155], v[196:199], v[20:23]
	v_mfma_f32_16x16x32_bf16 v[12:15], v[160:163], v[196:199], v[12:15]
	s_setprio 0
	s_barrier
	s_add_u32 s12, s16, 0xb0000
	s_addc_u32 s13, s17, 0
	s_add_i32 s44, s35, s25
	v_lshl_add_u64 v[148:149], s[12:13], 0, v[130:131]
	s_mov_b32 m0, s44
	s_nop 0
	global_load_lds_dwordx4 v[148:149], off
	v_lshl_add_u64 v[148:149], s[12:13], 0, v[128:129]
	s_add_i32 m0, s44, 0x2000
	s_nop 0
	global_load_lds_dwordx4 v[148:149], off
	s_waitcnt vmcnt(6)
	s_barrier
	s_setprio 1
	v_mfma_f32_16x16x32_bf16 v[48:51], v[200:203], v[164:167], v[48:51]
	v_mfma_f32_16x16x32_bf16 v[40:43], v[208:211], v[164:167], v[40:43]
	v_mfma_f32_16x16x32_bf16 v[32:35], v[200:203], v[176:179], v[32:35]
	v_mfma_f32_16x16x32_bf16 v[24:27], v[208:211], v[176:179], v[24:27]
	v_mfma_f32_16x16x32_bf16 v[16:19], v[200:203], v[184:187], v[16:19]
	v_mfma_f32_16x16x32_bf16 v[8:11], v[208:211], v[184:187], v[8:11]
	v_mfma_f32_16x16x32_bf16 v[4:7], v[200:203], v[192:195], v[4:7]
	v_mfma_f32_16x16x32_bf16 v[0:3], v[208:211], v[192:195], v[0:3]
	v_mfma_f32_16x16x32_bf16 v[48:51], v[204:207], v[172:175], v[48:51]
	v_mfma_f32_16x16x32_bf16 v[40:43], v[212:215], v[172:175], v[40:43]
	v_mfma_f32_16x16x32_bf16 v[32:35], v[204:207], v[180:183], v[32:35]
	v_mfma_f32_16x16x32_bf16 v[24:27], v[212:215], v[180:183], v[24:27]
	v_mfma_f32_16x16x32_bf16 v[16:19], v[204:207], v[188:191], v[16:19]
	v_mfma_f32_16x16x32_bf16 v[8:11], v[212:215], v[188:191], v[8:11]
	v_mfma_f32_16x16x32_bf16 v[4:7], v[204:207], v[196:199], v[4:7]
	v_mfma_f32_16x16x32_bf16 v[0:3], v[212:215], v[196:199], v[0:3]
	s_setprio 0
	s_add_i32 s44, 0, 0x18000
	v_add_u32_e32 v160, s44, v144
	s_barrier
	ds_read_b128 v[148:151], v160
	ds_read_b128 v[152:155], v160 offset:1024
	ds_read_b128 v[156:159], v160 offset:2048
	ds_read_b128 v[160:163], v160 offset:3072
	s_add_u32 s12, s18, 0xb0000
	s_addc_u32 s13, s19, 0
	s_mov_b32 m0, s28
	v_lshl_add_u64 v[200:201], s[12:13], 0, v[130:131]
	ds_read_b128 v[164:167], v146 offset:32768
	ds_read_b128 v[172:175], v146 offset:33792
	ds_read_b128 v[176:179], v146 offset:34816
	ds_read_b128 v[180:183], v146 offset:35840
	ds_read_b128 v[184:187], v146 offset:36864
	ds_read_b128 v[188:191], v146 offset:37888
	ds_read_b128 v[192:195], v146 offset:38912
	ds_read_b128 v[196:199], v146 offset:39936
	global_load_lds_dwordx4 v[200:201], off
	v_lshl_add_u64 v[200:201], s[12:13], 0, v[128:129]
	s_mov_b32 m0, s29
	s_nop 0
	global_load_lds_dwordx4 v[200:201], off
	s_waitcnt lgkmcnt(8)
	s_barrier
	s_waitcnt lgkmcnt(0)
	s_setprio 1
	s_waitcnt lgkmcnt(0)
	v_mfma_f32_16x16x32_bf16 v[124:127], v[148:151], v[164:167], v[124:127]
	v_mfma_f32_16x16x32_bf16 v[120:123], v[156:159], v[164:167], v[120:123]
	v_mfma_f32_16x16x32_bf16 v[116:119], v[148:151], v[176:179], v[116:119]
	v_mfma_f32_16x16x32_bf16 v[108:111], v[156:159], v[176:179], v[108:111]
	v_mfma_f32_16x16x32_bf16 v[100:103], v[148:151], v[184:187], v[100:103]
	v_mfma_f32_16x16x32_bf16 v[92:95], v[156:159], v[184:187], v[92:95]
	v_mfma_f32_16x16x32_bf16 v[84:87], v[148:151], v[192:195], v[84:87]
	v_mfma_f32_16x16x32_bf16 v[76:79], v[156:159], v[192:195], v[76:79]
	v_mfma_f32_16x16x32_bf16 v[124:127], v[152:155], v[172:175], v[124:127]
	v_mfma_f32_16x16x32_bf16 v[120:123], v[160:163], v[172:175], v[120:123]
	v_mfma_f32_16x16x32_bf16 v[116:119], v[152:155], v[180:183], v[116:119]
	v_mfma_f32_16x16x32_bf16 v[108:111], v[160:163], v[180:183], v[108:111]
	v_mfma_f32_16x16x32_bf16 v[100:103], v[152:155], v[188:191], v[100:103]
	v_mfma_f32_16x16x32_bf16 v[92:95], v[160:163], v[188:191], v[92:95]
	v_mfma_f32_16x16x32_bf16 v[84:87], v[152:155], v[196:199], v[84:87]
	v_mfma_f32_16x16x32_bf16 v[76:79], v[160:163], v[196:199], v[76:79]
	s_setprio 0
	s_barrier
	s_add_i32 s18, 0, 0x1c000
	s_add_i32 s12, s44, s25
	v_add_u32_e32 v171, s18, v144
	v_lshl_add_u64 v[168:169], v[168:169], 0, s[10:11]
	s_mov_b32 m0, s12
	ds_read_b128 v[200:203], v171
	ds_read_b128 v[204:207], v171 offset:1024
	ds_read_b128 v[208:211], v171 offset:2048
	ds_read_b128 v[212:215], v171 offset:3072
	global_load_lds_dwordx4 v[168:169], off
	v_lshl_add_u64 v[168:169], v[216:217], 0, s[10:11]
	s_add_i32 m0, s12, 0x2000
	s_nop 0
	global_load_lds_dwordx4 v[168:169], off
	s_barrier
	s_waitcnt lgkmcnt(0)
	s_setprio 1
	s_waitcnt lgkmcnt(0)
	v_mfma_f32_16x16x32_bf16 v[112:115], v[200:203], v[164:167], v[112:115]
	v_mfma_f32_16x16x32_bf16 v[104:107], v[208:211], v[164:167], v[104:107]
	v_mfma_f32_16x16x32_bf16 v[96:99], v[200:203], v[176:179], v[96:99]
	v_mfma_f32_16x16x32_bf16 v[88:91], v[208:211], v[176:179], v[88:91]
	v_mfma_f32_16x16x32_bf16 v[80:83], v[200:203], v[184:187], v[80:83]
	v_mfma_f32_16x16x32_bf16 v[72:75], v[208:211], v[184:187], v[72:75]
	v_mfma_f32_16x16x32_bf16 v[68:71], v[200:203], v[192:195], v[68:71]
	v_mfma_f32_16x16x32_bf16 v[64:67], v[208:211], v[192:195], v[64:67]
	v_mfma_f32_16x16x32_bf16 v[112:115], v[204:207], v[172:175], v[112:115]
	v_mfma_f32_16x16x32_bf16 v[104:107], v[212:215], v[172:175], v[104:107]
	v_mfma_f32_16x16x32_bf16 v[96:99], v[204:207], v[180:183], v[96:99]
	v_mfma_f32_16x16x32_bf16 v[88:91], v[212:215], v[180:183], v[88:91]
	v_mfma_f32_16x16x32_bf16 v[80:83], v[204:207], v[188:191], v[80:83]
	v_mfma_f32_16x16x32_bf16 v[72:75], v[212:215], v[188:191], v[72:75]
	v_mfma_f32_16x16x32_bf16 v[68:71], v[204:207], v[196:199], v[68:71]
	v_mfma_f32_16x16x32_bf16 v[64:67], v[212:215], v[196:199], v[64:67]
	s_setprio 0
	s_mov_b32 m0, s30
	v_lshl_add_u64 v[168:169], v[218:219], 0, s[10:11]
	s_barrier
	ds_read_b128 v[164:167], v146 offset:49152
	ds_read_b128 v[172:175], v146 offset:50176
	ds_read_b128 v[176:179], v146 offset:51200
	ds_read_b128 v[180:183], v146 offset:52224
	ds_read_b128 v[184:187], v146 offset:53248
	ds_read_b128 v[188:191], v146 offset:54272
	ds_read_b128 v[192:195], v146 offset:55296
	ds_read_b128 v[196:199], v146 offset:56320
	global_load_lds_dwordx4 v[168:169], off
	v_lshl_add_u64 v[168:169], v[220:221], 0, s[10:11]
	s_mov_b32 m0, s31
	s_nop 0
	global_load_lds_dwordx4 v[168:169], off
	s_barrier
	s_waitcnt lgkmcnt(0)
	s_setprio 1
	s_waitcnt lgkmcnt(0)
	v_mfma_f32_16x16x32_bf16 v[60:63], v[148:151], v[164:167], v[60:63]
	v_mfma_f32_16x16x32_bf16 v[56:59], v[156:159], v[164:167], v[56:59]
	v_mfma_f32_16x16x32_bf16 v[52:55], v[148:151], v[176:179], v[52:55]
	v_mfma_f32_16x16x32_bf16 v[44:47], v[156:159], v[176:179], v[44:47]
	v_mfma_f32_16x16x32_bf16 v[36:39], v[148:151], v[184:187], v[36:39]
	v_mfma_f32_16x16x32_bf16 v[28:31], v[156:159], v[184:187], v[28:31]
	v_mfma_f32_16x16x32_bf16 v[20:23], v[148:151], v[192:195], v[20:23]
	v_mfma_f32_16x16x32_bf16 v[12:15], v[156:159], v[192:195], v[12:15]
	v_mfma_f32_16x16x32_bf16 v[60:63], v[152:155], v[172:175], v[60:63]
	v_mfma_f32_16x16x32_bf16 v[56:59], v[160:163], v[172:175], v[56:59]
	v_mfma_f32_16x16x32_bf16 v[52:55], v[152:155], v[180:183], v[52:55]
	v_mfma_f32_16x16x32_bf16 v[44:47], v[160:163], v[180:183], v[44:47]
	v_mfma_f32_16x16x32_bf16 v[36:39], v[152:155], v[188:191], v[36:39]
	v_mfma_f32_16x16x32_bf16 v[28:31], v[160:163], v[188:191], v[28:31]
	v_mfma_f32_16x16x32_bf16 v[20:23], v[152:155], v[196:199], v[20:23]
	v_mfma_f32_16x16x32_bf16 v[12:15], v[160:163], v[196:199], v[12:15]
	s_setprio 0
	s_barrier
	s_add_u32 s12, s16, 0xb0080
	s_addc_u32 s13, s17, 0
	s_add_i32 s16, s18, s25
	v_lshl_add_u64 v[148:149], s[12:13], 0, v[130:131]
	s_mov_b32 m0, s16
	s_nop 0
	global_load_lds_dwordx4 v[148:149], off
	v_lshl_add_u64 v[148:149], s[12:13], 0, v[128:129]
	s_add_i32 m0, s16, 0x2000
	s_nop 0
	global_load_lds_dwordx4 v[148:149], off
	s_waitcnt vmcnt(6)
	s_barrier
	s_setprio 1
	v_mfma_f32_16x16x32_bf16 v[48:51], v[200:203], v[164:167], v[48:51]
	v_mfma_f32_16x16x32_bf16 v[40:43], v[208:211], v[164:167], v[40:43]
	v_mfma_f32_16x16x32_bf16 v[32:35], v[200:203], v[176:179], v[32:35]
	v_mfma_f32_16x16x32_bf16 v[24:27], v[208:211], v[176:179], v[24:27]
	v_mfma_f32_16x16x32_bf16 v[16:19], v[200:203], v[184:187], v[16:19]
	v_mfma_f32_16x16x32_bf16 v[8:11], v[208:211], v[184:187], v[8:11]
	v_mfma_f32_16x16x32_bf16 v[4:7], v[200:203], v[192:195], v[4:7]
	v_mfma_f32_16x16x32_bf16 v[0:3], v[208:211], v[192:195], v[0:3]
	v_mfma_f32_16x16x32_bf16 v[48:51], v[204:207], v[172:175], v[48:51]
	v_mfma_f32_16x16x32_bf16 v[40:43], v[212:215], v[172:175], v[40:43]
	v_mfma_f32_16x16x32_bf16 v[32:35], v[204:207], v[180:183], v[32:35]
	v_mfma_f32_16x16x32_bf16 v[24:27], v[212:215], v[180:183], v[24:27]
	v_mfma_f32_16x16x32_bf16 v[16:19], v[204:207], v[188:191], v[16:19]
	v_mfma_f32_16x16x32_bf16 v[8:11], v[212:215], v[188:191], v[8:11]
	v_mfma_f32_16x16x32_bf16 v[4:7], v[204:207], v[196:199], v[4:7]
	v_mfma_f32_16x16x32_bf16 v[0:3], v[212:215], v[196:199], v[0:3]
	s_setprio 0
	s_add_i32 s43, s43, 2
	s_add_u32 s41, s41, 0x100
	s_addc_u32 s42, s42, 0
	s_cmp_gt_u32 s43, 41
	s_mov_b64 s[12:13], s[14:15]
	s_barrier
	s_cbranch_scc0 .LBB0_2279
	v_readlane_b32 s12, v235, 24
	v_lshl_add_u32 v148, s12, 8, v143
	v_readlane_b32 s12, v235, 16
	s_lshl_b32 s12, s12, 8
	v_ashrrev_i32_e32 v149, 31, v148
	s_ashr_i32 s13, s12, 31
	v_lshlrev_b64 v[150:151], 11, v[148:149]
	v_lshl_add_u64 v[150:151], s[2:3], 0, v[150:151]
	s_lshl_b64 s[12:13], s[12:13], 1
	v_lshl_add_u64 v[150:151], v[150:151], 0, s[12:13]
	v_lshl_add_u64 v[150:151], v[150:151], 0, s[8:9]
	v_lshl_add_u64 v[150:151], v[150:151], 0, v[132:133]
	v_mbcnt_lo_u32_b32 v237, -1, 0
	v_mbcnt_hi_u32_b32 v237, -1, v237
	v_bfe_i32 v237, v237, 4, 1
	v_and_b32_e32 v244, 24, v237
	v_add_co_u32_e32 v248, vcc, v244, v150
	s_nop 1
	v_addc_co_u32_e32 v249, vcc, 0, v151, vcc
	v_cvt_pk_bf16_f32 v124, v124, v125
	v_cvt_pk_bf16_f32 v125, v126, v127
	v_cvt_pk_bf16_f32 v120, v120, v121
	v_cvt_pk_bf16_f32 v121, v122, v123
	v_bfi_b32 v244, v237, v124, v120
	v_bfi_b32 v245, v237, v125, v121
	ds_swizzle_b32 v250, v244 offset:0x401f
	ds_swizzle_b32 v251, v245 offset:0x401f
	v_cvt_pk_bf16_f32 v112, v112, v113
	v_cvt_pk_bf16_f32 v113, v114, v115
	v_cvt_pk_bf16_f32 v104, v104, v105
	v_cvt_pk_bf16_f32 v105, v106, v107
	v_bfi_b32 v246, v237, v112, v104
	v_bfi_b32 v247, v237, v113, v105
	ds_swizzle_b32 v252, v246 offset:0x401f
	ds_swizzle_b32 v253, v247 offset:0x401f
	s_waitcnt lgkmcnt(0)
	v_bfi_b32 v240, v237, v250, v124
	v_bfi_b32 v241, v237, v251, v125
	v_bfi_b32 v242, v237, v120, v250
	v_bfi_b32 v243, v237, v121, v251
	global_store_dwordx4 v[248:249], v[240:243], off nt
	s_nop 1
	v_bfi_b32 v240, v237, v252, v112
	v_bfi_b32 v241, v237, v253, v113
	v_bfi_b32 v242, v237, v104, v252
	v_bfi_b32 v243, v237, v105, v253
	global_store_dwordx4 v[248:249], v[240:243], off offset:256 nt
	s_nop 1
	v_add_co_u32_e32 v238, vcc, 0x8000, v248
	s_nop 1
	v_addc_co_u32_e32 v239, vcc, 0, v249, vcc
	v_cvt_pk_bf16_f32 v116, v116, v117
	v_cvt_pk_bf16_f32 v117, v118, v119
	v_cvt_pk_bf16_f32 v108, v108, v109
	v_cvt_pk_bf16_f32 v109, v110, v111
	v_bfi_b32 v244, v237, v116, v108
	v_bfi_b32 v245, v237, v117, v109
	ds_swizzle_b32 v250, v244 offset:0x401f
	ds_swizzle_b32 v251, v245 offset:0x401f
	v_cvt_pk_bf16_f32 v96, v96, v97
	v_cvt_pk_bf16_f32 v97, v98, v99
	v_cvt_pk_bf16_f32 v88, v88, v89
	v_cvt_pk_bf16_f32 v89, v90, v91
	v_bfi_b32 v246, v237, v96, v88
	v_bfi_b32 v247, v237, v97, v89
	ds_swizzle_b32 v252, v246 offset:0x401f
	ds_swizzle_b32 v253, v247 offset:0x401f
	s_waitcnt lgkmcnt(0)
	v_bfi_b32 v240, v237, v250, v116
	v_bfi_b32 v241, v237, v251, v117
	v_bfi_b32 v242, v237, v108, v250
	v_bfi_b32 v243, v237, v109, v251
	global_store_dwordx4 v[238:239], v[240:243], off nt
	s_nop 1
	v_bfi_b32 v240, v237, v252, v96
	v_bfi_b32 v241, v237, v253, v97
	v_bfi_b32 v242, v237, v88, v252
	v_bfi_b32 v243, v237, v89, v253
	global_store_dwordx4 v[238:239], v[240:243], off offset:256 nt
	s_nop 1
	v_add_co_u32_e32 v238, vcc, 0x10000, v248
	s_nop 1
	v_addc_co_u32_e32 v239, vcc, 0, v249, vcc
	v_cvt_pk_bf16_f32 v100, v100, v101
	v_cvt_pk_bf16_f32 v101, v102, v103
	v_cvt_pk_bf16_f32 v92, v92, v93
	v_cvt_pk_bf16_f32 v93, v94, v95
	v_bfi_b32 v244, v237, v100, v92
	v_bfi_b32 v245, v237, v101, v93
	ds_swizzle_b32 v250, v244 offset:0x401f
	ds_swizzle_b32 v251, v245 offset:0x401f
	v_cvt_pk_bf16_f32 v80, v80, v81
	v_cvt_pk_bf16_f32 v81, v82, v83
	v_cvt_pk_bf16_f32 v72, v72, v73
	v_cvt_pk_bf16_f32 v73, v74, v75
	v_bfi_b32 v246, v237, v80, v72
	v_bfi_b32 v247, v237, v81, v73
	ds_swizzle_b32 v252, v246 offset:0x401f
	ds_swizzle_b32 v253, v247 offset:0x401f
	s_waitcnt lgkmcnt(0)
	v_bfi_b32 v240, v237, v250, v100
	v_bfi_b32 v241, v237, v251, v101
	v_bfi_b32 v242, v237, v92, v250
	v_bfi_b32 v243, v237, v93, v251
	global_store_dwordx4 v[238:239], v[240:243], off nt
	s_nop 1
	v_bfi_b32 v240, v237, v252, v80
	v_bfi_b32 v241, v237, v253, v81
	v_bfi_b32 v242, v237, v72, v252
	v_bfi_b32 v243, v237, v73, v253
	global_store_dwordx4 v[238:239], v[240:243], off offset:256 nt
	s_nop 1
	v_add_co_u32_e32 v238, vcc, 0x18000, v248
	s_nop 1
	v_addc_co_u32_e32 v239, vcc, 0, v249, vcc
	v_cvt_pk_bf16_f32 v84, v84, v85
	v_cvt_pk_bf16_f32 v85, v86, v87
	v_cvt_pk_bf16_f32 v76, v76, v77
	v_cvt_pk_bf16_f32 v77, v78, v79
	v_bfi_b32 v244, v237, v84, v76
	v_bfi_b32 v245, v237, v85, v77
	ds_swizzle_b32 v250, v244 offset:0x401f
	ds_swizzle_b32 v251, v245 offset:0x401f
	v_cvt_pk_bf16_f32 v68, v68, v69
	v_cvt_pk_bf16_f32 v69, v70, v71
	v_cvt_pk_bf16_f32 v64, v64, v65
	v_cvt_pk_bf16_f32 v65, v66, v67
	v_bfi_b32 v246, v237, v68, v64
	v_bfi_b32 v247, v237, v69, v65
	ds_swizzle_b32 v252, v246 offset:0x401f
	ds_swizzle_b32 v253, v247 offset:0x401f
	s_waitcnt lgkmcnt(0)
	v_bfi_b32 v240, v237, v250, v84
	v_bfi_b32 v241, v237, v251, v85
	v_bfi_b32 v242, v237, v76, v250
	v_bfi_b32 v243, v237, v77, v251
	global_store_dwordx4 v[238:239], v[240:243], off nt
	s_nop 1
	v_bfi_b32 v240, v237, v252, v68
	v_bfi_b32 v241, v237, v253, v69
	v_bfi_b32 v242, v237, v64, v252
	v_bfi_b32 v243, v237, v65, v253
	global_store_dwordx4 v[238:239], v[240:243], off offset:256 nt
	s_nop 1
	v_add_co_u32_e32 v238, vcc, 0x40000, v248
	s_nop 1
	v_addc_co_u32_e32 v239, vcc, 0, v249, vcc
	v_cvt_pk_bf16_f32 v60, v60, v61
	v_cvt_pk_bf16_f32 v61, v62, v63
	v_cvt_pk_bf16_f32 v56, v56, v57
	v_cvt_pk_bf16_f32 v57, v58, v59
	v_bfi_b32 v244, v237, v60, v56
	v_bfi_b32 v245, v237, v61, v57
	ds_swizzle_b32 v250, v244 offset:0x401f
	ds_swizzle_b32 v251, v245 offset:0x401f
	v_cvt_pk_bf16_f32 v48, v48, v49
	v_cvt_pk_bf16_f32 v49, v50, v51
	v_cvt_pk_bf16_f32 v40, v40, v41
	v_cvt_pk_bf16_f32 v41, v42, v43
	v_bfi_b32 v246, v237, v48, v40
	v_bfi_b32 v247, v237, v49, v41
	ds_swizzle_b32 v252, v246 offset:0x401f
	ds_swizzle_b32 v253, v247 offset:0x401f
	s_waitcnt lgkmcnt(0)
	v_bfi_b32 v240, v237, v250, v60
	v_bfi_b32 v241, v237, v251, v61
	v_bfi_b32 v242, v237, v56, v250
	v_bfi_b32 v243, v237, v57, v251
	global_store_dwordx4 v[238:239], v[240:243], off nt
	s_nop 1
	v_bfi_b32 v240, v237, v252, v48
	v_bfi_b32 v241, v237, v253, v49
	v_bfi_b32 v242, v237, v40, v252
	v_bfi_b32 v243, v237, v41, v253
	global_store_dwordx4 v[238:239], v[240:243], off offset:256 nt
	s_nop 1
	v_add_co_u32_e32 v238, vcc, 0x48000, v248
	s_nop 1
	v_addc_co_u32_e32 v239, vcc, 0, v249, vcc
	v_cvt_pk_bf16_f32 v52, v52, v53
	v_cvt_pk_bf16_f32 v53, v54, v55
	v_cvt_pk_bf16_f32 v44, v44, v45
	v_cvt_pk_bf16_f32 v45, v46, v47
	v_bfi_b32 v244, v237, v52, v44
	v_bfi_b32 v245, v237, v53, v45
	ds_swizzle_b32 v250, v244 offset:0x401f
	ds_swizzle_b32 v251, v245 offset:0x401f
	v_cvt_pk_bf16_f32 v32, v32, v33
	v_cvt_pk_bf16_f32 v33, v34, v35
	v_cvt_pk_bf16_f32 v24, v24, v25
	v_cvt_pk_bf16_f32 v25, v26, v27
	v_bfi_b32 v246, v237, v32, v24
	v_bfi_b32 v247, v237, v33, v25
	ds_swizzle_b32 v252, v246 offset:0x401f
	ds_swizzle_b32 v253, v247 offset:0x401f
	s_waitcnt lgkmcnt(0)
	v_bfi_b32 v240, v237, v250, v52
	v_bfi_b32 v241, v237, v251, v53
	v_bfi_b32 v242, v237, v44, v250
	v_bfi_b32 v243, v237, v45, v251
	global_store_dwordx4 v[238:239], v[240:243], off nt
	s_nop 1
	v_bfi_b32 v240, v237, v252, v32
	v_bfi_b32 v241, v237, v253, v33
	v_bfi_b32 v242, v237, v24, v252
	v_bfi_b32 v243, v237, v25, v253
	global_store_dwordx4 v[238:239], v[240:243], off offset:256 nt
	s_nop 1
	v_add_co_u32_e32 v238, vcc, 0x50000, v248
	s_nop 1
	v_addc_co_u32_e32 v239, vcc, 0, v249, vcc
	v_cvt_pk_bf16_f32 v36, v36, v37
	v_cvt_pk_bf16_f32 v37, v38, v39
	v_cvt_pk_bf16_f32 v28, v28, v29
	v_cvt_pk_bf16_f32 v29, v30, v31
	v_bfi_b32 v244, v237, v36, v28
	v_bfi_b32 v245, v237, v37, v29
	ds_swizzle_b32 v250, v244 offset:0x401f
	ds_swizzle_b32 v251, v245 offset:0x401f
	v_cvt_pk_bf16_f32 v16, v16, v17
	v_cvt_pk_bf16_f32 v17, v18, v19
	v_cvt_pk_bf16_f32 v8, v8, v9
	v_cvt_pk_bf16_f32 v9, v10, v11
	v_bfi_b32 v246, v237, v16, v8
	v_bfi_b32 v247, v237, v17, v9
	ds_swizzle_b32 v252, v246 offset:0x401f
	ds_swizzle_b32 v253, v247 offset:0x401f
	s_waitcnt lgkmcnt(0)
	v_bfi_b32 v240, v237, v250, v36
	v_bfi_b32 v241, v237, v251, v37
	v_bfi_b32 v242, v237, v28, v250
	v_bfi_b32 v243, v237, v29, v251
	global_store_dwordx4 v[238:239], v[240:243], off nt
	s_nop 1
	v_bfi_b32 v240, v237, v252, v16
	v_bfi_b32 v241, v237, v253, v17
	v_bfi_b32 v242, v237, v8, v252
	v_bfi_b32 v243, v237, v9, v253
	global_store_dwordx4 v[238:239], v[240:243], off offset:256 nt
	s_nop 1
	v_add_co_u32_e32 v238, vcc, 0x58000, v248
	s_nop 1
	v_addc_co_u32_e32 v239, vcc, 0, v249, vcc
	v_cvt_pk_bf16_f32 v20, v20, v21
	v_cvt_pk_bf16_f32 v21, v22, v23
	v_cvt_pk_bf16_f32 v12, v12, v13
	v_cvt_pk_bf16_f32 v13, v14, v15
	v_bfi_b32 v244, v237, v20, v12
	v_bfi_b32 v245, v237, v21, v13
	ds_swizzle_b32 v250, v244 offset:0x401f
	ds_swizzle_b32 v251, v245 offset:0x401f
	v_cvt_pk_bf16_f32 v4, v4, v5
	v_cvt_pk_bf16_f32 v5, v6, v7
	v_cvt_pk_bf16_f32 v0, v0, v1
	v_cvt_pk_bf16_f32 v1, v2, v3
	v_bfi_b32 v246, v237, v4, v0
	v_bfi_b32 v247, v237, v5, v1
	ds_swizzle_b32 v252, v246 offset:0x401f
	ds_swizzle_b32 v253, v247 offset:0x401f
	s_waitcnt lgkmcnt(0)
	v_bfi_b32 v240, v237, v250, v20
	v_bfi_b32 v241, v237, v251, v21
	v_bfi_b32 v242, v237, v12, v250
	v_bfi_b32 v243, v237, v13, v251
	global_store_dwordx4 v[238:239], v[240:243], off nt
	s_nop 1
	v_bfi_b32 v240, v237, v252, v4
	v_bfi_b32 v241, v237, v253, v5
	v_bfi_b32 v242, v237, v0, v252
	v_bfi_b32 v243, v237, v1, v253
	global_store_dwordx4 v[238:239], v[240:243], off offset:256 nt
	s_nop 1
	s_and_b64 vcc, exec, s[4:5]
	v_writelane_b32 v235, s39, 16
	s_mov_b64 s[14:15], s[0:1]
	s_mov_b64 s[12:13], s[6:7]
	v_writelane_b32 v235, s40, 24
	s_cbranch_vccz .LBB0_2272
	s_waitcnt vmcnt(0)
	s_cmpk_gt_u32 s20, 0xff
	s_cbranch_scc1 .LBB0_2283
	s_barrier
